# merge: cooperative L2 prefetch of the next group's A rows (one dword per 64-byte sector, split over the 8 workgroups sharing a row tile)
# speedup vs baseline: 1.0036x; 1.0015x over previous
.LBB0_1004:
	v_and_b32_e32 v2, 7, v192
	v_lshrrev_b32_e32 v3, 3, v192
	v_bfe_u32 v4, v192, 4, 3
	v_xor_b32_e32 v2, v2, v4
	v_lshlrev_b32_e32 v2, 4, v2
	v_mul_u32_u24_e32 v4, 0x3e00, v3
	v_add_u32_e32 v188, v4, v2
	v_add_u32_e32 v189, 0xf8000, v188
	v_add_u32_e32 v190, 0x1f0000, v188
	v_add_u32_e32 v191, 0x2e8000, v188
	v_and_b32_e32 v4, 35, v3
	v_bfe_u32 v5, v3, 4, 1
	v_lshl_or_b32 v4, v5, 2, v4
	v_bfe_u32 v5, v3, 2, 2
	v_lshl_or_b32 v4, v5, 3, v4
	v_lshl_or_b32 v205, v4, 10, v2
	v_add_u32_e32 v206, 0x10000, v205
	v_bfe_u32 v2, v192, 1, 3
	v_bfe_u32 v3, v192, 4, 2
	v_xor_b32_e32 v2, v2, v3
	v_lshlrev_b32_e32 v2, 4, v2
	v_and_b32_e32 v3, 15, v192
	v_lshrrev_b32_e32 v4, 7, v192
	v_lshl_or_b32 v4, v4, 6, v3
	v_lshl_or_b32 v207, v4, 7, v2
	v_xor_b32_e32 v119, 64, v207
	v_add_u32_e32 v0, 0x10000, v207
	v_add_u32_e32 v255, 0x10000, v119
	v_bfe_u32 v4, v192, 6, 1
	v_lshl_or_b32 v4, v4, 6, v3
	v_lshl_or_b32 v4, v4, 7, v2
	v_add_u32_e32 v90, 0x18000, v4
	v_xor_b32_e32 v91, 64, v90
	v_lshrrev_b32_e32 v5, 6, v192
	s_nop 0
	v_readfirstlane_b32 s67, v5
	s_lshl_b32 s67, s67, 10
	s_add_u32 s80, s46, 0xc00
	s_addc_u32 s81, s47, 0
	s_mov_b32 s96, s48
	s_mov_b32 s97, s49
	v_lshrrev_b32_e32 v2, 4, v192
	v_mul_u32_u24_e32 v2, 0x3e00, v2
	v_and_b32_e32 v3, 15, v192
	v_lshl_or_b32 v93, v3, 6, v2
	s_lshr_b32 s32, s13, 17
	s_mul_i32 s32, s32, 0x7c000
	s_add_u32 s86, s46, s32
	s_addc_u32 s87, s47, 0
	s_add_u32 s98, s86, 0x1000
	s_addc_u32 s99, s87, 0
	global_load_dword v92, v93, s[98:99]
	s_add_i32 m0, s67, 0x0
	s_nop 0
	global_load_lds_dwordx4 v188, s[80:81]
	s_add_i32 m0, s67, 0x2000
	s_nop 0
	global_load_lds_dwordx4 v189, s[80:81]
	s_add_i32 m0, s67, 0x4000
	s_nop 0
	global_load_lds_dwordx4 v190, s[80:81]
	s_add_i32 m0, s67, 0x6000
	s_nop 0
	global_load_lds_dwordx4 v191, s[80:81]
	s_add_i32 m0, s67, 0x18000
	s_nop 0
	global_load_lds_dwordx4 v205, s[96:97]
	s_add_i32 m0, s67, 0x1a000
	s_nop 0
	global_load_lds_dwordx4 v206, s[96:97]
	s_add_u32 s80, s80, 0x80
	s_addc_u32 s81, s81, 0
	s_add_u32 s96, s96, 0x80
	s_addc_u32 s97, s97, 0
	s_add_i32 m0, s67, 0x8000
	s_nop 0
	global_load_lds_dwordx4 v188, s[80:81]
	s_add_i32 m0, s67, 0xa000
	s_nop 0
	global_load_lds_dwordx4 v189, s[80:81]
	s_add_i32 m0, s67, 0xc000
	s_nop 0
	global_load_lds_dwordx4 v190, s[80:81]
	s_add_i32 m0, s67, 0xe000
	s_nop 0
	global_load_lds_dwordx4 v191, s[80:81]
	s_add_i32 m0, s67, 0x1c000
	s_nop 0
	global_load_lds_dwordx4 v205, s[96:97]
	s_add_i32 m0, s67, 0x1e000
	s_nop 0
	global_load_lds_dwordx4 v206, s[96:97]
	s_add_u32 s80, s80, 0x80
	s_addc_u32 s81, s81, 0
	s_add_u32 s96, s96, 0x80
	s_addc_u32 s97, s97, 0
	s_add_i32 m0, s67, 0x10000
	s_nop 0
	global_load_lds_dwordx4 v188, s[80:81]
	s_add_i32 m0, s67, 0x12000
	s_nop 0
	global_load_lds_dwordx4 v189, s[80:81]
	s_add_i32 m0, s67, 0x14000
	s_nop 0
	global_load_lds_dwordx4 v190, s[80:81]
	s_add_i32 m0, s67, 0x16000
	s_nop 0
	global_load_lds_dwordx4 v191, s[80:81]
	s_add_i32 m0, s67, 0x20400
	s_nop 0
	global_load_lds_dwordx4 v205, s[96:97]
	s_add_i32 m0, s67, 0x22400
	s_nop 0
	global_load_lds_dwordx4 v206, s[96:97]
	s_add_u32 s80, s80, 0x80
	s_addc_u32 s81, s81, 0
	s_add_u32 s96, s96, 0x80
	s_addc_u32 s97, s97, 0
	s_waitcnt vmcnt(12)
	s_barrier
	ds_read_b128 v[82:85], v90 offset:0
	ds_read_b128 v[86:89], v90 offset:2048
	ds_read_b128 v[208:211], v90 offset:4096
	ds_read_b128 v[212:215], v90 offset:6144
	ds_read_b128 v[66:69], v207 offset:0
	ds_read_b128 v[70:73], v207 offset:2048
	ds_read_b128 v[74:77], v207 offset:4096
	ds_read_b128 v[78:81], v207 offset:6144
	ds_read_b128 v[216:219], v91 offset:0
	ds_read_b128 v[220:223], v91 offset:2048
	ds_read_b128 v[224:227], v91 offset:4096
	ds_read_b128 v[228:231], v91 offset:6144
	s_waitcnt lgkmcnt(7)
	v_mfma_f32_16x16x32_bf16 v[6:9], v[82:85], v[66:69], 0
	v_mfma_f32_16x16x32_bf16 v[30:33], v[86:89], v[66:69], 0
	v_mfma_f32_16x16x32_bf16 v[38:41], v[208:211], v[66:69], 0
	v_mfma_f32_16x16x32_bf16 v[42:45], v[212:215], v[66:69], 0
	ds_read_b128 v[66:69], v119 offset:0
	s_waitcnt lgkmcnt(7)
	v_mfma_f32_16x16x32_bf16 v[46:49], v[82:85], v[70:73], 0
	v_mfma_f32_16x16x32_bf16 v[26:29], v[86:89], v[70:73], 0
	v_mfma_f32_16x16x32_bf16 v[14:17], v[208:211], v[70:73], 0
	v_mfma_f32_16x16x32_bf16 v[10:13], v[212:215], v[70:73], 0
	ds_read_b128 v[70:73], v119 offset:2048
	s_waitcnt lgkmcnt(7)
	v_mfma_f32_16x16x32_bf16 v[34:37], v[82:85], v[74:77], 0
	v_mfma_f32_16x16x32_bf16 v[22:25], v[86:89], v[74:77], 0
	v_mfma_f32_16x16x32_bf16 v[18:21], v[208:211], v[74:77], 0
	v_mfma_f32_16x16x32_bf16 v[62:65], v[212:215], v[74:77], 0
	ds_read_b128 v[74:77], v119 offset:4096
	s_waitcnt lgkmcnt(7)
	v_mfma_f32_16x16x32_bf16 v[58:61], v[82:85], v[78:81], 0
	v_mfma_f32_16x16x32_bf16 v[54:57], v[86:89], v[78:81], 0
	v_mfma_f32_16x16x32_bf16 v[50:53], v[208:211], v[78:81], 0
	v_mfma_f32_16x16x32_bf16 v[2:5], v[212:215], v[78:81], 0
	ds_read_b128 v[78:81], v119 offset:6144
	s_waitcnt lgkmcnt(3)
	v_mfma_f32_16x16x32_bf16 v[6:9], v[216:219], v[66:69], v[6:9]
	v_mfma_f32_16x16x32_bf16 v[30:33], v[220:223], v[66:69], v[30:33]
	v_mfma_f32_16x16x32_bf16 v[38:41], v[224:227], v[66:69], v[38:41]
	v_mfma_f32_16x16x32_bf16 v[42:45], v[228:231], v[66:69], v[42:45]
	s_waitcnt lgkmcnt(2)
	v_mfma_f32_16x16x32_bf16 v[46:49], v[216:219], v[70:73], v[46:49]
	v_mfma_f32_16x16x32_bf16 v[26:29], v[220:223], v[70:73], v[26:29]
	v_mfma_f32_16x16x32_bf16 v[14:17], v[224:227], v[70:73], v[14:17]
	v_mfma_f32_16x16x32_bf16 v[10:13], v[228:231], v[70:73], v[10:13]
	s_waitcnt vmcnt(6)
	s_waitcnt lgkmcnt(0)
	s_barrier
	s_add_i32 m0, s67, 0x0
	s_nop 0
	global_load_lds_dwordx4 v188, s[80:81]
	s_add_i32 m0, s67, 0x2000
	s_nop 0
	global_load_lds_dwordx4 v189, s[80:81]
	s_add_i32 m0, s67, 0x4000
	s_nop 0
	global_load_lds_dwordx4 v190, s[80:81]
	s_add_i32 m0, s67, 0x6000
	s_nop 0
	global_load_lds_dwordx4 v191, s[80:81]
	s_add_i32 m0, s67, 0x18000
	s_nop 0
	global_load_lds_dwordx4 v205, s[96:97]
	s_add_i32 m0, s67, 0x1a000
	s_nop 0
	global_load_lds_dwordx4 v206, s[96:97]
	s_add_u32 s80, s80, 0x80
	s_addc_u32 s81, s81, 0
	s_add_u32 s96, s96, 0x80
	s_addc_u32 s97, s97, 0
	ds_read_b128 v[82:85], v90 offset:16384
	ds_read_b128 v[86:89], v90 offset:18432
	ds_read_b128 v[208:211], v90 offset:20480
	ds_read_b128 v[212:215], v90 offset:22528
	ds_read_b128 v[66:69], v207 offset:32768
	ds_read_b128 v[70:73], v207 offset:34816
	v_mfma_f32_16x16x32_bf16 v[34:37], v[216:219], v[74:77], v[34:37]
	v_mfma_f32_16x16x32_bf16 v[22:25], v[220:223], v[74:77], v[22:25]
	v_mfma_f32_16x16x32_bf16 v[18:21], v[224:227], v[74:77], v[18:21]
	v_mfma_f32_16x16x32_bf16 v[62:65], v[228:231], v[74:77], v[62:65]
	ds_read_b128 v[74:77], v207 offset:36864
	v_mfma_f32_16x16x32_bf16 v[58:61], v[216:219], v[78:81], v[58:61]
	v_mfma_f32_16x16x32_bf16 v[54:57], v[220:223], v[78:81], v[54:57]
	v_mfma_f32_16x16x32_bf16 v[50:53], v[224:227], v[78:81], v[50:53]
	v_mfma_f32_16x16x32_bf16 v[2:5], v[228:231], v[78:81], v[2:5]
	ds_read_b128 v[78:81], v207 offset:38912
	ds_read_b128 v[216:219], v91 offset:16384
	ds_read_b128 v[220:223], v91 offset:18432
	ds_read_b128 v[224:227], v91 offset:20480
	ds_read_b128 v[228:231], v91 offset:22528
	s_waitcnt lgkmcnt(7)
	v_mfma_f32_16x16x32_bf16 v[6:9], v[82:85], v[66:69], v[6:9]
	v_mfma_f32_16x16x32_bf16 v[30:33], v[86:89], v[66:69], v[30:33]
	v_mfma_f32_16x16x32_bf16 v[38:41], v[208:211], v[66:69], v[38:41]
	v_mfma_f32_16x16x32_bf16 v[42:45], v[212:215], v[66:69], v[42:45]
	ds_read_b128 v[66:69], v119 offset:32768
	s_waitcnt lgkmcnt(7)
	v_mfma_f32_16x16x32_bf16 v[46:49], v[82:85], v[70:73], v[46:49]
	v_mfma_f32_16x16x32_bf16 v[26:29], v[86:89], v[70:73], v[26:29]
	v_mfma_f32_16x16x32_bf16 v[14:17], v[208:211], v[70:73], v[14:17]
	v_mfma_f32_16x16x32_bf16 v[10:13], v[212:215], v[70:73], v[10:13]
	ds_read_b128 v[70:73], v119 offset:34816
	s_waitcnt lgkmcnt(7)
	v_mfma_f32_16x16x32_bf16 v[34:37], v[82:85], v[74:77], v[34:37]
	v_mfma_f32_16x16x32_bf16 v[22:25], v[86:89], v[74:77], v[22:25]
	v_mfma_f32_16x16x32_bf16 v[18:21], v[208:211], v[74:77], v[18:21]
	v_mfma_f32_16x16x32_bf16 v[62:65], v[212:215], v[74:77], v[62:65]
	ds_read_b128 v[74:77], v119 offset:36864
	s_waitcnt lgkmcnt(7)
	v_mfma_f32_16x16x32_bf16 v[58:61], v[82:85], v[78:81], v[58:61]
	v_mfma_f32_16x16x32_bf16 v[54:57], v[86:89], v[78:81], v[54:57]
	v_mfma_f32_16x16x32_bf16 v[50:53], v[208:211], v[78:81], v[50:53]
	v_mfma_f32_16x16x32_bf16 v[2:5], v[212:215], v[78:81], v[2:5]
	ds_read_b128 v[78:81], v119 offset:38912
	s_waitcnt lgkmcnt(3)
	v_mfma_f32_16x16x32_bf16 v[6:9], v[216:219], v[66:69], v[6:9]
	v_mfma_f32_16x16x32_bf16 v[30:33], v[220:223], v[66:69], v[30:33]
	v_mfma_f32_16x16x32_bf16 v[38:41], v[224:227], v[66:69], v[38:41]
	v_mfma_f32_16x16x32_bf16 v[42:45], v[228:231], v[66:69], v[42:45]
	s_waitcnt lgkmcnt(2)
	v_mfma_f32_16x16x32_bf16 v[46:49], v[216:219], v[70:73], v[46:49]
	v_mfma_f32_16x16x32_bf16 v[26:29], v[220:223], v[70:73], v[26:29]
	v_mfma_f32_16x16x32_bf16 v[14:17], v[224:227], v[70:73], v[14:17]
	v_mfma_f32_16x16x32_bf16 v[10:13], v[228:231], v[70:73], v[10:13]
	s_waitcnt vmcnt(6)
	s_waitcnt lgkmcnt(0)
	s_barrier
	s_add_i32 m0, s67, 0x8000
	s_nop 0
	global_load_lds_dwordx4 v188, s[80:81]
	s_add_i32 m0, s67, 0xa000
	s_nop 0
	global_load_lds_dwordx4 v189, s[80:81]
	s_add_i32 m0, s67, 0xc000
	s_nop 0
	global_load_lds_dwordx4 v190, s[80:81]
	s_add_i32 m0, s67, 0xe000
	s_nop 0
	global_load_lds_dwordx4 v191, s[80:81]
	s_add_i32 m0, s67, 0x1c000
	s_nop 0
	global_load_lds_dwordx4 v205, s[96:97]
	s_add_i32 m0, s67, 0x1e000
	s_nop 0
	global_load_lds_dwordx4 v206, s[96:97]
	s_add_u32 s80, s80, 0x80
	s_addc_u32 s81, s81, 0
	s_add_u32 s96, s96, 0x80
	s_addc_u32 s97, s97, 0
	ds_read_b128 v[82:85], v90 offset:33792
	ds_read_b128 v[86:89], v90 offset:35840
	ds_read_b128 v[208:211], v90 offset:37888
	ds_read_b128 v[212:215], v90 offset:39936
	ds_read_b128 v[66:69], v0 offset:0
	ds_read_b128 v[70:73], v0 offset:2048
	v_mfma_f32_16x16x32_bf16 v[34:37], v[216:219], v[74:77], v[34:37]
	v_mfma_f32_16x16x32_bf16 v[22:25], v[220:223], v[74:77], v[22:25]
	v_mfma_f32_16x16x32_bf16 v[18:21], v[224:227], v[74:77], v[18:21]
	v_mfma_f32_16x16x32_bf16 v[62:65], v[228:231], v[74:77], v[62:65]
	ds_read_b128 v[74:77], v0 offset:4096
	v_mfma_f32_16x16x32_bf16 v[58:61], v[216:219], v[78:81], v[58:61]
	v_mfma_f32_16x16x32_bf16 v[54:57], v[220:223], v[78:81], v[54:57]
	v_mfma_f32_16x16x32_bf16 v[50:53], v[224:227], v[78:81], v[50:53]
	v_mfma_f32_16x16x32_bf16 v[2:5], v[228:231], v[78:81], v[2:5]
	ds_read_b128 v[78:81], v0 offset:6144
	ds_read_b128 v[216:219], v91 offset:33792
	ds_read_b128 v[220:223], v91 offset:35840
	ds_read_b128 v[224:227], v91 offset:37888
	ds_read_b128 v[228:231], v91 offset:39936
	s_waitcnt lgkmcnt(7)
	v_mfma_f32_16x16x32_bf16 v[6:9], v[82:85], v[66:69], v[6:9]
	v_mfma_f32_16x16x32_bf16 v[30:33], v[86:89], v[66:69], v[30:33]
	v_mfma_f32_16x16x32_bf16 v[38:41], v[208:211], v[66:69], v[38:41]
	v_mfma_f32_16x16x32_bf16 v[42:45], v[212:215], v[66:69], v[42:45]
	ds_read_b128 v[66:69], v255 offset:0
	s_waitcnt lgkmcnt(7)
	v_mfma_f32_16x16x32_bf16 v[46:49], v[82:85], v[70:73], v[46:49]
	v_mfma_f32_16x16x32_bf16 v[26:29], v[86:89], v[70:73], v[26:29]
	v_mfma_f32_16x16x32_bf16 v[14:17], v[208:211], v[70:73], v[14:17]
	v_mfma_f32_16x16x32_bf16 v[10:13], v[212:215], v[70:73], v[10:13]
	ds_read_b128 v[70:73], v255 offset:2048
	s_waitcnt lgkmcnt(7)
	v_mfma_f32_16x16x32_bf16 v[34:37], v[82:85], v[74:77], v[34:37]
	v_mfma_f32_16x16x32_bf16 v[22:25], v[86:89], v[74:77], v[22:25]
	v_mfma_f32_16x16x32_bf16 v[18:21], v[208:211], v[74:77], v[18:21]
	v_mfma_f32_16x16x32_bf16 v[62:65], v[212:215], v[74:77], v[62:65]
	ds_read_b128 v[74:77], v255 offset:4096
	s_waitcnt lgkmcnt(7)
	v_mfma_f32_16x16x32_bf16 v[58:61], v[82:85], v[78:81], v[58:61]
	v_mfma_f32_16x16x32_bf16 v[54:57], v[86:89], v[78:81], v[54:57]
	v_mfma_f32_16x16x32_bf16 v[50:53], v[208:211], v[78:81], v[50:53]
	v_mfma_f32_16x16x32_bf16 v[2:5], v[212:215], v[78:81], v[2:5]
	ds_read_b128 v[78:81], v255 offset:6144
	s_waitcnt lgkmcnt(3)
	v_mfma_f32_16x16x32_bf16 v[6:9], v[216:219], v[66:69], v[6:9]
	v_mfma_f32_16x16x32_bf16 v[30:33], v[220:223], v[66:69], v[30:33]
	v_mfma_f32_16x16x32_bf16 v[38:41], v[224:227], v[66:69], v[38:41]
	v_mfma_f32_16x16x32_bf16 v[42:45], v[228:231], v[66:69], v[42:45]
	s_waitcnt lgkmcnt(2)
	v_mfma_f32_16x16x32_bf16 v[46:49], v[216:219], v[70:73], v[46:49]
	v_mfma_f32_16x16x32_bf16 v[26:29], v[220:223], v[70:73], v[26:29]
	v_mfma_f32_16x16x32_bf16 v[14:17], v[224:227], v[70:73], v[14:17]
	v_mfma_f32_16x16x32_bf16 v[10:13], v[228:231], v[70:73], v[10:13]
	s_waitcnt vmcnt(6)
	s_waitcnt lgkmcnt(0)
	s_barrier
	s_add_i32 m0, s67, 0x10000
	s_nop 0
	global_load_lds_dwordx4 v188, s[80:81]
	s_add_i32 m0, s67, 0x12000
	s_nop 0
	global_load_lds_dwordx4 v189, s[80:81]
	s_add_i32 m0, s67, 0x14000
	s_nop 0
	global_load_lds_dwordx4 v190, s[80:81]
	s_add_i32 m0, s67, 0x16000
	s_nop 0
	global_load_lds_dwordx4 v191, s[80:81]
	s_add_i32 m0, s67, 0x20400
	s_nop 0
	global_load_lds_dwordx4 v205, s[96:97]
	s_add_i32 m0, s67, 0x22400
	s_nop 0
	global_load_lds_dwordx4 v206, s[96:97]
	s_add_u32 s80, s80, 0x80
	s_addc_u32 s81, s81, 0
	s_add_u32 s96, s96, 0x80
	s_addc_u32 s97, s97, 0
	ds_read_b128 v[82:85], v90 offset:0
	ds_read_b128 v[86:89], v90 offset:2048
	ds_read_b128 v[208:211], v90 offset:4096
	ds_read_b128 v[212:215], v90 offset:6144
	ds_read_b128 v[66:69], v207 offset:0
	ds_read_b128 v[70:73], v207 offset:2048
	v_mfma_f32_16x16x32_bf16 v[34:37], v[216:219], v[74:77], v[34:37]
	v_mfma_f32_16x16x32_bf16 v[22:25], v[220:223], v[74:77], v[22:25]
	v_mfma_f32_16x16x32_bf16 v[18:21], v[224:227], v[74:77], v[18:21]
	v_mfma_f32_16x16x32_bf16 v[62:65], v[228:231], v[74:77], v[62:65]
	ds_read_b128 v[74:77], v207 offset:4096
	v_mfma_f32_16x16x32_bf16 v[58:61], v[216:219], v[78:81], v[58:61]
	v_mfma_f32_16x16x32_bf16 v[54:57], v[220:223], v[78:81], v[54:57]
	v_mfma_f32_16x16x32_bf16 v[50:53], v[224:227], v[78:81], v[50:53]
	v_mfma_f32_16x16x32_bf16 v[2:5], v[228:231], v[78:81], v[2:5]
	ds_read_b128 v[78:81], v207 offset:6144
	ds_read_b128 v[216:219], v91 offset:0
	ds_read_b128 v[220:223], v91 offset:2048
	ds_read_b128 v[224:227], v91 offset:4096
	ds_read_b128 v[228:231], v91 offset:6144
	s_waitcnt lgkmcnt(7)
	v_mfma_f32_16x16x32_bf16 v[6:9], v[82:85], v[66:69], v[6:9]
	v_mfma_f32_16x16x32_bf16 v[30:33], v[86:89], v[66:69], v[30:33]
	v_mfma_f32_16x16x32_bf16 v[38:41], v[208:211], v[66:69], v[38:41]
	v_mfma_f32_16x16x32_bf16 v[42:45], v[212:215], v[66:69], v[42:45]
	ds_read_b128 v[66:69], v119 offset:0
	s_waitcnt lgkmcnt(7)
	v_mfma_f32_16x16x32_bf16 v[46:49], v[82:85], v[70:73], v[46:49]
	v_mfma_f32_16x16x32_bf16 v[26:29], v[86:89], v[70:73], v[26:29]
	v_mfma_f32_16x16x32_bf16 v[14:17], v[208:211], v[70:73], v[14:17]
	v_mfma_f32_16x16x32_bf16 v[10:13], v[212:215], v[70:73], v[10:13]
	ds_read_b128 v[70:73], v119 offset:2048
	s_waitcnt lgkmcnt(7)
	v_mfma_f32_16x16x32_bf16 v[34:37], v[82:85], v[74:77], v[34:37]
	v_mfma_f32_16x16x32_bf16 v[22:25], v[86:89], v[74:77], v[22:25]
	v_mfma_f32_16x16x32_bf16 v[18:21], v[208:211], v[74:77], v[18:21]
	v_mfma_f32_16x16x32_bf16 v[62:65], v[212:215], v[74:77], v[62:65]
	ds_read_b128 v[74:77], v119 offset:4096
	s_waitcnt lgkmcnt(7)
	v_mfma_f32_16x16x32_bf16 v[58:61], v[82:85], v[78:81], v[58:61]
	v_mfma_f32_16x16x32_bf16 v[54:57], v[86:89], v[78:81], v[54:57]
	v_mfma_f32_16x16x32_bf16 v[50:53], v[208:211], v[78:81], v[50:53]
	v_mfma_f32_16x16x32_bf16 v[2:5], v[212:215], v[78:81], v[2:5]
	ds_read_b128 v[78:81], v119 offset:6144
	s_waitcnt lgkmcnt(3)
	v_mfma_f32_16x16x32_bf16 v[6:9], v[216:219], v[66:69], v[6:9]
	v_mfma_f32_16x16x32_bf16 v[30:33], v[220:223], v[66:69], v[30:33]
	v_mfma_f32_16x16x32_bf16 v[38:41], v[224:227], v[66:69], v[38:41]
	v_mfma_f32_16x16x32_bf16 v[42:45], v[228:231], v[66:69], v[42:45]
	s_waitcnt lgkmcnt(2)
	v_mfma_f32_16x16x32_bf16 v[46:49], v[216:219], v[70:73], v[46:49]
	v_mfma_f32_16x16x32_bf16 v[26:29], v[220:223], v[70:73], v[26:29]
	v_mfma_f32_16x16x32_bf16 v[14:17], v[224:227], v[70:73], v[14:17]
	v_mfma_f32_16x16x32_bf16 v[10:13], v[228:231], v[70:73], v[10:13]
	s_waitcnt vmcnt(6)
	s_waitcnt lgkmcnt(0)
	s_barrier
	s_add_i32 m0, s67, 0x0
	s_nop 0
	global_load_lds_dwordx4 v188, s[80:81]
	s_add_i32 m0, s67, 0x2000
	s_nop 0
	global_load_lds_dwordx4 v189, s[80:81]
	s_add_i32 m0, s67, 0x4000
	s_nop 0
	global_load_lds_dwordx4 v190, s[80:81]
	s_add_i32 m0, s67, 0x6000
	s_nop 0
	global_load_lds_dwordx4 v191, s[80:81]
	s_add_i32 m0, s67, 0x18000
	s_nop 0
	global_load_lds_dwordx4 v205, s[96:97]
	s_add_i32 m0, s67, 0x1a000
	s_nop 0
	global_load_lds_dwordx4 v206, s[96:97]
	s_add_u32 s80, s80, 0x80
	s_addc_u32 s81, s81, 0
	s_add_u32 s96, s96, 0x80
	s_addc_u32 s97, s97, 0
	s_movk_i32 s10, 0x0
	s_mov_b32 s11, 0
	v_lshl_add_u64 v[248:249], v[128:129], 0, s[10:11]
	global_load_dwordx2 v[232:233], v[248:249], off
	global_load_dwordx2 v[234:235], v[248:249], off offset:32
	v_lshl_add_u64 v[248:249], v[132:133], 0, s[10:11]
	global_load_dwordx2 v[236:237], v[248:249], off
	global_load_dwordx2 v[238:239], v[248:249], off offset:32
	v_lshl_add_u64 v[248:249], v[152:153], 0, s[10:11]
	global_load_dwordx2 v[240:241], v[248:249], off
	global_load_dwordx2 v[242:243], v[248:249], off offset:32
	v_lshl_add_u64 v[248:249], v[154:155], 0, s[10:11]
	global_load_dwordx2 v[244:245], v[248:249], off
	global_load_dwordx2 v[246:247], v[248:249], off offset:32
	ds_read_b128 v[82:85], v90 offset:16384
	ds_read_b128 v[86:89], v90 offset:18432
	ds_read_b128 v[208:211], v90 offset:20480
	ds_read_b128 v[212:215], v90 offset:22528
	ds_read_b128 v[66:69], v207 offset:32768
	ds_read_b128 v[70:73], v207 offset:34816
	v_mfma_f32_16x16x32_bf16 v[34:37], v[216:219], v[74:77], v[34:37]
	v_mfma_f32_16x16x32_bf16 v[22:25], v[220:223], v[74:77], v[22:25]
	v_mfma_f32_16x16x32_bf16 v[18:21], v[224:227], v[74:77], v[18:21]
	v_mfma_f32_16x16x32_bf16 v[62:65], v[228:231], v[74:77], v[62:65]
	ds_read_b128 v[74:77], v207 offset:36864
	v_mfma_f32_16x16x32_bf16 v[58:61], v[216:219], v[78:81], v[58:61]
	v_mfma_f32_16x16x32_bf16 v[54:57], v[220:223], v[78:81], v[54:57]
	v_mfma_f32_16x16x32_bf16 v[50:53], v[224:227], v[78:81], v[50:53]
	v_mfma_f32_16x16x32_bf16 v[2:5], v[228:231], v[78:81], v[2:5]
	ds_read_b128 v[78:81], v207 offset:38912
	ds_read_b128 v[216:219], v91 offset:16384
	ds_read_b128 v[220:223], v91 offset:18432
	ds_read_b128 v[224:227], v91 offset:20480
	ds_read_b128 v[228:231], v91 offset:22528
	s_waitcnt lgkmcnt(7)
	v_mfma_f32_16x16x32_bf16 v[6:9], v[82:85], v[66:69], v[6:9]
	v_mfma_f32_16x16x32_bf16 v[30:33], v[86:89], v[66:69], v[30:33]
	v_mfma_f32_16x16x32_bf16 v[38:41], v[208:211], v[66:69], v[38:41]
	v_mfma_f32_16x16x32_bf16 v[42:45], v[212:215], v[66:69], v[42:45]
	ds_read_b128 v[66:69], v119 offset:32768
	s_waitcnt lgkmcnt(7)
	v_mfma_f32_16x16x32_bf16 v[46:49], v[82:85], v[70:73], v[46:49]
	v_mfma_f32_16x16x32_bf16 v[26:29], v[86:89], v[70:73], v[26:29]
	v_mfma_f32_16x16x32_bf16 v[14:17], v[208:211], v[70:73], v[14:17]
	v_mfma_f32_16x16x32_bf16 v[10:13], v[212:215], v[70:73], v[10:13]
	ds_read_b128 v[70:73], v119 offset:34816
	s_waitcnt lgkmcnt(7)
	v_mfma_f32_16x16x32_bf16 v[34:37], v[82:85], v[74:77], v[34:37]
	v_mfma_f32_16x16x32_bf16 v[22:25], v[86:89], v[74:77], v[22:25]
	v_mfma_f32_16x16x32_bf16 v[18:21], v[208:211], v[74:77], v[18:21]
	v_mfma_f32_16x16x32_bf16 v[62:65], v[212:215], v[74:77], v[62:65]
	ds_read_b128 v[74:77], v119 offset:36864
	s_waitcnt lgkmcnt(7)
	v_mfma_f32_16x16x32_bf16 v[58:61], v[82:85], v[78:81], v[58:61]
	v_mfma_f32_16x16x32_bf16 v[54:57], v[86:89], v[78:81], v[54:57]
	v_mfma_f32_16x16x32_bf16 v[50:53], v[208:211], v[78:81], v[50:53]
	v_mfma_f32_16x16x32_bf16 v[2:5], v[212:215], v[78:81], v[2:5]
	ds_read_b128 v[78:81], v119 offset:38912
	s_waitcnt lgkmcnt(3)
	v_mfma_f32_16x16x32_bf16 v[6:9], v[216:219], v[66:69], v[6:9]
	v_mfma_f32_16x16x32_bf16 v[30:33], v[220:223], v[66:69], v[30:33]
	v_mfma_f32_16x16x32_bf16 v[38:41], v[224:227], v[66:69], v[38:41]
	v_mfma_f32_16x16x32_bf16 v[42:45], v[228:231], v[66:69], v[42:45]
	s_waitcnt lgkmcnt(2)
	v_mfma_f32_16x16x32_bf16 v[46:49], v[216:219], v[70:73], v[46:49]
	v_mfma_f32_16x16x32_bf16 v[26:29], v[220:223], v[70:73], v[26:29]
	v_mfma_f32_16x16x32_bf16 v[14:17], v[224:227], v[70:73], v[14:17]
	v_mfma_f32_16x16x32_bf16 v[10:13], v[228:231], v[70:73], v[10:13]
	s_waitcnt vmcnt(14)
	s_waitcnt lgkmcnt(0)
	s_barrier
	s_add_i32 m0, s67, 0x8000
	s_nop 0
	global_load_lds_dwordx4 v188, s[80:81]
	s_add_i32 m0, s67, 0xa000
	s_nop 0
	global_load_lds_dwordx4 v189, s[80:81]
	s_add_i32 m0, s67, 0xc000
	s_nop 0
	global_load_lds_dwordx4 v190, s[80:81]
	s_add_i32 m0, s67, 0xe000
	s_nop 0
	global_load_lds_dwordx4 v191, s[80:81]
	s_add_i32 m0, s67, 0x1c000
	s_nop 0
	global_load_lds_dwordx4 v205, s[96:97]
	s_add_i32 m0, s67, 0x1e000
	s_nop 0
	global_load_lds_dwordx4 v206, s[96:97]
	s_add_u32 s80, s80, 0x80
	s_addc_u32 s81, s81, 0
	s_add_u32 s96, s96, 0xffc80
	s_addc_u32 s97, s97, 0
	ds_read_b128 v[82:85], v90 offset:33792
	ds_read_b128 v[86:89], v90 offset:35840
	ds_read_b128 v[208:211], v90 offset:37888
	ds_read_b128 v[212:215], v90 offset:39936
	ds_read_b128 v[66:69], v0 offset:0
	ds_read_b128 v[70:73], v0 offset:2048
	v_mfma_f32_16x16x32_bf16 v[34:37], v[216:219], v[74:77], v[34:37]
	v_mfma_f32_16x16x32_bf16 v[22:25], v[220:223], v[74:77], v[22:25]
	v_mfma_f32_16x16x32_bf16 v[18:21], v[224:227], v[74:77], v[18:21]
	v_mfma_f32_16x16x32_bf16 v[62:65], v[228:231], v[74:77], v[62:65]
	ds_read_b128 v[74:77], v0 offset:4096
	v_mfma_f32_16x16x32_bf16 v[58:61], v[216:219], v[78:81], v[58:61]
	v_mfma_f32_16x16x32_bf16 v[54:57], v[220:223], v[78:81], v[54:57]
	v_mfma_f32_16x16x32_bf16 v[50:53], v[224:227], v[78:81], v[50:53]
	v_mfma_f32_16x16x32_bf16 v[2:5], v[228:231], v[78:81], v[2:5]
	ds_read_b128 v[78:81], v0 offset:6144
	ds_read_b128 v[216:219], v91 offset:33792
	ds_read_b128 v[220:223], v91 offset:35840
	ds_read_b128 v[224:227], v91 offset:37888
	ds_read_b128 v[228:231], v91 offset:39936
	s_waitcnt lgkmcnt(7)
	v_mfma_f32_16x16x32_bf16 v[6:9], v[82:85], v[66:69], v[6:9]
	v_mfma_f32_16x16x32_bf16 v[30:33], v[86:89], v[66:69], v[30:33]
	v_mfma_f32_16x16x32_bf16 v[38:41], v[208:211], v[66:69], v[38:41]
	v_mfma_f32_16x16x32_bf16 v[42:45], v[212:215], v[66:69], v[42:45]
	ds_read_b128 v[66:69], v255 offset:0
	s_waitcnt lgkmcnt(7)
	v_mfma_f32_16x16x32_bf16 v[46:49], v[82:85], v[70:73], v[46:49]
	v_mfma_f32_16x16x32_bf16 v[26:29], v[86:89], v[70:73], v[26:29]
	v_mfma_f32_16x16x32_bf16 v[14:17], v[208:211], v[70:73], v[14:17]
	v_mfma_f32_16x16x32_bf16 v[10:13], v[212:215], v[70:73], v[10:13]
	ds_read_b128 v[70:73], v255 offset:2048
	s_waitcnt lgkmcnt(7)
	v_mfma_f32_16x16x32_bf16 v[34:37], v[82:85], v[74:77], v[34:37]
	v_mfma_f32_16x16x32_bf16 v[22:25], v[86:89], v[74:77], v[22:25]
	v_mfma_f32_16x16x32_bf16 v[18:21], v[208:211], v[74:77], v[18:21]
	v_mfma_f32_16x16x32_bf16 v[62:65], v[212:215], v[74:77], v[62:65]
	ds_read_b128 v[74:77], v255 offset:4096
	s_waitcnt lgkmcnt(7)
	v_mfma_f32_16x16x32_bf16 v[58:61], v[82:85], v[78:81], v[58:61]
	v_mfma_f32_16x16x32_bf16 v[54:57], v[86:89], v[78:81], v[54:57]
	v_mfma_f32_16x16x32_bf16 v[50:53], v[208:211], v[78:81], v[50:53]
	v_mfma_f32_16x16x32_bf16 v[2:5], v[212:215], v[78:81], v[2:5]
	ds_read_b128 v[78:81], v255 offset:6144
	s_waitcnt lgkmcnt(3)
	v_mfma_f32_16x16x32_bf16 v[6:9], v[216:219], v[66:69], v[6:9]
	v_mfma_f32_16x16x32_bf16 v[30:33], v[220:223], v[66:69], v[30:33]
	v_mfma_f32_16x16x32_bf16 v[38:41], v[224:227], v[66:69], v[38:41]
	v_mfma_f32_16x16x32_bf16 v[42:45], v[228:231], v[66:69], v[42:45]
	s_waitcnt lgkmcnt(2)
	v_mfma_f32_16x16x32_bf16 v[46:49], v[216:219], v[70:73], v[46:49]
	v_mfma_f32_16x16x32_bf16 v[26:29], v[220:223], v[70:73], v[26:29]
	v_mfma_f32_16x16x32_bf16 v[14:17], v[224:227], v[70:73], v[14:17]
	v_mfma_f32_16x16x32_bf16 v[10:13], v[228:231], v[70:73], v[10:13]
	s_waitcnt vmcnt(14)
	s_waitcnt lgkmcnt(0)
	s_barrier
	s_add_i32 m0, s67, 0x10000
	s_nop 0
	global_load_lds_dwordx4 v188, s[80:81]
	s_add_i32 m0, s67, 0x12000
	s_nop 0
	global_load_lds_dwordx4 v189, s[80:81]
	s_add_i32 m0, s67, 0x14000
	s_nop 0
	global_load_lds_dwordx4 v190, s[80:81]
	s_add_i32 m0, s67, 0x16000
	s_nop 0
	global_load_lds_dwordx4 v191, s[80:81]
	s_add_i32 m0, s67, 0x20400
	s_nop 0
	global_load_lds_dwordx4 v205, s[96:97]
	s_add_i32 m0, s67, 0x22400
	s_nop 0
	global_load_lds_dwordx4 v206, s[96:97]
	s_add_u32 s80, s80, 0x80
	s_addc_u32 s81, s81, 0
	s_add_u32 s96, s96, 0x80
	s_addc_u32 s97, s97, 0
	ds_read_b128 v[82:85], v90 offset:0
	ds_read_b128 v[86:89], v90 offset:2048
	ds_read_b128 v[208:211], v90 offset:4096
	ds_read_b128 v[212:215], v90 offset:6144
	ds_read_b128 v[66:69], v207 offset:0
	ds_read_b128 v[70:73], v207 offset:2048
	v_mfma_f32_16x16x32_bf16 v[34:37], v[216:219], v[74:77], v[34:37]
	v_mfma_f32_16x16x32_bf16 v[22:25], v[220:223], v[74:77], v[22:25]
	v_mfma_f32_16x16x32_bf16 v[18:21], v[224:227], v[74:77], v[18:21]
	v_mfma_f32_16x16x32_bf16 v[62:65], v[228:231], v[74:77], v[62:65]
	ds_read_b128 v[74:77], v207 offset:4096
	v_mfma_f32_16x16x32_bf16 v[58:61], v[216:219], v[78:81], v[58:61]
	v_mfma_f32_16x16x32_bf16 v[54:57], v[220:223], v[78:81], v[54:57]
	v_mfma_f32_16x16x32_bf16 v[50:53], v[224:227], v[78:81], v[50:53]
	v_mfma_f32_16x16x32_bf16 v[2:5], v[228:231], v[78:81], v[2:5]
	ds_read_b128 v[78:81], v207 offset:6144
	ds_read_b128 v[216:219], v91 offset:0
	ds_read_b128 v[220:223], v91 offset:2048
	ds_read_b128 v[224:227], v91 offset:4096
	ds_read_b128 v[228:231], v91 offset:6144
	s_waitcnt lgkmcnt(7)
	v_mfma_f32_16x16x32_bf16 v[6:9], v[82:85], v[66:69], v[6:9]
	v_mfma_f32_16x16x32_bf16 v[30:33], v[86:89], v[66:69], v[30:33]
	v_mfma_f32_16x16x32_bf16 v[38:41], v[208:211], v[66:69], v[38:41]
	v_mfma_f32_16x16x32_bf16 v[42:45], v[212:215], v[66:69], v[42:45]
	ds_read_b128 v[66:69], v119 offset:0
	s_waitcnt lgkmcnt(7)
	v_mfma_f32_16x16x32_bf16 v[46:49], v[82:85], v[70:73], v[46:49]
	v_mfma_f32_16x16x32_bf16 v[26:29], v[86:89], v[70:73], v[26:29]
	v_mfma_f32_16x16x32_bf16 v[14:17], v[208:211], v[70:73], v[14:17]
	v_mfma_f32_16x16x32_bf16 v[10:13], v[212:215], v[70:73], v[10:13]
	ds_read_b128 v[70:73], v119 offset:2048
	s_waitcnt lgkmcnt(7)
	v_mfma_f32_16x16x32_bf16 v[34:37], v[82:85], v[74:77], v[34:37]
	v_mfma_f32_16x16x32_bf16 v[22:25], v[86:89], v[74:77], v[22:25]
	v_mfma_f32_16x16x32_bf16 v[18:21], v[208:211], v[74:77], v[18:21]
	v_mfma_f32_16x16x32_bf16 v[62:65], v[212:215], v[74:77], v[62:65]
	ds_read_b128 v[74:77], v119 offset:4096
	s_waitcnt lgkmcnt(7)
	v_mfma_f32_16x16x32_bf16 v[58:61], v[82:85], v[78:81], v[58:61]
	v_mfma_f32_16x16x32_bf16 v[54:57], v[86:89], v[78:81], v[54:57]
	v_mfma_f32_16x16x32_bf16 v[50:53], v[208:211], v[78:81], v[50:53]
	v_mfma_f32_16x16x32_bf16 v[2:5], v[212:215], v[78:81], v[2:5]
	ds_read_b128 v[78:81], v119 offset:6144
	s_waitcnt lgkmcnt(3)
	v_mfma_f32_16x16x32_bf16 v[6:9], v[216:219], v[66:69], v[6:9]
	v_mfma_f32_16x16x32_bf16 v[30:33], v[220:223], v[66:69], v[30:33]
	v_mfma_f32_16x16x32_bf16 v[38:41], v[224:227], v[66:69], v[38:41]
	v_mfma_f32_16x16x32_bf16 v[42:45], v[228:231], v[66:69], v[42:45]
	s_waitcnt lgkmcnt(2)
	v_mfma_f32_16x16x32_bf16 v[46:49], v[216:219], v[70:73], v[46:49]
	v_mfma_f32_16x16x32_bf16 v[26:29], v[220:223], v[70:73], v[26:29]
	v_mfma_f32_16x16x32_bf16 v[14:17], v[224:227], v[70:73], v[14:17]
	v_mfma_f32_16x16x32_bf16 v[10:13], v[228:231], v[70:73], v[10:13]
	s_waitcnt vmcnt(6)
	s_waitcnt lgkmcnt(0)
	s_barrier
	s_add_i32 m0, s67, 0x0
	s_nop 0
	global_load_lds_dwordx4 v188, s[80:81]
	s_add_i32 m0, s67, 0x2000
	s_nop 0
	global_load_lds_dwordx4 v189, s[80:81]
	s_add_i32 m0, s67, 0x4000
	s_nop 0
	global_load_lds_dwordx4 v190, s[80:81]
	s_add_i32 m0, s67, 0x6000
	s_nop 0
	global_load_lds_dwordx4 v191, s[80:81]
	s_add_i32 m0, s67, 0x18000
	s_nop 0
	global_load_lds_dwordx4 v205, s[96:97]
	s_add_i32 m0, s67, 0x1a000
	s_nop 0
	global_load_lds_dwordx4 v206, s[96:97]
	s_add_u32 s80, s80, 0x80
	s_addc_u32 s81, s81, 0
	s_add_u32 s96, s96, 0x80
	s_addc_u32 s97, s97, 0
	ds_read_b128 v[82:85], v90 offset:16384
	ds_read_b128 v[86:89], v90 offset:18432
	ds_read_b128 v[208:211], v90 offset:20480
	ds_read_b128 v[212:215], v90 offset:22528
	ds_read_b128 v[66:69], v207 offset:32768
	ds_read_b128 v[70:73], v207 offset:34816
	v_mfma_f32_16x16x32_bf16 v[34:37], v[216:219], v[74:77], v[34:37]
	v_mfma_f32_16x16x32_bf16 v[22:25], v[220:223], v[74:77], v[22:25]
	v_mfma_f32_16x16x32_bf16 v[18:21], v[224:227], v[74:77], v[18:21]
	v_mfma_f32_16x16x32_bf16 v[62:65], v[228:231], v[74:77], v[62:65]
	ds_read_b128 v[74:77], v207 offset:36864
	v_mfma_f32_16x16x32_bf16 v[58:61], v[216:219], v[78:81], v[58:61]
	v_mfma_f32_16x16x32_bf16 v[54:57], v[220:223], v[78:81], v[54:57]
	v_mfma_f32_16x16x32_bf16 v[50:53], v[224:227], v[78:81], v[50:53]
	v_mfma_f32_16x16x32_bf16 v[2:5], v[228:231], v[78:81], v[2:5]
	ds_read_b128 v[78:81], v207 offset:38912
	ds_read_b128 v[216:219], v91 offset:16384
	ds_read_b128 v[220:223], v91 offset:18432
	ds_read_b128 v[224:227], v91 offset:20480
	ds_read_b128 v[228:231], v91 offset:22528
	s_waitcnt lgkmcnt(7)
	v_mfma_f32_16x16x32_bf16 v[6:9], v[82:85], v[66:69], v[6:9]
	v_mfma_f32_16x16x32_bf16 v[30:33], v[86:89], v[66:69], v[30:33]
	v_mfma_f32_16x16x32_bf16 v[38:41], v[208:211], v[66:69], v[38:41]
	v_mfma_f32_16x16x32_bf16 v[42:45], v[212:215], v[66:69], v[42:45]
	ds_read_b128 v[66:69], v119 offset:32768
	s_waitcnt lgkmcnt(7)
	v_mfma_f32_16x16x32_bf16 v[46:49], v[82:85], v[70:73], v[46:49]
	v_mfma_f32_16x16x32_bf16 v[26:29], v[86:89], v[70:73], v[26:29]
	v_mfma_f32_16x16x32_bf16 v[14:17], v[208:211], v[70:73], v[14:17]
	v_mfma_f32_16x16x32_bf16 v[10:13], v[212:215], v[70:73], v[10:13]
	ds_read_b128 v[70:73], v119 offset:34816
	s_waitcnt lgkmcnt(7)
	v_mfma_f32_16x16x32_bf16 v[34:37], v[82:85], v[74:77], v[34:37]
	v_mfma_f32_16x16x32_bf16 v[22:25], v[86:89], v[74:77], v[22:25]
	v_mfma_f32_16x16x32_bf16 v[18:21], v[208:211], v[74:77], v[18:21]
	v_mfma_f32_16x16x32_bf16 v[62:65], v[212:215], v[74:77], v[62:65]
	ds_read_b128 v[74:77], v119 offset:36864
	s_waitcnt lgkmcnt(7)
	v_mfma_f32_16x16x32_bf16 v[58:61], v[82:85], v[78:81], v[58:61]
	v_mfma_f32_16x16x32_bf16 v[54:57], v[86:89], v[78:81], v[54:57]
	v_mfma_f32_16x16x32_bf16 v[50:53], v[208:211], v[78:81], v[50:53]
	v_mfma_f32_16x16x32_bf16 v[2:5], v[212:215], v[78:81], v[2:5]
	ds_read_b128 v[78:81], v119 offset:38912
	s_waitcnt lgkmcnt(3)
	v_mfma_f32_16x16x32_bf16 v[6:9], v[216:219], v[66:69], v[6:9]
	s_waitcnt vmcnt(18)
	v_mfma_f32_16x16x32_bf16 v[30:33], v[220:223], v[66:69], v[30:33]
	v_mfma_f32_16x16x32_bf16 v[38:41], v[224:227], v[66:69], v[38:41]
	v_mfma_f32_16x16x32_bf16 v[42:45], v[228:231], v[66:69], v[42:45]
	v_cvt_f32_ubyte0_e32 v248, v232
	v_cvt_f32_ubyte1_e32 v249, v232
	v_cvt_f32_ubyte2_e32 v250, v232
	v_cvt_f32_ubyte3_e32 v251, v232
	v_mul_f32_e32 v248, s34, v248
	v_mul_f32_e32 v249, s34, v249
	v_mul_f32_e32 v250, s34, v250
	v_mul_f32_e32 v251, s34, v251
	v_fma_f32 v184, v6, v248, v184
	v_fma_f32 v185, v7, v249, v185
	v_fma_f32 v186, v8, v250, v186
	v_fma_f32 v187, v9, v251, v187
	s_waitcnt lgkmcnt(2)
	v_mfma_f32_16x16x32_bf16 v[46:49], v[216:219], v[70:73], v[46:49]
	v_cvt_f32_ubyte0_e32 v248, v233
	v_cvt_f32_ubyte1_e32 v249, v233
	v_cvt_f32_ubyte2_e32 v250, v233
	v_cvt_f32_ubyte3_e32 v251, v233
	v_mul_f32_e32 v248, s34, v248
	v_mul_f32_e32 v249, s34, v249
	v_mul_f32_e32 v250, s34, v250
	v_mul_f32_e32 v251, s34, v251
	v_fma_f32 v180, v30, v248, v180
	v_fma_f32 v181, v31, v249, v181
	v_fma_f32 v182, v32, v250, v182
	v_fma_f32 v183, v33, v251, v183
	v_mfma_f32_16x16x32_bf16 v[26:29], v[220:223], v[70:73], v[26:29]
	v_cvt_f32_ubyte0_e32 v248, v234
	v_cvt_f32_ubyte1_e32 v249, v234
	v_cvt_f32_ubyte2_e32 v250, v234
	v_cvt_f32_ubyte3_e32 v251, v234
	v_mul_f32_e32 v248, s34, v248
	v_mul_f32_e32 v249, s34, v249
	v_mul_f32_e32 v250, s34, v250
	v_mul_f32_e32 v251, s34, v251
	v_fma_f32 v176, v38, v248, v176
	v_fma_f32 v177, v39, v249, v177
	v_fma_f32 v178, v40, v250, v178
	v_fma_f32 v179, v41, v251, v179
	v_mfma_f32_16x16x32_bf16 v[14:17], v[224:227], v[70:73], v[14:17]
	v_cvt_f32_ubyte0_e32 v248, v235
	v_cvt_f32_ubyte1_e32 v249, v235
	v_cvt_f32_ubyte2_e32 v250, v235
	v_cvt_f32_ubyte3_e32 v251, v235
	v_mul_f32_e32 v248, s34, v248
	v_mul_f32_e32 v249, s34, v249
	v_mul_f32_e32 v250, s34, v250
	v_mul_f32_e32 v251, s34, v251
	v_fma_f32 v172, v42, v248, v172
	v_fma_f32 v173, v43, v249, v173
	v_fma_f32 v174, v44, v250, v174
	v_fma_f32 v175, v45, v251, v175
	v_mfma_f32_16x16x32_bf16 v[10:13], v[228:231], v[70:73], v[10:13]
	v_cvt_f32_ubyte0_e32 v248, v236
	v_cvt_f32_ubyte1_e32 v249, v236
	v_cvt_f32_ubyte2_e32 v250, v236
	v_cvt_f32_ubyte3_e32 v251, v236
	v_mul_f32_e32 v248, s34, v248
	v_mul_f32_e32 v249, s34, v249
	v_mul_f32_e32 v250, s34, v250
	v_mul_f32_e32 v251, s34, v251
	v_fma_f32 v168, v46, v248, v168
	v_fma_f32 v169, v47, v249, v169
	v_fma_f32 v170, v48, v250, v170
	v_fma_f32 v171, v49, v251, v171
	s_waitcnt vmcnt(6)
	s_waitcnt lgkmcnt(0)
	s_barrier
	s_add_i32 m0, s67, 0x8000
	s_nop 0
	global_load_lds_dwordx4 v188, s[80:81]
	s_add_i32 m0, s67, 0xa000
	s_nop 0
	global_load_lds_dwordx4 v189, s[80:81]
	s_add_i32 m0, s67, 0xc000
	s_nop 0
	global_load_lds_dwordx4 v190, s[80:81]
	s_add_i32 m0, s67, 0xe000
	s_nop 0
	global_load_lds_dwordx4 v191, s[80:81]
	s_add_i32 m0, s67, 0x1c000
	s_nop 0
	global_load_lds_dwordx4 v205, s[96:97]
	s_add_i32 m0, s67, 0x1e000
	s_nop 0
	global_load_lds_dwordx4 v206, s[96:97]
	s_add_u32 s80, s80, 0x80
	s_addc_u32 s81, s81, 0
	s_add_u32 s96, s96, 0x80
	s_addc_u32 s97, s97, 0
	ds_read_b128 v[82:85], v90 offset:33792
	ds_read_b128 v[86:89], v90 offset:35840
	ds_read_b128 v[208:211], v90 offset:37888
	ds_read_b128 v[212:215], v90 offset:39936
	ds_read_b128 v[66:69], v0 offset:0
	ds_read_b128 v[70:73], v0 offset:2048
	v_mfma_f32_16x16x32_bf16 v[34:37], v[216:219], v[74:77], v[34:37]
	v_cvt_f32_ubyte0_e32 v248, v237
	v_cvt_f32_ubyte1_e32 v249, v237
	v_cvt_f32_ubyte2_e32 v250, v237
	v_cvt_f32_ubyte3_e32 v251, v237
	v_mul_f32_e32 v248, s34, v248
	v_mul_f32_e32 v249, s34, v249
	v_mul_f32_e32 v250, s34, v250
	v_mul_f32_e32 v251, s34, v251
	v_fma_f32 v164, v26, v248, v164
	v_fma_f32 v165, v27, v249, v165
	v_fma_f32 v166, v28, v250, v166
	v_fma_f32 v167, v29, v251, v167
	v_mfma_f32_16x16x32_bf16 v[22:25], v[220:223], v[74:77], v[22:25]
	v_cvt_f32_ubyte0_e32 v248, v238
	v_cvt_f32_ubyte1_e32 v249, v238
	v_cvt_f32_ubyte2_e32 v250, v238
	v_cvt_f32_ubyte3_e32 v251, v238
	v_mul_f32_e32 v248, s34, v248
	v_mul_f32_e32 v249, s34, v249
	v_mul_f32_e32 v250, s34, v250
	v_mul_f32_e32 v251, s34, v251
	v_fma_f32 v160, v14, v248, v160
	v_fma_f32 v161, v15, v249, v161
	v_fma_f32 v162, v16, v250, v162
	v_fma_f32 v163, v17, v251, v163
	v_mfma_f32_16x16x32_bf16 v[18:21], v[224:227], v[74:77], v[18:21]
	v_cvt_f32_ubyte0_e32 v248, v239
	v_cvt_f32_ubyte1_e32 v249, v239
	v_cvt_f32_ubyte2_e32 v250, v239
	v_cvt_f32_ubyte3_e32 v251, v239
	v_mul_f32_e32 v248, s34, v248
	v_mul_f32_e32 v249, s34, v249
	v_mul_f32_e32 v250, s34, v250
	v_mul_f32_e32 v251, s34, v251
	v_fma_f32 v156, v10, v248, v156
	v_fma_f32 v157, v11, v249, v157
	v_fma_f32 v158, v12, v250, v158
	v_fma_f32 v159, v13, v251, v159
	v_mfma_f32_16x16x32_bf16 v[62:65], v[228:231], v[74:77], v[62:65]
	v_cvt_f32_ubyte0_e32 v248, v240
	v_cvt_f32_ubyte1_e32 v249, v240
	v_cvt_f32_ubyte2_e32 v250, v240
	v_cvt_f32_ubyte3_e32 v251, v240
	v_mul_f32_e32 v248, s34, v248
	v_mul_f32_e32 v249, s34, v249
	v_mul_f32_e32 v250, s34, v250
	v_mul_f32_e32 v251, s34, v251
	v_fma_f32 v136, v34, v248, v136
	v_fma_f32 v137, v35, v249, v137
	v_fma_f32 v150, v36, v250, v150
	v_fma_f32 v151, v37, v251, v151
	ds_read_b128 v[74:77], v0 offset:4096
	v_mfma_f32_16x16x32_bf16 v[58:61], v[216:219], v[78:81], v[58:61]
	v_cvt_f32_ubyte0_e32 v248, v241
	v_cvt_f32_ubyte1_e32 v249, v241
	v_cvt_f32_ubyte2_e32 v250, v241
	v_cvt_f32_ubyte3_e32 v251, v241
	v_mul_f32_e32 v248, s34, v248
	v_mul_f32_e32 v249, s34, v249
	v_mul_f32_e32 v250, s34, v250
	v_mul_f32_e32 v251, s34, v251
	v_fma_f32 v130, v22, v248, v130
	v_fma_f32 v131, v23, v249, v131
	v_fma_f32 v134, v24, v250, v134
	v_fma_f32 v135, v25, v251, v135
	v_mfma_f32_16x16x32_bf16 v[54:57], v[220:223], v[78:81], v[54:57]
	v_cvt_f32_ubyte0_e32 v248, v242
	v_cvt_f32_ubyte1_e32 v249, v242
	v_cvt_f32_ubyte2_e32 v250, v242
	v_cvt_f32_ubyte3_e32 v251, v242
	v_mul_f32_e32 v248, s34, v248
	v_mul_f32_e32 v249, s34, v249
	v_mul_f32_e32 v250, s34, v250
	v_mul_f32_e32 v251, s34, v251
	v_fma_f32 v124, v18, v248, v124
	v_fma_f32 v125, v19, v249, v125
	v_fma_f32 v126, v20, v250, v126
	v_fma_f32 v127, v21, v251, v127
	v_mfma_f32_16x16x32_bf16 v[50:53], v[224:227], v[78:81], v[50:53]
	v_cvt_f32_ubyte0_e32 v248, v243
	v_cvt_f32_ubyte1_e32 v249, v243
	v_cvt_f32_ubyte2_e32 v250, v243
	v_cvt_f32_ubyte3_e32 v251, v243
	v_mul_f32_e32 v248, s34, v248
	v_mul_f32_e32 v249, s34, v249
	v_mul_f32_e32 v250, s34, v250
	v_mul_f32_e32 v251, s34, v251
	v_fma_f32 v120, v62, v248, v120
	v_fma_f32 v121, v63, v249, v121
	v_fma_f32 v122, v64, v250, v122
	v_fma_f32 v123, v65, v251, v123
	v_mfma_f32_16x16x32_bf16 v[2:5], v[228:231], v[78:81], v[2:5]
	v_cvt_f32_ubyte0_e32 v248, v244
	v_cvt_f32_ubyte1_e32 v249, v244
	v_cvt_f32_ubyte2_e32 v250, v244
	v_cvt_f32_ubyte3_e32 v251, v244
	v_mul_f32_e32 v248, s34, v248
	v_mul_f32_e32 v249, s34, v249
	v_mul_f32_e32 v250, s34, v250
	v_mul_f32_e32 v251, s34, v251
	v_fma_f32 v114, v58, v248, v114
	v_fma_f32 v115, v59, v249, v115
	v_fma_f32 v116, v60, v250, v116
	v_fma_f32 v117, v61, v251, v117
	ds_read_b128 v[78:81], v0 offset:6144
	s_nop 7
	s_nop 3
	v_cvt_f32_ubyte0_e32 v248, v245
	v_cvt_f32_ubyte1_e32 v249, v245
	v_cvt_f32_ubyte2_e32 v250, v245
	v_cvt_f32_ubyte3_e32 v251, v245
	v_mul_f32_e32 v248, s34, v248
	v_mul_f32_e32 v249, s34, v249
	v_mul_f32_e32 v250, s34, v250
	v_mul_f32_e32 v251, s34, v251
	v_fma_f32 v106, v54, v248, v106
	v_fma_f32 v107, v55, v249, v107
	v_fma_f32 v108, v56, v250, v108
	v_fma_f32 v109, v57, v251, v109
	v_cvt_f32_ubyte0_e32 v248, v246
	v_cvt_f32_ubyte1_e32 v249, v246
	v_cvt_f32_ubyte2_e32 v250, v246
	v_cvt_f32_ubyte3_e32 v251, v246
	v_mul_f32_e32 v248, s34, v248
	v_mul_f32_e32 v249, s34, v249
	v_mul_f32_e32 v250, s34, v250
	v_mul_f32_e32 v251, s34, v251
	v_fma_f32 v100, v50, v248, v100
	v_fma_f32 v101, v51, v249, v101
	v_fma_f32 v102, v52, v250, v102
	v_fma_f32 v103, v53, v251, v103
	v_cvt_f32_ubyte0_e32 v248, v247
	v_cvt_f32_ubyte1_e32 v249, v247
	v_cvt_f32_ubyte2_e32 v250, v247
	v_cvt_f32_ubyte3_e32 v251, v247
	v_mul_f32_e32 v248, s34, v248
	v_mul_f32_e32 v249, s34, v249
	v_mul_f32_e32 v250, s34, v250
	v_mul_f32_e32 v251, s34, v251
	v_fma_f32 v96, v2, v248, v96
	v_fma_f32 v97, v3, v249, v97
	v_fma_f32 v98, v4, v250, v98
	v_fma_f32 v99, v5, v251, v99
	s_add_u32 s98, s86, 0x1600
	s_addc_u32 s99, s87, 0
	global_load_dword v92, v93, s[98:99]
	ds_read_b128 v[216:219], v91 offset:33792
	ds_read_b128 v[220:223], v91 offset:35840
	ds_read_b128 v[224:227], v91 offset:37888
	ds_read_b128 v[228:231], v91 offset:39936
	s_waitcnt lgkmcnt(7)
	v_mfma_f32_16x16x32_bf16 v[6:9], v[82:85], v[66:69], 0
	v_mfma_f32_16x16x32_bf16 v[30:33], v[86:89], v[66:69], 0
	v_mfma_f32_16x16x32_bf16 v[38:41], v[208:211], v[66:69], 0
	v_mfma_f32_16x16x32_bf16 v[42:45], v[212:215], v[66:69], 0
	ds_read_b128 v[66:69], v255 offset:0
	s_waitcnt lgkmcnt(7)
	v_mfma_f32_16x16x32_bf16 v[46:49], v[82:85], v[70:73], 0
	v_mfma_f32_16x16x32_bf16 v[26:29], v[86:89], v[70:73], 0
	v_mfma_f32_16x16x32_bf16 v[14:17], v[208:211], v[70:73], 0
	v_mfma_f32_16x16x32_bf16 v[10:13], v[212:215], v[70:73], 0
	ds_read_b128 v[70:73], v255 offset:2048
	s_waitcnt lgkmcnt(7)
	v_mfma_f32_16x16x32_bf16 v[34:37], v[82:85], v[74:77], 0
	v_mfma_f32_16x16x32_bf16 v[22:25], v[86:89], v[74:77], 0
	v_mfma_f32_16x16x32_bf16 v[18:21], v[208:211], v[74:77], 0
	v_mfma_f32_16x16x32_bf16 v[62:65], v[212:215], v[74:77], 0
	ds_read_b128 v[74:77], v255 offset:4096
	s_waitcnt lgkmcnt(7)
	v_mfma_f32_16x16x32_bf16 v[58:61], v[82:85], v[78:81], 0
	v_mfma_f32_16x16x32_bf16 v[54:57], v[86:89], v[78:81], 0
	v_mfma_f32_16x16x32_bf16 v[50:53], v[208:211], v[78:81], 0
	v_mfma_f32_16x16x32_bf16 v[2:5], v[212:215], v[78:81], 0
	ds_read_b128 v[78:81], v255 offset:6144
	s_waitcnt lgkmcnt(3)
	v_mfma_f32_16x16x32_bf16 v[6:9], v[216:219], v[66:69], v[6:9]
	v_mfma_f32_16x16x32_bf16 v[30:33], v[220:223], v[66:69], v[30:33]
	v_mfma_f32_16x16x32_bf16 v[38:41], v[224:227], v[66:69], v[38:41]
	v_mfma_f32_16x16x32_bf16 v[42:45], v[228:231], v[66:69], v[42:45]
	s_waitcnt lgkmcnt(2)
	v_mfma_f32_16x16x32_bf16 v[46:49], v[216:219], v[70:73], v[46:49]
	v_mfma_f32_16x16x32_bf16 v[26:29], v[220:223], v[70:73], v[26:29]
	v_mfma_f32_16x16x32_bf16 v[14:17], v[224:227], v[70:73], v[14:17]
	v_mfma_f32_16x16x32_bf16 v[10:13], v[228:231], v[70:73], v[10:13]
	s_waitcnt vmcnt(7)
	s_waitcnt lgkmcnt(0)
	s_barrier
	s_add_i32 m0, s67, 0x10000
	s_nop 0
	global_load_lds_dwordx4 v188, s[80:81]
	s_add_i32 m0, s67, 0x12000
	s_nop 0
	global_load_lds_dwordx4 v189, s[80:81]
	s_add_i32 m0, s67, 0x14000
	s_nop 0
	global_load_lds_dwordx4 v190, s[80:81]
	s_add_i32 m0, s67, 0x16000
	s_nop 0
	global_load_lds_dwordx4 v191, s[80:81]
	s_add_i32 m0, s67, 0x20400
	s_nop 0
	global_load_lds_dwordx4 v205, s[96:97]
	s_add_i32 m0, s67, 0x22400
	s_nop 0
	global_load_lds_dwordx4 v206, s[96:97]
	s_add_u32 s80, s80, 0x80
	s_addc_u32 s81, s81, 0
	s_add_u32 s96, s96, 0x80
	s_addc_u32 s97, s97, 0
	ds_read_b128 v[82:85], v90 offset:0
	ds_read_b128 v[86:89], v90 offset:2048
	ds_read_b128 v[208:211], v90 offset:4096
	ds_read_b128 v[212:215], v90 offset:6144
	ds_read_b128 v[66:69], v207 offset:0
	ds_read_b128 v[70:73], v207 offset:2048
	v_mfma_f32_16x16x32_bf16 v[34:37], v[216:219], v[74:77], v[34:37]
	v_mfma_f32_16x16x32_bf16 v[22:25], v[220:223], v[74:77], v[22:25]
	v_mfma_f32_16x16x32_bf16 v[18:21], v[224:227], v[74:77], v[18:21]
	v_mfma_f32_16x16x32_bf16 v[62:65], v[228:231], v[74:77], v[62:65]
	ds_read_b128 v[74:77], v207 offset:4096
	v_mfma_f32_16x16x32_bf16 v[58:61], v[216:219], v[78:81], v[58:61]
	v_mfma_f32_16x16x32_bf16 v[54:57], v[220:223], v[78:81], v[54:57]
	v_mfma_f32_16x16x32_bf16 v[50:53], v[224:227], v[78:81], v[50:53]
	v_mfma_f32_16x16x32_bf16 v[2:5], v[228:231], v[78:81], v[2:5]
	ds_read_b128 v[78:81], v207 offset:6144
	ds_read_b128 v[216:219], v91 offset:0
	ds_read_b128 v[220:223], v91 offset:2048
	ds_read_b128 v[224:227], v91 offset:4096
	ds_read_b128 v[228:231], v91 offset:6144
	s_waitcnt lgkmcnt(7)
	v_mfma_f32_16x16x32_bf16 v[6:9], v[82:85], v[66:69], v[6:9]
	v_mfma_f32_16x16x32_bf16 v[30:33], v[86:89], v[66:69], v[30:33]
	v_mfma_f32_16x16x32_bf16 v[38:41], v[208:211], v[66:69], v[38:41]
	v_mfma_f32_16x16x32_bf16 v[42:45], v[212:215], v[66:69], v[42:45]
	ds_read_b128 v[66:69], v119 offset:0
	s_waitcnt lgkmcnt(7)
	v_mfma_f32_16x16x32_bf16 v[46:49], v[82:85], v[70:73], v[46:49]
	v_mfma_f32_16x16x32_bf16 v[26:29], v[86:89], v[70:73], v[26:29]
	v_mfma_f32_16x16x32_bf16 v[14:17], v[208:211], v[70:73], v[14:17]
	v_mfma_f32_16x16x32_bf16 v[10:13], v[212:215], v[70:73], v[10:13]
	ds_read_b128 v[70:73], v119 offset:2048
	s_waitcnt lgkmcnt(7)
	v_mfma_f32_16x16x32_bf16 v[34:37], v[82:85], v[74:77], v[34:37]
	v_mfma_f32_16x16x32_bf16 v[22:25], v[86:89], v[74:77], v[22:25]
	v_mfma_f32_16x16x32_bf16 v[18:21], v[208:211], v[74:77], v[18:21]
	v_mfma_f32_16x16x32_bf16 v[62:65], v[212:215], v[74:77], v[62:65]
	ds_read_b128 v[74:77], v119 offset:4096
	s_waitcnt lgkmcnt(7)
	v_mfma_f32_16x16x32_bf16 v[58:61], v[82:85], v[78:81], v[58:61]
	v_mfma_f32_16x16x32_bf16 v[54:57], v[86:89], v[78:81], v[54:57]
	v_mfma_f32_16x16x32_bf16 v[50:53], v[208:211], v[78:81], v[50:53]
	v_mfma_f32_16x16x32_bf16 v[2:5], v[212:215], v[78:81], v[2:5]
	ds_read_b128 v[78:81], v119 offset:6144
	s_waitcnt lgkmcnt(3)
	v_mfma_f32_16x16x32_bf16 v[6:9], v[216:219], v[66:69], v[6:9]
	v_mfma_f32_16x16x32_bf16 v[30:33], v[220:223], v[66:69], v[30:33]
	v_mfma_f32_16x16x32_bf16 v[38:41], v[224:227], v[66:69], v[38:41]
	v_mfma_f32_16x16x32_bf16 v[42:45], v[228:231], v[66:69], v[42:45]
	s_waitcnt lgkmcnt(2)
	v_mfma_f32_16x16x32_bf16 v[46:49], v[216:219], v[70:73], v[46:49]
	v_mfma_f32_16x16x32_bf16 v[26:29], v[220:223], v[70:73], v[26:29]
	v_mfma_f32_16x16x32_bf16 v[14:17], v[224:227], v[70:73], v[14:17]
	v_mfma_f32_16x16x32_bf16 v[10:13], v[228:231], v[70:73], v[10:13]
	s_waitcnt vmcnt(7)
	s_waitcnt lgkmcnt(0)
	s_barrier
	s_add_i32 m0, s67, 0x0
	s_nop 0
	global_load_lds_dwordx4 v188, s[80:81]
	s_add_i32 m0, s67, 0x2000
	s_nop 0
	global_load_lds_dwordx4 v189, s[80:81]
	s_add_i32 m0, s67, 0x4000
	s_nop 0
	global_load_lds_dwordx4 v190, s[80:81]
	s_add_i32 m0, s67, 0x6000
	s_nop 0
	global_load_lds_dwordx4 v191, s[80:81]
	s_add_i32 m0, s67, 0x18000
	s_nop 0
	global_load_lds_dwordx4 v205, s[96:97]
	s_add_i32 m0, s67, 0x1a000
	s_nop 0
	global_load_lds_dwordx4 v206, s[96:97]
	s_add_u32 s80, s80, 0x80
	s_addc_u32 s81, s81, 0
	s_add_u32 s96, s96, 0x80
	s_addc_u32 s97, s97, 0
	ds_read_b128 v[82:85], v90 offset:16384
	ds_read_b128 v[86:89], v90 offset:18432
	ds_read_b128 v[208:211], v90 offset:20480
	ds_read_b128 v[212:215], v90 offset:22528
	ds_read_b128 v[66:69], v207 offset:32768
	ds_read_b128 v[70:73], v207 offset:34816
	v_mfma_f32_16x16x32_bf16 v[34:37], v[216:219], v[74:77], v[34:37]
	v_mfma_f32_16x16x32_bf16 v[22:25], v[220:223], v[74:77], v[22:25]
	v_mfma_f32_16x16x32_bf16 v[18:21], v[224:227], v[74:77], v[18:21]
	v_mfma_f32_16x16x32_bf16 v[62:65], v[228:231], v[74:77], v[62:65]
	ds_read_b128 v[74:77], v207 offset:36864
	v_mfma_f32_16x16x32_bf16 v[58:61], v[216:219], v[78:81], v[58:61]
	v_mfma_f32_16x16x32_bf16 v[54:57], v[220:223], v[78:81], v[54:57]
	v_mfma_f32_16x16x32_bf16 v[50:53], v[224:227], v[78:81], v[50:53]
	v_mfma_f32_16x16x32_bf16 v[2:5], v[228:231], v[78:81], v[2:5]
	ds_read_b128 v[78:81], v207 offset:38912
	ds_read_b128 v[216:219], v91 offset:16384
	ds_read_b128 v[220:223], v91 offset:18432
	ds_read_b128 v[224:227], v91 offset:20480
	ds_read_b128 v[228:231], v91 offset:22528
	s_waitcnt lgkmcnt(7)
	v_mfma_f32_16x16x32_bf16 v[6:9], v[82:85], v[66:69], v[6:9]
	v_mfma_f32_16x16x32_bf16 v[30:33], v[86:89], v[66:69], v[30:33]
	v_mfma_f32_16x16x32_bf16 v[38:41], v[208:211], v[66:69], v[38:41]
	v_mfma_f32_16x16x32_bf16 v[42:45], v[212:215], v[66:69], v[42:45]
	ds_read_b128 v[66:69], v119 offset:32768
	s_waitcnt lgkmcnt(7)
	v_mfma_f32_16x16x32_bf16 v[46:49], v[82:85], v[70:73], v[46:49]
	v_mfma_f32_16x16x32_bf16 v[26:29], v[86:89], v[70:73], v[26:29]
	v_mfma_f32_16x16x32_bf16 v[14:17], v[208:211], v[70:73], v[14:17]
	v_mfma_f32_16x16x32_bf16 v[10:13], v[212:215], v[70:73], v[10:13]
	ds_read_b128 v[70:73], v119 offset:34816
	s_waitcnt lgkmcnt(7)
	v_mfma_f32_16x16x32_bf16 v[34:37], v[82:85], v[74:77], v[34:37]
	v_mfma_f32_16x16x32_bf16 v[22:25], v[86:89], v[74:77], v[22:25]
	v_mfma_f32_16x16x32_bf16 v[18:21], v[208:211], v[74:77], v[18:21]
	v_mfma_f32_16x16x32_bf16 v[62:65], v[212:215], v[74:77], v[62:65]
	ds_read_b128 v[74:77], v119 offset:36864
	s_waitcnt lgkmcnt(7)
	v_mfma_f32_16x16x32_bf16 v[58:61], v[82:85], v[78:81], v[58:61]
	v_mfma_f32_16x16x32_bf16 v[54:57], v[86:89], v[78:81], v[54:57]
	v_mfma_f32_16x16x32_bf16 v[50:53], v[208:211], v[78:81], v[50:53]
	v_mfma_f32_16x16x32_bf16 v[2:5], v[212:215], v[78:81], v[2:5]
	ds_read_b128 v[78:81], v119 offset:38912
	s_waitcnt lgkmcnt(3)
	v_mfma_f32_16x16x32_bf16 v[6:9], v[216:219], v[66:69], v[6:9]
	v_mfma_f32_16x16x32_bf16 v[30:33], v[220:223], v[66:69], v[30:33]
	v_mfma_f32_16x16x32_bf16 v[38:41], v[224:227], v[66:69], v[38:41]
	v_mfma_f32_16x16x32_bf16 v[42:45], v[228:231], v[66:69], v[42:45]
	s_waitcnt lgkmcnt(2)
	v_mfma_f32_16x16x32_bf16 v[46:49], v[216:219], v[70:73], v[46:49]
	v_mfma_f32_16x16x32_bf16 v[26:29], v[220:223], v[70:73], v[26:29]
	v_mfma_f32_16x16x32_bf16 v[14:17], v[224:227], v[70:73], v[14:17]
	v_mfma_f32_16x16x32_bf16 v[10:13], v[228:231], v[70:73], v[10:13]
	s_waitcnt vmcnt(6)
	s_waitcnt lgkmcnt(0)
	s_barrier
	s_add_i32 m0, s67, 0x8000
	s_nop 0
	global_load_lds_dwordx4 v188, s[80:81]
	s_add_i32 m0, s67, 0xa000
	s_nop 0
	global_load_lds_dwordx4 v189, s[80:81]
	s_add_i32 m0, s67, 0xc000
	s_nop 0
	global_load_lds_dwordx4 v190, s[80:81]
	s_add_i32 m0, s67, 0xe000
	s_nop 0
	global_load_lds_dwordx4 v191, s[80:81]
	s_add_i32 m0, s67, 0x1c000
	s_nop 0
	global_load_lds_dwordx4 v205, s[96:97]
	s_add_i32 m0, s67, 0x1e000
	s_nop 0
	global_load_lds_dwordx4 v206, s[96:97]
	s_add_u32 s80, s80, 0x80
	s_addc_u32 s81, s81, 0
	s_add_u32 s96, s96, 0x80
	s_addc_u32 s97, s97, 0
	ds_read_b128 v[82:85], v90 offset:33792
	ds_read_b128 v[86:89], v90 offset:35840
	ds_read_b128 v[208:211], v90 offset:37888
	ds_read_b128 v[212:215], v90 offset:39936
	ds_read_b128 v[66:69], v0 offset:0
	ds_read_b128 v[70:73], v0 offset:2048
	v_mfma_f32_16x16x32_bf16 v[34:37], v[216:219], v[74:77], v[34:37]
	v_mfma_f32_16x16x32_bf16 v[22:25], v[220:223], v[74:77], v[22:25]
	v_mfma_f32_16x16x32_bf16 v[18:21], v[224:227], v[74:77], v[18:21]
	v_mfma_f32_16x16x32_bf16 v[62:65], v[228:231], v[74:77], v[62:65]
	ds_read_b128 v[74:77], v0 offset:4096
	v_mfma_f32_16x16x32_bf16 v[58:61], v[216:219], v[78:81], v[58:61]
	v_mfma_f32_16x16x32_bf16 v[54:57], v[220:223], v[78:81], v[54:57]
	v_mfma_f32_16x16x32_bf16 v[50:53], v[224:227], v[78:81], v[50:53]
	v_mfma_f32_16x16x32_bf16 v[2:5], v[228:231], v[78:81], v[2:5]
	ds_read_b128 v[78:81], v0 offset:6144
	ds_read_b128 v[216:219], v91 offset:33792
	ds_read_b128 v[220:223], v91 offset:35840
	ds_read_b128 v[224:227], v91 offset:37888
	ds_read_b128 v[228:231], v91 offset:39936
	s_waitcnt lgkmcnt(7)
	v_mfma_f32_16x16x32_bf16 v[6:9], v[82:85], v[66:69], v[6:9]
	v_mfma_f32_16x16x32_bf16 v[30:33], v[86:89], v[66:69], v[30:33]
	v_mfma_f32_16x16x32_bf16 v[38:41], v[208:211], v[66:69], v[38:41]
	v_mfma_f32_16x16x32_bf16 v[42:45], v[212:215], v[66:69], v[42:45]
	ds_read_b128 v[66:69], v255 offset:0
	s_waitcnt lgkmcnt(7)
	v_mfma_f32_16x16x32_bf16 v[46:49], v[82:85], v[70:73], v[46:49]
	v_mfma_f32_16x16x32_bf16 v[26:29], v[86:89], v[70:73], v[26:29]
	v_mfma_f32_16x16x32_bf16 v[14:17], v[208:211], v[70:73], v[14:17]
	v_mfma_f32_16x16x32_bf16 v[10:13], v[212:215], v[70:73], v[10:13]
	ds_read_b128 v[70:73], v255 offset:2048
	s_waitcnt lgkmcnt(7)
	v_mfma_f32_16x16x32_bf16 v[34:37], v[82:85], v[74:77], v[34:37]
	v_mfma_f32_16x16x32_bf16 v[22:25], v[86:89], v[74:77], v[22:25]
	v_mfma_f32_16x16x32_bf16 v[18:21], v[208:211], v[74:77], v[18:21]
	v_mfma_f32_16x16x32_bf16 v[62:65], v[212:215], v[74:77], v[62:65]
	ds_read_b128 v[74:77], v255 offset:4096
	s_waitcnt lgkmcnt(7)
	v_mfma_f32_16x16x32_bf16 v[58:61], v[82:85], v[78:81], v[58:61]
	v_mfma_f32_16x16x32_bf16 v[54:57], v[86:89], v[78:81], v[54:57]
	v_mfma_f32_16x16x32_bf16 v[50:53], v[208:211], v[78:81], v[50:53]
	v_mfma_f32_16x16x32_bf16 v[2:5], v[212:215], v[78:81], v[2:5]
	ds_read_b128 v[78:81], v255 offset:6144
	s_waitcnt lgkmcnt(3)
	v_mfma_f32_16x16x32_bf16 v[6:9], v[216:219], v[66:69], v[6:9]
	v_mfma_f32_16x16x32_bf16 v[30:33], v[220:223], v[66:69], v[30:33]
	v_mfma_f32_16x16x32_bf16 v[38:41], v[224:227], v[66:69], v[38:41]
	v_mfma_f32_16x16x32_bf16 v[42:45], v[228:231], v[66:69], v[42:45]
	s_waitcnt lgkmcnt(2)
	v_mfma_f32_16x16x32_bf16 v[46:49], v[216:219], v[70:73], v[46:49]
	v_mfma_f32_16x16x32_bf16 v[26:29], v[220:223], v[70:73], v[26:29]
	v_mfma_f32_16x16x32_bf16 v[14:17], v[224:227], v[70:73], v[14:17]
	v_mfma_f32_16x16x32_bf16 v[10:13], v[228:231], v[70:73], v[10:13]
	s_waitcnt vmcnt(6)
	s_waitcnt lgkmcnt(0)
	s_barrier
	s_add_i32 m0, s67, 0x10000
	s_nop 0
	global_load_lds_dwordx4 v188, s[80:81]
	s_add_i32 m0, s67, 0x12000
	s_nop 0
	global_load_lds_dwordx4 v189, s[80:81]
	s_add_i32 m0, s67, 0x14000
	s_nop 0
	global_load_lds_dwordx4 v190, s[80:81]
	s_add_i32 m0, s67, 0x16000
	s_nop 0
	global_load_lds_dwordx4 v191, s[80:81]
	s_add_i32 m0, s67, 0x20400
	s_nop 0
	global_load_lds_dwordx4 v205, s[96:97]
	s_add_i32 m0, s67, 0x22400
	s_nop 0
	global_load_lds_dwordx4 v206, s[96:97]
	s_add_u32 s80, s80, 0x80
	s_addc_u32 s81, s81, 0
	s_add_u32 s96, s96, 0x80
	s_addc_u32 s97, s97, 0
	s_movk_i32 s10, 0x400
	s_mov_b32 s11, 0
	v_lshl_add_u64 v[248:249], v[128:129], 0, s[10:11]
	global_load_dwordx2 v[232:233], v[248:249], off
	global_load_dwordx2 v[234:235], v[248:249], off offset:32
	v_lshl_add_u64 v[248:249], v[132:133], 0, s[10:11]
	global_load_dwordx2 v[236:237], v[248:249], off
	global_load_dwordx2 v[238:239], v[248:249], off offset:32
	v_lshl_add_u64 v[248:249], v[152:153], 0, s[10:11]
	global_load_dwordx2 v[240:241], v[248:249], off
	global_load_dwordx2 v[242:243], v[248:249], off offset:32
	v_lshl_add_u64 v[248:249], v[154:155], 0, s[10:11]
	global_load_dwordx2 v[244:245], v[248:249], off
	global_load_dwordx2 v[246:247], v[248:249], off offset:32
	ds_read_b128 v[82:85], v90 offset:0
	ds_read_b128 v[86:89], v90 offset:2048
	ds_read_b128 v[208:211], v90 offset:4096
	ds_read_b128 v[212:215], v90 offset:6144
	ds_read_b128 v[66:69], v207 offset:0
	ds_read_b128 v[70:73], v207 offset:2048
	v_mfma_f32_16x16x32_bf16 v[34:37], v[216:219], v[74:77], v[34:37]
	v_mfma_f32_16x16x32_bf16 v[22:25], v[220:223], v[74:77], v[22:25]
	v_mfma_f32_16x16x32_bf16 v[18:21], v[224:227], v[74:77], v[18:21]
	v_mfma_f32_16x16x32_bf16 v[62:65], v[228:231], v[74:77], v[62:65]
	ds_read_b128 v[74:77], v207 offset:4096
	v_mfma_f32_16x16x32_bf16 v[58:61], v[216:219], v[78:81], v[58:61]
	v_mfma_f32_16x16x32_bf16 v[54:57], v[220:223], v[78:81], v[54:57]
	v_mfma_f32_16x16x32_bf16 v[50:53], v[224:227], v[78:81], v[50:53]
	v_mfma_f32_16x16x32_bf16 v[2:5], v[228:231], v[78:81], v[2:5]
	ds_read_b128 v[78:81], v207 offset:6144
	ds_read_b128 v[216:219], v91 offset:0
	ds_read_b128 v[220:223], v91 offset:2048
	ds_read_b128 v[224:227], v91 offset:4096
	ds_read_b128 v[228:231], v91 offset:6144
	s_waitcnt lgkmcnt(7)
	v_mfma_f32_16x16x32_bf16 v[6:9], v[82:85], v[66:69], v[6:9]
	v_mfma_f32_16x16x32_bf16 v[30:33], v[86:89], v[66:69], v[30:33]
	v_mfma_f32_16x16x32_bf16 v[38:41], v[208:211], v[66:69], v[38:41]
	v_mfma_f32_16x16x32_bf16 v[42:45], v[212:215], v[66:69], v[42:45]
	ds_read_b128 v[66:69], v119 offset:0
	s_waitcnt lgkmcnt(7)
	v_mfma_f32_16x16x32_bf16 v[46:49], v[82:85], v[70:73], v[46:49]
	v_mfma_f32_16x16x32_bf16 v[26:29], v[86:89], v[70:73], v[26:29]
	v_mfma_f32_16x16x32_bf16 v[14:17], v[208:211], v[70:73], v[14:17]
	v_mfma_f32_16x16x32_bf16 v[10:13], v[212:215], v[70:73], v[10:13]
	ds_read_b128 v[70:73], v119 offset:2048
	s_waitcnt lgkmcnt(7)
	v_mfma_f32_16x16x32_bf16 v[34:37], v[82:85], v[74:77], v[34:37]
	v_mfma_f32_16x16x32_bf16 v[22:25], v[86:89], v[74:77], v[22:25]
	v_mfma_f32_16x16x32_bf16 v[18:21], v[208:211], v[74:77], v[18:21]
	v_mfma_f32_16x16x32_bf16 v[62:65], v[212:215], v[74:77], v[62:65]
	ds_read_b128 v[74:77], v119 offset:4096
	s_waitcnt lgkmcnt(7)
	v_mfma_f32_16x16x32_bf16 v[58:61], v[82:85], v[78:81], v[58:61]
	v_mfma_f32_16x16x32_bf16 v[54:57], v[86:89], v[78:81], v[54:57]
	v_mfma_f32_16x16x32_bf16 v[50:53], v[208:211], v[78:81], v[50:53]
	v_mfma_f32_16x16x32_bf16 v[2:5], v[212:215], v[78:81], v[2:5]
	ds_read_b128 v[78:81], v119 offset:6144
	s_waitcnt lgkmcnt(3)
	v_mfma_f32_16x16x32_bf16 v[6:9], v[216:219], v[66:69], v[6:9]
	v_mfma_f32_16x16x32_bf16 v[30:33], v[220:223], v[66:69], v[30:33]
	v_mfma_f32_16x16x32_bf16 v[38:41], v[224:227], v[66:69], v[38:41]
	v_mfma_f32_16x16x32_bf16 v[42:45], v[228:231], v[66:69], v[42:45]
	s_waitcnt lgkmcnt(2)
	v_mfma_f32_16x16x32_bf16 v[46:49], v[216:219], v[70:73], v[46:49]
	v_mfma_f32_16x16x32_bf16 v[26:29], v[220:223], v[70:73], v[26:29]
	v_mfma_f32_16x16x32_bf16 v[14:17], v[224:227], v[70:73], v[14:17]
	v_mfma_f32_16x16x32_bf16 v[10:13], v[228:231], v[70:73], v[10:13]
	s_waitcnt vmcnt(14)
	s_waitcnt lgkmcnt(0)
	s_barrier
	s_add_i32 m0, s67, 0x0
	s_nop 0
	global_load_lds_dwordx4 v188, s[80:81]
	s_add_i32 m0, s67, 0x2000
	s_nop 0
	global_load_lds_dwordx4 v189, s[80:81]
	s_add_i32 m0, s67, 0x4000
	s_nop 0
	global_load_lds_dwordx4 v190, s[80:81]
	s_add_i32 m0, s67, 0x6000
	s_nop 0
	global_load_lds_dwordx4 v191, s[80:81]
	s_add_i32 m0, s67, 0x18000
	s_nop 0
	global_load_lds_dwordx4 v205, s[96:97]
	s_add_i32 m0, s67, 0x1a000
	s_nop 0
	global_load_lds_dwordx4 v206, s[96:97]
	s_add_u32 s80, s80, 0x280
	s_addc_u32 s81, s81, 0
	s_add_u32 s96, s96, 0xffc80
	s_addc_u32 s97, s97, 0
	ds_read_b128 v[82:85], v90 offset:16384
	ds_read_b128 v[86:89], v90 offset:18432
	ds_read_b128 v[208:211], v90 offset:20480
	ds_read_b128 v[212:215], v90 offset:22528
	ds_read_b128 v[66:69], v207 offset:32768
	ds_read_b128 v[70:73], v207 offset:34816
	v_mfma_f32_16x16x32_bf16 v[34:37], v[216:219], v[74:77], v[34:37]
	v_mfma_f32_16x16x32_bf16 v[22:25], v[220:223], v[74:77], v[22:25]
	v_mfma_f32_16x16x32_bf16 v[18:21], v[224:227], v[74:77], v[18:21]
	v_mfma_f32_16x16x32_bf16 v[62:65], v[228:231], v[74:77], v[62:65]
	ds_read_b128 v[74:77], v207 offset:36864
	v_mfma_f32_16x16x32_bf16 v[58:61], v[216:219], v[78:81], v[58:61]
	v_mfma_f32_16x16x32_bf16 v[54:57], v[220:223], v[78:81], v[54:57]
	v_mfma_f32_16x16x32_bf16 v[50:53], v[224:227], v[78:81], v[50:53]
	v_mfma_f32_16x16x32_bf16 v[2:5], v[228:231], v[78:81], v[2:5]
	ds_read_b128 v[78:81], v207 offset:38912
	ds_read_b128 v[216:219], v91 offset:16384
	ds_read_b128 v[220:223], v91 offset:18432
	ds_read_b128 v[224:227], v91 offset:20480
	ds_read_b128 v[228:231], v91 offset:22528
	s_waitcnt lgkmcnt(7)
	v_mfma_f32_16x16x32_bf16 v[6:9], v[82:85], v[66:69], v[6:9]
	v_mfma_f32_16x16x32_bf16 v[30:33], v[86:89], v[66:69], v[30:33]
	v_mfma_f32_16x16x32_bf16 v[38:41], v[208:211], v[66:69], v[38:41]
	v_mfma_f32_16x16x32_bf16 v[42:45], v[212:215], v[66:69], v[42:45]
	ds_read_b128 v[66:69], v119 offset:32768
	s_waitcnt lgkmcnt(7)
	v_mfma_f32_16x16x32_bf16 v[46:49], v[82:85], v[70:73], v[46:49]
	v_mfma_f32_16x16x32_bf16 v[26:29], v[86:89], v[70:73], v[26:29]
	v_mfma_f32_16x16x32_bf16 v[14:17], v[208:211], v[70:73], v[14:17]
	v_mfma_f32_16x16x32_bf16 v[10:13], v[212:215], v[70:73], v[10:13]
	ds_read_b128 v[70:73], v119 offset:34816
	s_waitcnt lgkmcnt(7)
	v_mfma_f32_16x16x32_bf16 v[34:37], v[82:85], v[74:77], v[34:37]
	v_mfma_f32_16x16x32_bf16 v[22:25], v[86:89], v[74:77], v[22:25]
	v_mfma_f32_16x16x32_bf16 v[18:21], v[208:211], v[74:77], v[18:21]
	v_mfma_f32_16x16x32_bf16 v[62:65], v[212:215], v[74:77], v[62:65]
	ds_read_b128 v[74:77], v119 offset:36864
	s_waitcnt lgkmcnt(7)
	v_mfma_f32_16x16x32_bf16 v[58:61], v[82:85], v[78:81], v[58:61]
	v_mfma_f32_16x16x32_bf16 v[54:57], v[86:89], v[78:81], v[54:57]
	v_mfma_f32_16x16x32_bf16 v[50:53], v[208:211], v[78:81], v[50:53]
	v_mfma_f32_16x16x32_bf16 v[2:5], v[212:215], v[78:81], v[2:5]
	ds_read_b128 v[78:81], v119 offset:38912
	s_waitcnt lgkmcnt(3)
	v_mfma_f32_16x16x32_bf16 v[6:9], v[216:219], v[66:69], v[6:9]
	v_mfma_f32_16x16x32_bf16 v[30:33], v[220:223], v[66:69], v[30:33]
	v_mfma_f32_16x16x32_bf16 v[38:41], v[224:227], v[66:69], v[38:41]
	v_mfma_f32_16x16x32_bf16 v[42:45], v[228:231], v[66:69], v[42:45]
	s_waitcnt lgkmcnt(2)
	v_mfma_f32_16x16x32_bf16 v[46:49], v[216:219], v[70:73], v[46:49]
	v_mfma_f32_16x16x32_bf16 v[26:29], v[220:223], v[70:73], v[26:29]
	v_mfma_f32_16x16x32_bf16 v[14:17], v[224:227], v[70:73], v[14:17]
	v_mfma_f32_16x16x32_bf16 v[10:13], v[228:231], v[70:73], v[10:13]
	s_waitcnt vmcnt(14)
	s_waitcnt lgkmcnt(0)
	s_barrier
	s_add_i32 m0, s67, 0x8000
	s_nop 0
	global_load_lds_dwordx4 v188, s[80:81]
	s_add_i32 m0, s67, 0xa000
	s_nop 0
	global_load_lds_dwordx4 v189, s[80:81]
	s_add_i32 m0, s67, 0xc000
	s_nop 0
	global_load_lds_dwordx4 v190, s[80:81]
	s_add_i32 m0, s67, 0xe000
	s_nop 0
	global_load_lds_dwordx4 v191, s[80:81]
	s_add_i32 m0, s67, 0x1c000
	s_nop 0
	global_load_lds_dwordx4 v205, s[96:97]
	s_add_i32 m0, s67, 0x1e000
	s_nop 0
	global_load_lds_dwordx4 v206, s[96:97]
	s_add_u32 s80, s80, 0x80
	s_addc_u32 s81, s81, 0
	s_add_u32 s96, s96, 0x80
	s_addc_u32 s97, s97, 0
	ds_read_b128 v[82:85], v90 offset:33792
	ds_read_b128 v[86:89], v90 offset:35840
	ds_read_b128 v[208:211], v90 offset:37888
	ds_read_b128 v[212:215], v90 offset:39936
	ds_read_b128 v[66:69], v0 offset:0
	ds_read_b128 v[70:73], v0 offset:2048
	v_mfma_f32_16x16x32_bf16 v[34:37], v[216:219], v[74:77], v[34:37]
	v_mfma_f32_16x16x32_bf16 v[22:25], v[220:223], v[74:77], v[22:25]
	v_mfma_f32_16x16x32_bf16 v[18:21], v[224:227], v[74:77], v[18:21]
	v_mfma_f32_16x16x32_bf16 v[62:65], v[228:231], v[74:77], v[62:65]
	ds_read_b128 v[74:77], v0 offset:4096
	v_mfma_f32_16x16x32_bf16 v[58:61], v[216:219], v[78:81], v[58:61]
	v_mfma_f32_16x16x32_bf16 v[54:57], v[220:223], v[78:81], v[54:57]
	v_mfma_f32_16x16x32_bf16 v[50:53], v[224:227], v[78:81], v[50:53]
	v_mfma_f32_16x16x32_bf16 v[2:5], v[228:231], v[78:81], v[2:5]
	ds_read_b128 v[78:81], v0 offset:6144
	ds_read_b128 v[216:219], v91 offset:33792
	ds_read_b128 v[220:223], v91 offset:35840
	ds_read_b128 v[224:227], v91 offset:37888
	ds_read_b128 v[228:231], v91 offset:39936
	s_waitcnt lgkmcnt(7)
	v_mfma_f32_16x16x32_bf16 v[6:9], v[82:85], v[66:69], v[6:9]
	v_mfma_f32_16x16x32_bf16 v[30:33], v[86:89], v[66:69], v[30:33]
	v_mfma_f32_16x16x32_bf16 v[38:41], v[208:211], v[66:69], v[38:41]
	v_mfma_f32_16x16x32_bf16 v[42:45], v[212:215], v[66:69], v[42:45]
	ds_read_b128 v[66:69], v255 offset:0
	s_waitcnt lgkmcnt(7)
	v_mfma_f32_16x16x32_bf16 v[46:49], v[82:85], v[70:73], v[46:49]
	v_mfma_f32_16x16x32_bf16 v[26:29], v[86:89], v[70:73], v[26:29]
	v_mfma_f32_16x16x32_bf16 v[14:17], v[208:211], v[70:73], v[14:17]
	v_mfma_f32_16x16x32_bf16 v[10:13], v[212:215], v[70:73], v[10:13]
	ds_read_b128 v[70:73], v255 offset:2048
	s_waitcnt lgkmcnt(7)
	v_mfma_f32_16x16x32_bf16 v[34:37], v[82:85], v[74:77], v[34:37]
	v_mfma_f32_16x16x32_bf16 v[22:25], v[86:89], v[74:77], v[22:25]
	v_mfma_f32_16x16x32_bf16 v[18:21], v[208:211], v[74:77], v[18:21]
	v_mfma_f32_16x16x32_bf16 v[62:65], v[212:215], v[74:77], v[62:65]
	ds_read_b128 v[74:77], v255 offset:4096
	s_waitcnt lgkmcnt(7)
	v_mfma_f32_16x16x32_bf16 v[58:61], v[82:85], v[78:81], v[58:61]
	v_mfma_f32_16x16x32_bf16 v[54:57], v[86:89], v[78:81], v[54:57]
	v_mfma_f32_16x16x32_bf16 v[50:53], v[208:211], v[78:81], v[50:53]
	v_mfma_f32_16x16x32_bf16 v[2:5], v[212:215], v[78:81], v[2:5]
	ds_read_b128 v[78:81], v255 offset:6144
	s_waitcnt lgkmcnt(3)
	v_mfma_f32_16x16x32_bf16 v[6:9], v[216:219], v[66:69], v[6:9]
	v_mfma_f32_16x16x32_bf16 v[30:33], v[220:223], v[66:69], v[30:33]
	v_mfma_f32_16x16x32_bf16 v[38:41], v[224:227], v[66:69], v[38:41]
	v_mfma_f32_16x16x32_bf16 v[42:45], v[228:231], v[66:69], v[42:45]
	s_waitcnt lgkmcnt(2)
	v_mfma_f32_16x16x32_bf16 v[46:49], v[216:219], v[70:73], v[46:49]
	v_mfma_f32_16x16x32_bf16 v[26:29], v[220:223], v[70:73], v[26:29]
	v_mfma_f32_16x16x32_bf16 v[14:17], v[224:227], v[70:73], v[14:17]
	v_mfma_f32_16x16x32_bf16 v[10:13], v[228:231], v[70:73], v[10:13]
	s_waitcnt vmcnt(6)
	s_waitcnt lgkmcnt(0)
	s_barrier
	s_add_i32 m0, s67, 0x10000
	s_nop 0
	global_load_lds_dwordx4 v188, s[80:81]
	s_add_i32 m0, s67, 0x12000
	s_nop 0
	global_load_lds_dwordx4 v189, s[80:81]
	s_add_i32 m0, s67, 0x14000
	s_nop 0
	global_load_lds_dwordx4 v190, s[80:81]
	s_add_i32 m0, s67, 0x16000
	s_nop 0
	global_load_lds_dwordx4 v191, s[80:81]
	s_add_i32 m0, s67, 0x20400
	s_nop 0
	global_load_lds_dwordx4 v205, s[96:97]
	s_add_i32 m0, s67, 0x22400
	s_nop 0
	global_load_lds_dwordx4 v206, s[96:97]
	s_add_u32 s80, s80, 0x80
	s_addc_u32 s81, s81, 0
	s_add_u32 s96, s96, 0x80
	s_addc_u32 s97, s97, 0
	ds_read_b128 v[82:85], v90 offset:0
	ds_read_b128 v[86:89], v90 offset:2048
	ds_read_b128 v[208:211], v90 offset:4096
	ds_read_b128 v[212:215], v90 offset:6144
	ds_read_b128 v[66:69], v207 offset:0
	ds_read_b128 v[70:73], v207 offset:2048
	v_mfma_f32_16x16x32_bf16 v[34:37], v[216:219], v[74:77], v[34:37]
	v_mfma_f32_16x16x32_bf16 v[22:25], v[220:223], v[74:77], v[22:25]
	v_mfma_f32_16x16x32_bf16 v[18:21], v[224:227], v[74:77], v[18:21]
	v_mfma_f32_16x16x32_bf16 v[62:65], v[228:231], v[74:77], v[62:65]
	ds_read_b128 v[74:77], v207 offset:4096
	v_mfma_f32_16x16x32_bf16 v[58:61], v[216:219], v[78:81], v[58:61]
	v_mfma_f32_16x16x32_bf16 v[54:57], v[220:223], v[78:81], v[54:57]
	v_mfma_f32_16x16x32_bf16 v[50:53], v[224:227], v[78:81], v[50:53]
	v_mfma_f32_16x16x32_bf16 v[2:5], v[228:231], v[78:81], v[2:5]
	ds_read_b128 v[78:81], v207 offset:6144
	ds_read_b128 v[216:219], v91 offset:0
	ds_read_b128 v[220:223], v91 offset:2048
	ds_read_b128 v[224:227], v91 offset:4096
	ds_read_b128 v[228:231], v91 offset:6144
	s_waitcnt lgkmcnt(7)
	v_mfma_f32_16x16x32_bf16 v[6:9], v[82:85], v[66:69], v[6:9]
	v_mfma_f32_16x16x32_bf16 v[30:33], v[86:89], v[66:69], v[30:33]
	v_mfma_f32_16x16x32_bf16 v[38:41], v[208:211], v[66:69], v[38:41]
	v_mfma_f32_16x16x32_bf16 v[42:45], v[212:215], v[66:69], v[42:45]
	ds_read_b128 v[66:69], v119 offset:0
	s_waitcnt lgkmcnt(7)
	v_mfma_f32_16x16x32_bf16 v[46:49], v[82:85], v[70:73], v[46:49]
	v_mfma_f32_16x16x32_bf16 v[26:29], v[86:89], v[70:73], v[26:29]
	v_mfma_f32_16x16x32_bf16 v[14:17], v[208:211], v[70:73], v[14:17]
	v_mfma_f32_16x16x32_bf16 v[10:13], v[212:215], v[70:73], v[10:13]
	ds_read_b128 v[70:73], v119 offset:2048
	s_waitcnt lgkmcnt(7)
	v_mfma_f32_16x16x32_bf16 v[34:37], v[82:85], v[74:77], v[34:37]
	v_mfma_f32_16x16x32_bf16 v[22:25], v[86:89], v[74:77], v[22:25]
	v_mfma_f32_16x16x32_bf16 v[18:21], v[208:211], v[74:77], v[18:21]
	v_mfma_f32_16x16x32_bf16 v[62:65], v[212:215], v[74:77], v[62:65]
	ds_read_b128 v[74:77], v119 offset:4096
	s_waitcnt lgkmcnt(7)
	v_mfma_f32_16x16x32_bf16 v[58:61], v[82:85], v[78:81], v[58:61]
	v_mfma_f32_16x16x32_bf16 v[54:57], v[86:89], v[78:81], v[54:57]
	v_mfma_f32_16x16x32_bf16 v[50:53], v[208:211], v[78:81], v[50:53]
	v_mfma_f32_16x16x32_bf16 v[2:5], v[212:215], v[78:81], v[2:5]
	ds_read_b128 v[78:81], v119 offset:6144
	s_waitcnt lgkmcnt(3)
	v_mfma_f32_16x16x32_bf16 v[6:9], v[216:219], v[66:69], v[6:9]
	s_waitcnt vmcnt(18)
	v_mfma_f32_16x16x32_bf16 v[30:33], v[220:223], v[66:69], v[30:33]
	v_mfma_f32_16x16x32_bf16 v[38:41], v[224:227], v[66:69], v[38:41]
	v_mfma_f32_16x16x32_bf16 v[42:45], v[228:231], v[66:69], v[42:45]
	v_cvt_f32_ubyte0_e32 v248, v232
	v_cvt_f32_ubyte1_e32 v249, v232
	v_cvt_f32_ubyte2_e32 v250, v232
	v_cvt_f32_ubyte3_e32 v251, v232
	v_mul_f32_e32 v248, s34, v248
	v_mul_f32_e32 v249, s34, v249
	v_mul_f32_e32 v250, s34, v250
	v_mul_f32_e32 v251, s34, v251
	v_fma_f32 v184, v6, v248, v184
	v_fma_f32 v185, v7, v249, v185
	v_fma_f32 v186, v8, v250, v186
	v_fma_f32 v187, v9, v251, v187
	s_waitcnt lgkmcnt(2)
	v_mfma_f32_16x16x32_bf16 v[46:49], v[216:219], v[70:73], v[46:49]
	v_cvt_f32_ubyte0_e32 v248, v233
	v_cvt_f32_ubyte1_e32 v249, v233
	v_cvt_f32_ubyte2_e32 v250, v233
	v_cvt_f32_ubyte3_e32 v251, v233
	v_mul_f32_e32 v248, s34, v248
	v_mul_f32_e32 v249, s34, v249
	v_mul_f32_e32 v250, s34, v250
	v_mul_f32_e32 v251, s34, v251
	v_fma_f32 v180, v30, v248, v180
	v_fma_f32 v181, v31, v249, v181
	v_fma_f32 v182, v32, v250, v182
	v_fma_f32 v183, v33, v251, v183
	v_mfma_f32_16x16x32_bf16 v[26:29], v[220:223], v[70:73], v[26:29]
	v_cvt_f32_ubyte0_e32 v248, v234
	v_cvt_f32_ubyte1_e32 v249, v234
	v_cvt_f32_ubyte2_e32 v250, v234
	v_cvt_f32_ubyte3_e32 v251, v234
	v_mul_f32_e32 v248, s34, v248
	v_mul_f32_e32 v249, s34, v249
	v_mul_f32_e32 v250, s34, v250
	v_mul_f32_e32 v251, s34, v251
	v_fma_f32 v176, v38, v248, v176
	v_fma_f32 v177, v39, v249, v177
	v_fma_f32 v178, v40, v250, v178
	v_fma_f32 v179, v41, v251, v179
	v_mfma_f32_16x16x32_bf16 v[14:17], v[224:227], v[70:73], v[14:17]
	v_cvt_f32_ubyte0_e32 v248, v235
	v_cvt_f32_ubyte1_e32 v249, v235
	v_cvt_f32_ubyte2_e32 v250, v235
	v_cvt_f32_ubyte3_e32 v251, v235
	v_mul_f32_e32 v248, s34, v248
	v_mul_f32_e32 v249, s34, v249
	v_mul_f32_e32 v250, s34, v250
	v_mul_f32_e32 v251, s34, v251
	v_fma_f32 v172, v42, v248, v172
	v_fma_f32 v173, v43, v249, v173
	v_fma_f32 v174, v44, v250, v174
	v_fma_f32 v175, v45, v251, v175
	v_mfma_f32_16x16x32_bf16 v[10:13], v[228:231], v[70:73], v[10:13]
	v_cvt_f32_ubyte0_e32 v248, v236
	v_cvt_f32_ubyte1_e32 v249, v236
	v_cvt_f32_ubyte2_e32 v250, v236
	v_cvt_f32_ubyte3_e32 v251, v236
	v_mul_f32_e32 v248, s34, v248
	v_mul_f32_e32 v249, s34, v249
	v_mul_f32_e32 v250, s34, v250
	v_mul_f32_e32 v251, s34, v251
	v_fma_f32 v168, v46, v248, v168
	v_fma_f32 v169, v47, v249, v169
	v_fma_f32 v170, v48, v250, v170
	v_fma_f32 v171, v49, v251, v171
	s_waitcnt vmcnt(6)
	s_waitcnt lgkmcnt(0)
	s_barrier
	s_add_i32 m0, s67, 0x0
	s_nop 0
	global_load_lds_dwordx4 v188, s[80:81]
	s_add_i32 m0, s67, 0x2000
	s_nop 0
	global_load_lds_dwordx4 v189, s[80:81]
	s_add_i32 m0, s67, 0x4000
	s_nop 0
	global_load_lds_dwordx4 v190, s[80:81]
	s_add_i32 m0, s67, 0x6000
	s_nop 0
	global_load_lds_dwordx4 v191, s[80:81]
	s_add_i32 m0, s67, 0x18000
	s_nop 0
	global_load_lds_dwordx4 v205, s[96:97]
	s_add_i32 m0, s67, 0x1a000
	s_nop 0
	global_load_lds_dwordx4 v206, s[96:97]
	s_add_u32 s80, s80, 0x80
	s_addc_u32 s81, s81, 0
	s_add_u32 s96, s96, 0x80
	s_addc_u32 s97, s97, 0
	ds_read_b128 v[82:85], v90 offset:16384
	ds_read_b128 v[86:89], v90 offset:18432
	ds_read_b128 v[208:211], v90 offset:20480
	ds_read_b128 v[212:215], v90 offset:22528
	ds_read_b128 v[66:69], v207 offset:32768
	ds_read_b128 v[70:73], v207 offset:34816
	v_mfma_f32_16x16x32_bf16 v[34:37], v[216:219], v[74:77], v[34:37]
	v_cvt_f32_ubyte0_e32 v248, v237
	v_cvt_f32_ubyte1_e32 v249, v237
	v_cvt_f32_ubyte2_e32 v250, v237
	v_cvt_f32_ubyte3_e32 v251, v237
	v_mul_f32_e32 v248, s34, v248
	v_mul_f32_e32 v249, s34, v249
	v_mul_f32_e32 v250, s34, v250
	v_mul_f32_e32 v251, s34, v251
	v_fma_f32 v164, v26, v248, v164
	v_fma_f32 v165, v27, v249, v165
	v_fma_f32 v166, v28, v250, v166
	v_fma_f32 v167, v29, v251, v167
	v_mfma_f32_16x16x32_bf16 v[22:25], v[220:223], v[74:77], v[22:25]
	v_cvt_f32_ubyte0_e32 v248, v238
	v_cvt_f32_ubyte1_e32 v249, v238
	v_cvt_f32_ubyte2_e32 v250, v238
	v_cvt_f32_ubyte3_e32 v251, v238
	v_mul_f32_e32 v248, s34, v248
	v_mul_f32_e32 v249, s34, v249
	v_mul_f32_e32 v250, s34, v250
	v_mul_f32_e32 v251, s34, v251
	v_fma_f32 v160, v14, v248, v160
	v_fma_f32 v161, v15, v249, v161
	v_fma_f32 v162, v16, v250, v162
	v_fma_f32 v163, v17, v251, v163
	v_mfma_f32_16x16x32_bf16 v[18:21], v[224:227], v[74:77], v[18:21]
	v_cvt_f32_ubyte0_e32 v248, v239
	v_cvt_f32_ubyte1_e32 v249, v239
	v_cvt_f32_ubyte2_e32 v250, v239
	v_cvt_f32_ubyte3_e32 v251, v239
	v_mul_f32_e32 v248, s34, v248
	v_mul_f32_e32 v249, s34, v249
	v_mul_f32_e32 v250, s34, v250
	v_mul_f32_e32 v251, s34, v251
	v_fma_f32 v156, v10, v248, v156
	v_fma_f32 v157, v11, v249, v157
	v_fma_f32 v158, v12, v250, v158
	v_fma_f32 v159, v13, v251, v159
	v_mfma_f32_16x16x32_bf16 v[62:65], v[228:231], v[74:77], v[62:65]
	v_cvt_f32_ubyte0_e32 v248, v240
	v_cvt_f32_ubyte1_e32 v249, v240
	v_cvt_f32_ubyte2_e32 v250, v240
	v_cvt_f32_ubyte3_e32 v251, v240
	v_mul_f32_e32 v248, s34, v248
	v_mul_f32_e32 v249, s34, v249
	v_mul_f32_e32 v250, s34, v250
	v_mul_f32_e32 v251, s34, v251
	v_fma_f32 v136, v34, v248, v136
	v_fma_f32 v137, v35, v249, v137
	v_fma_f32 v150, v36, v250, v150
	v_fma_f32 v151, v37, v251, v151
	ds_read_b128 v[74:77], v207 offset:36864
	v_mfma_f32_16x16x32_bf16 v[58:61], v[216:219], v[78:81], v[58:61]
	v_cvt_f32_ubyte0_e32 v248, v241
	v_cvt_f32_ubyte1_e32 v249, v241
	v_cvt_f32_ubyte2_e32 v250, v241
	v_cvt_f32_ubyte3_e32 v251, v241
	v_mul_f32_e32 v248, s34, v248
	v_mul_f32_e32 v249, s34, v249
	v_mul_f32_e32 v250, s34, v250
	v_mul_f32_e32 v251, s34, v251
	v_fma_f32 v130, v22, v248, v130
	v_fma_f32 v131, v23, v249, v131
	v_fma_f32 v134, v24, v250, v134
	v_fma_f32 v135, v25, v251, v135
	v_mfma_f32_16x16x32_bf16 v[54:57], v[220:223], v[78:81], v[54:57]
	v_cvt_f32_ubyte0_e32 v248, v242
	v_cvt_f32_ubyte1_e32 v249, v242
	v_cvt_f32_ubyte2_e32 v250, v242
	v_cvt_f32_ubyte3_e32 v251, v242
	v_mul_f32_e32 v248, s34, v248
	v_mul_f32_e32 v249, s34, v249
	v_mul_f32_e32 v250, s34, v250
	v_mul_f32_e32 v251, s34, v251
	v_fma_f32 v124, v18, v248, v124
	v_fma_f32 v125, v19, v249, v125
	v_fma_f32 v126, v20, v250, v126
	v_fma_f32 v127, v21, v251, v127
	v_mfma_f32_16x16x32_bf16 v[50:53], v[224:227], v[78:81], v[50:53]
	v_cvt_f32_ubyte0_e32 v248, v243
	v_cvt_f32_ubyte1_e32 v249, v243
	v_cvt_f32_ubyte2_e32 v250, v243
	v_cvt_f32_ubyte3_e32 v251, v243
	v_mul_f32_e32 v248, s34, v248
	v_mul_f32_e32 v249, s34, v249
	v_mul_f32_e32 v250, s34, v250
	v_mul_f32_e32 v251, s34, v251
	v_fma_f32 v120, v62, v248, v120
	v_fma_f32 v121, v63, v249, v121
	v_fma_f32 v122, v64, v250, v122
	v_fma_f32 v123, v65, v251, v123
	v_mfma_f32_16x16x32_bf16 v[2:5], v[228:231], v[78:81], v[2:5]
	v_cvt_f32_ubyte0_e32 v248, v244
	v_cvt_f32_ubyte1_e32 v249, v244
	v_cvt_f32_ubyte2_e32 v250, v244
	v_cvt_f32_ubyte3_e32 v251, v244
	v_mul_f32_e32 v248, s34, v248
	v_mul_f32_e32 v249, s34, v249
	v_mul_f32_e32 v250, s34, v250
	v_mul_f32_e32 v251, s34, v251
	v_fma_f32 v114, v58, v248, v114
	v_fma_f32 v115, v59, v249, v115
	v_fma_f32 v116, v60, v250, v116
	v_fma_f32 v117, v61, v251, v117
	ds_read_b128 v[78:81], v207 offset:38912
	s_nop 7
	s_nop 3
	v_cvt_f32_ubyte0_e32 v248, v245
	v_cvt_f32_ubyte1_e32 v249, v245
	v_cvt_f32_ubyte2_e32 v250, v245
	v_cvt_f32_ubyte3_e32 v251, v245
	v_mul_f32_e32 v248, s34, v248
	v_mul_f32_e32 v249, s34, v249
	v_mul_f32_e32 v250, s34, v250
	v_mul_f32_e32 v251, s34, v251
	v_fma_f32 v106, v54, v248, v106
	v_fma_f32 v107, v55, v249, v107
	v_fma_f32 v108, v56, v250, v108
	v_fma_f32 v109, v57, v251, v109
	v_cvt_f32_ubyte0_e32 v248, v246
	v_cvt_f32_ubyte1_e32 v249, v246
	v_cvt_f32_ubyte2_e32 v250, v246
	v_cvt_f32_ubyte3_e32 v251, v246
	v_mul_f32_e32 v248, s34, v248
	v_mul_f32_e32 v249, s34, v249
	v_mul_f32_e32 v250, s34, v250
	v_mul_f32_e32 v251, s34, v251
	v_fma_f32 v100, v50, v248, v100
	v_fma_f32 v101, v51, v249, v101
	v_fma_f32 v102, v52, v250, v102
	v_fma_f32 v103, v53, v251, v103
	v_cvt_f32_ubyte0_e32 v248, v247
	v_cvt_f32_ubyte1_e32 v249, v247
	v_cvt_f32_ubyte2_e32 v250, v247
	v_cvt_f32_ubyte3_e32 v251, v247
	v_mul_f32_e32 v248, s34, v248
	v_mul_f32_e32 v249, s34, v249
	v_mul_f32_e32 v250, s34, v250
	v_mul_f32_e32 v251, s34, v251
	v_fma_f32 v96, v2, v248, v96
	v_fma_f32 v97, v3, v249, v97
	v_fma_f32 v98, v4, v250, v98
	v_fma_f32 v99, v5, v251, v99
	s_add_u32 s98, s86, 0x2200
	s_addc_u32 s99, s87, 0
	global_load_dword v92, v93, s[98:99]
	ds_read_b128 v[216:219], v91 offset:16384
	ds_read_b128 v[220:223], v91 offset:18432
	ds_read_b128 v[224:227], v91 offset:20480
	ds_read_b128 v[228:231], v91 offset:22528
	s_waitcnt lgkmcnt(7)
	v_mfma_f32_16x16x32_bf16 v[6:9], v[82:85], v[66:69], 0
	v_mfma_f32_16x16x32_bf16 v[30:33], v[86:89], v[66:69], 0
	v_mfma_f32_16x16x32_bf16 v[38:41], v[208:211], v[66:69], 0
	v_mfma_f32_16x16x32_bf16 v[42:45], v[212:215], v[66:69], 0
	ds_read_b128 v[66:69], v119 offset:32768
	s_waitcnt lgkmcnt(7)
	v_mfma_f32_16x16x32_bf16 v[46:49], v[82:85], v[70:73], 0
	v_mfma_f32_16x16x32_bf16 v[26:29], v[86:89], v[70:73], 0
	v_mfma_f32_16x16x32_bf16 v[14:17], v[208:211], v[70:73], 0
	v_mfma_f32_16x16x32_bf16 v[10:13], v[212:215], v[70:73], 0
	ds_read_b128 v[70:73], v119 offset:34816
	s_waitcnt lgkmcnt(7)
	v_mfma_f32_16x16x32_bf16 v[34:37], v[82:85], v[74:77], 0
	v_mfma_f32_16x16x32_bf16 v[22:25], v[86:89], v[74:77], 0
	v_mfma_f32_16x16x32_bf16 v[18:21], v[208:211], v[74:77], 0
	v_mfma_f32_16x16x32_bf16 v[62:65], v[212:215], v[74:77], 0
	ds_read_b128 v[74:77], v119 offset:36864
	s_waitcnt lgkmcnt(7)
	v_mfma_f32_16x16x32_bf16 v[58:61], v[82:85], v[78:81], 0
	v_mfma_f32_16x16x32_bf16 v[54:57], v[86:89], v[78:81], 0
	v_mfma_f32_16x16x32_bf16 v[50:53], v[208:211], v[78:81], 0
	v_mfma_f32_16x16x32_bf16 v[2:5], v[212:215], v[78:81], 0
	ds_read_b128 v[78:81], v119 offset:38912
	s_waitcnt lgkmcnt(3)
	v_mfma_f32_16x16x32_bf16 v[6:9], v[216:219], v[66:69], v[6:9]
	v_mfma_f32_16x16x32_bf16 v[30:33], v[220:223], v[66:69], v[30:33]
	v_mfma_f32_16x16x32_bf16 v[38:41], v[224:227], v[66:69], v[38:41]
	v_mfma_f32_16x16x32_bf16 v[42:45], v[228:231], v[66:69], v[42:45]
	s_waitcnt lgkmcnt(2)
	v_mfma_f32_16x16x32_bf16 v[46:49], v[216:219], v[70:73], v[46:49]
	v_mfma_f32_16x16x32_bf16 v[26:29], v[220:223], v[70:73], v[26:29]
	v_mfma_f32_16x16x32_bf16 v[14:17], v[224:227], v[70:73], v[14:17]
	v_mfma_f32_16x16x32_bf16 v[10:13], v[228:231], v[70:73], v[10:13]
	s_waitcnt vmcnt(7)
	s_waitcnt lgkmcnt(0)
	s_barrier
	s_add_i32 m0, s67, 0x8000
	s_nop 0
	global_load_lds_dwordx4 v188, s[80:81]
	s_add_i32 m0, s67, 0xa000
	s_nop 0
	global_load_lds_dwordx4 v189, s[80:81]
	s_add_i32 m0, s67, 0xc000
	s_nop 0
	global_load_lds_dwordx4 v190, s[80:81]
	s_add_i32 m0, s67, 0xe000
	s_nop 0
	global_load_lds_dwordx4 v191, s[80:81]
	s_add_i32 m0, s67, 0x1c000
	s_nop 0
	global_load_lds_dwordx4 v205, s[96:97]
	s_add_i32 m0, s67, 0x1e000
	s_nop 0
	global_load_lds_dwordx4 v206, s[96:97]
	s_add_u32 s80, s80, 0x80
	s_addc_u32 s81, s81, 0
	s_add_u32 s96, s96, 0x80
	s_addc_u32 s97, s97, 0
	ds_read_b128 v[82:85], v90 offset:33792
	ds_read_b128 v[86:89], v90 offset:35840
	ds_read_b128 v[208:211], v90 offset:37888
	ds_read_b128 v[212:215], v90 offset:39936
	ds_read_b128 v[66:69], v0 offset:0
	ds_read_b128 v[70:73], v0 offset:2048
	v_mfma_f32_16x16x32_bf16 v[34:37], v[216:219], v[74:77], v[34:37]
	v_mfma_f32_16x16x32_bf16 v[22:25], v[220:223], v[74:77], v[22:25]
	v_mfma_f32_16x16x32_bf16 v[18:21], v[224:227], v[74:77], v[18:21]
	v_mfma_f32_16x16x32_bf16 v[62:65], v[228:231], v[74:77], v[62:65]
	ds_read_b128 v[74:77], v0 offset:4096
	v_mfma_f32_16x16x32_bf16 v[58:61], v[216:219], v[78:81], v[58:61]
	v_mfma_f32_16x16x32_bf16 v[54:57], v[220:223], v[78:81], v[54:57]
	v_mfma_f32_16x16x32_bf16 v[50:53], v[224:227], v[78:81], v[50:53]
	v_mfma_f32_16x16x32_bf16 v[2:5], v[228:231], v[78:81], v[2:5]
	ds_read_b128 v[78:81], v0 offset:6144
	ds_read_b128 v[216:219], v91 offset:33792
	ds_read_b128 v[220:223], v91 offset:35840
	ds_read_b128 v[224:227], v91 offset:37888
	ds_read_b128 v[228:231], v91 offset:39936
	s_waitcnt lgkmcnt(7)
	v_mfma_f32_16x16x32_bf16 v[6:9], v[82:85], v[66:69], v[6:9]
	v_mfma_f32_16x16x32_bf16 v[30:33], v[86:89], v[66:69], v[30:33]
	v_mfma_f32_16x16x32_bf16 v[38:41], v[208:211], v[66:69], v[38:41]
	v_mfma_f32_16x16x32_bf16 v[42:45], v[212:215], v[66:69], v[42:45]
	ds_read_b128 v[66:69], v255 offset:0
	s_waitcnt lgkmcnt(7)
	v_mfma_f32_16x16x32_bf16 v[46:49], v[82:85], v[70:73], v[46:49]
	v_mfma_f32_16x16x32_bf16 v[26:29], v[86:89], v[70:73], v[26:29]
	v_mfma_f32_16x16x32_bf16 v[14:17], v[208:211], v[70:73], v[14:17]
	v_mfma_f32_16x16x32_bf16 v[10:13], v[212:215], v[70:73], v[10:13]
	ds_read_b128 v[70:73], v255 offset:2048
	s_waitcnt lgkmcnt(7)
	v_mfma_f32_16x16x32_bf16 v[34:37], v[82:85], v[74:77], v[34:37]
	v_mfma_f32_16x16x32_bf16 v[22:25], v[86:89], v[74:77], v[22:25]
	v_mfma_f32_16x16x32_bf16 v[18:21], v[208:211], v[74:77], v[18:21]
	v_mfma_f32_16x16x32_bf16 v[62:65], v[212:215], v[74:77], v[62:65]
	ds_read_b128 v[74:77], v255 offset:4096
	s_waitcnt lgkmcnt(7)
	v_mfma_f32_16x16x32_bf16 v[58:61], v[82:85], v[78:81], v[58:61]
	v_mfma_f32_16x16x32_bf16 v[54:57], v[86:89], v[78:81], v[54:57]
	v_mfma_f32_16x16x32_bf16 v[50:53], v[208:211], v[78:81], v[50:53]
	v_mfma_f32_16x16x32_bf16 v[2:5], v[212:215], v[78:81], v[2:5]
	ds_read_b128 v[78:81], v255 offset:6144
	s_waitcnt lgkmcnt(3)
	v_mfma_f32_16x16x32_bf16 v[6:9], v[216:219], v[66:69], v[6:9]
	v_mfma_f32_16x16x32_bf16 v[30:33], v[220:223], v[66:69], v[30:33]
	v_mfma_f32_16x16x32_bf16 v[38:41], v[224:227], v[66:69], v[38:41]
	v_mfma_f32_16x16x32_bf16 v[42:45], v[228:231], v[66:69], v[42:45]
	s_waitcnt lgkmcnt(2)
	v_mfma_f32_16x16x32_bf16 v[46:49], v[216:219], v[70:73], v[46:49]
	v_mfma_f32_16x16x32_bf16 v[26:29], v[220:223], v[70:73], v[26:29]
	v_mfma_f32_16x16x32_bf16 v[14:17], v[224:227], v[70:73], v[14:17]
	v_mfma_f32_16x16x32_bf16 v[10:13], v[228:231], v[70:73], v[10:13]
	s_waitcnt vmcnt(7)
	s_waitcnt lgkmcnt(0)
	s_barrier
	s_add_i32 m0, s67, 0x10000
	s_nop 0
	global_load_lds_dwordx4 v188, s[80:81]
	s_add_i32 m0, s67, 0x12000
	s_nop 0
	global_load_lds_dwordx4 v189, s[80:81]
	s_add_i32 m0, s67, 0x14000
	s_nop 0
	global_load_lds_dwordx4 v190, s[80:81]
	s_add_i32 m0, s67, 0x16000
	s_nop 0
	global_load_lds_dwordx4 v191, s[80:81]
	s_add_i32 m0, s67, 0x20400
	s_nop 0
	global_load_lds_dwordx4 v205, s[96:97]
	s_add_i32 m0, s67, 0x22400
	s_nop 0
	global_load_lds_dwordx4 v206, s[96:97]
	s_add_u32 s80, s80, 0x80
	s_addc_u32 s81, s81, 0
	s_add_u32 s96, s96, 0x80
	s_addc_u32 s97, s97, 0
	ds_read_b128 v[82:85], v90 offset:0
	ds_read_b128 v[86:89], v90 offset:2048
	ds_read_b128 v[208:211], v90 offset:4096
	ds_read_b128 v[212:215], v90 offset:6144
	ds_read_b128 v[66:69], v207 offset:0
	ds_read_b128 v[70:73], v207 offset:2048
	v_mfma_f32_16x16x32_bf16 v[34:37], v[216:219], v[74:77], v[34:37]
	v_mfma_f32_16x16x32_bf16 v[22:25], v[220:223], v[74:77], v[22:25]
	v_mfma_f32_16x16x32_bf16 v[18:21], v[224:227], v[74:77], v[18:21]
	v_mfma_f32_16x16x32_bf16 v[62:65], v[228:231], v[74:77], v[62:65]
	ds_read_b128 v[74:77], v207 offset:4096
	v_mfma_f32_16x16x32_bf16 v[58:61], v[216:219], v[78:81], v[58:61]
	v_mfma_f32_16x16x32_bf16 v[54:57], v[220:223], v[78:81], v[54:57]
	v_mfma_f32_16x16x32_bf16 v[50:53], v[224:227], v[78:81], v[50:53]
	v_mfma_f32_16x16x32_bf16 v[2:5], v[228:231], v[78:81], v[2:5]
	ds_read_b128 v[78:81], v207 offset:6144
	ds_read_b128 v[216:219], v91 offset:0
	ds_read_b128 v[220:223], v91 offset:2048
	ds_read_b128 v[224:227], v91 offset:4096
	ds_read_b128 v[228:231], v91 offset:6144
	s_waitcnt lgkmcnt(7)
	v_mfma_f32_16x16x32_bf16 v[6:9], v[82:85], v[66:69], v[6:9]
	v_mfma_f32_16x16x32_bf16 v[30:33], v[86:89], v[66:69], v[30:33]
	v_mfma_f32_16x16x32_bf16 v[38:41], v[208:211], v[66:69], v[38:41]
	v_mfma_f32_16x16x32_bf16 v[42:45], v[212:215], v[66:69], v[42:45]
	ds_read_b128 v[66:69], v119 offset:0
	s_waitcnt lgkmcnt(7)
	v_mfma_f32_16x16x32_bf16 v[46:49], v[82:85], v[70:73], v[46:49]
	v_mfma_f32_16x16x32_bf16 v[26:29], v[86:89], v[70:73], v[26:29]
	v_mfma_f32_16x16x32_bf16 v[14:17], v[208:211], v[70:73], v[14:17]
	v_mfma_f32_16x16x32_bf16 v[10:13], v[212:215], v[70:73], v[10:13]
	ds_read_b128 v[70:73], v119 offset:2048
	s_waitcnt lgkmcnt(7)
	v_mfma_f32_16x16x32_bf16 v[34:37], v[82:85], v[74:77], v[34:37]
	v_mfma_f32_16x16x32_bf16 v[22:25], v[86:89], v[74:77], v[22:25]
	v_mfma_f32_16x16x32_bf16 v[18:21], v[208:211], v[74:77], v[18:21]
	v_mfma_f32_16x16x32_bf16 v[62:65], v[212:215], v[74:77], v[62:65]
	ds_read_b128 v[74:77], v119 offset:4096
	s_waitcnt lgkmcnt(7)
	v_mfma_f32_16x16x32_bf16 v[58:61], v[82:85], v[78:81], v[58:61]
	v_mfma_f32_16x16x32_bf16 v[54:57], v[86:89], v[78:81], v[54:57]
	v_mfma_f32_16x16x32_bf16 v[50:53], v[208:211], v[78:81], v[50:53]
	v_mfma_f32_16x16x32_bf16 v[2:5], v[212:215], v[78:81], v[2:5]
	ds_read_b128 v[78:81], v119 offset:6144
	s_waitcnt lgkmcnt(3)
	v_mfma_f32_16x16x32_bf16 v[6:9], v[216:219], v[66:69], v[6:9]
	v_mfma_f32_16x16x32_bf16 v[30:33], v[220:223], v[66:69], v[30:33]
	v_mfma_f32_16x16x32_bf16 v[38:41], v[224:227], v[66:69], v[38:41]
	v_mfma_f32_16x16x32_bf16 v[42:45], v[228:231], v[66:69], v[42:45]
	s_waitcnt lgkmcnt(2)
	v_mfma_f32_16x16x32_bf16 v[46:49], v[216:219], v[70:73], v[46:49]
	v_mfma_f32_16x16x32_bf16 v[26:29], v[220:223], v[70:73], v[26:29]
	v_mfma_f32_16x16x32_bf16 v[14:17], v[224:227], v[70:73], v[14:17]
	v_mfma_f32_16x16x32_bf16 v[10:13], v[228:231], v[70:73], v[10:13]
	s_waitcnt vmcnt(6)
	s_waitcnt lgkmcnt(0)
	s_barrier
	s_add_i32 m0, s67, 0x0
	s_nop 0
	global_load_lds_dwordx4 v188, s[80:81]
	s_add_i32 m0, s67, 0x2000
	s_nop 0
	global_load_lds_dwordx4 v189, s[80:81]
	s_add_i32 m0, s67, 0x4000
	s_nop 0
	global_load_lds_dwordx4 v190, s[80:81]
	s_add_i32 m0, s67, 0x6000
	s_nop 0
	global_load_lds_dwordx4 v191, s[80:81]
	s_add_i32 m0, s67, 0x18000
	s_nop 0
	global_load_lds_dwordx4 v205, s[96:97]
	s_add_i32 m0, s67, 0x1a000
	s_nop 0
	global_load_lds_dwordx4 v206, s[96:97]
	s_add_u32 s80, s80, 0x80
	s_addc_u32 s81, s81, 0
	s_add_u32 s96, s96, 0x80
	s_addc_u32 s97, s97, 0
	ds_read_b128 v[82:85], v90 offset:16384
	ds_read_b128 v[86:89], v90 offset:18432
	ds_read_b128 v[208:211], v90 offset:20480
	ds_read_b128 v[212:215], v90 offset:22528
	ds_read_b128 v[66:69], v207 offset:32768
	ds_read_b128 v[70:73], v207 offset:34816
	v_mfma_f32_16x16x32_bf16 v[34:37], v[216:219], v[74:77], v[34:37]
	v_mfma_f32_16x16x32_bf16 v[22:25], v[220:223], v[74:77], v[22:25]
	v_mfma_f32_16x16x32_bf16 v[18:21], v[224:227], v[74:77], v[18:21]
	v_mfma_f32_16x16x32_bf16 v[62:65], v[228:231], v[74:77], v[62:65]
	ds_read_b128 v[74:77], v207 offset:36864
	v_mfma_f32_16x16x32_bf16 v[58:61], v[216:219], v[78:81], v[58:61]
	v_mfma_f32_16x16x32_bf16 v[54:57], v[220:223], v[78:81], v[54:57]
	v_mfma_f32_16x16x32_bf16 v[50:53], v[224:227], v[78:81], v[50:53]
	v_mfma_f32_16x16x32_bf16 v[2:5], v[228:231], v[78:81], v[2:5]
	ds_read_b128 v[78:81], v207 offset:38912
	ds_read_b128 v[216:219], v91 offset:16384
	ds_read_b128 v[220:223], v91 offset:18432
	ds_read_b128 v[224:227], v91 offset:20480
	ds_read_b128 v[228:231], v91 offset:22528
	s_waitcnt lgkmcnt(7)
	v_mfma_f32_16x16x32_bf16 v[6:9], v[82:85], v[66:69], v[6:9]
	v_mfma_f32_16x16x32_bf16 v[30:33], v[86:89], v[66:69], v[30:33]
	v_mfma_f32_16x16x32_bf16 v[38:41], v[208:211], v[66:69], v[38:41]
	v_mfma_f32_16x16x32_bf16 v[42:45], v[212:215], v[66:69], v[42:45]
	ds_read_b128 v[66:69], v119 offset:32768
	s_waitcnt lgkmcnt(7)
	v_mfma_f32_16x16x32_bf16 v[46:49], v[82:85], v[70:73], v[46:49]
	v_mfma_f32_16x16x32_bf16 v[26:29], v[86:89], v[70:73], v[26:29]
	v_mfma_f32_16x16x32_bf16 v[14:17], v[208:211], v[70:73], v[14:17]
	v_mfma_f32_16x16x32_bf16 v[10:13], v[212:215], v[70:73], v[10:13]
	ds_read_b128 v[70:73], v119 offset:34816
	s_waitcnt lgkmcnt(7)
	v_mfma_f32_16x16x32_bf16 v[34:37], v[82:85], v[74:77], v[34:37]
	v_mfma_f32_16x16x32_bf16 v[22:25], v[86:89], v[74:77], v[22:25]
	v_mfma_f32_16x16x32_bf16 v[18:21], v[208:211], v[74:77], v[18:21]
	v_mfma_f32_16x16x32_bf16 v[62:65], v[212:215], v[74:77], v[62:65]
	ds_read_b128 v[74:77], v119 offset:36864
	s_waitcnt lgkmcnt(7)
	v_mfma_f32_16x16x32_bf16 v[58:61], v[82:85], v[78:81], v[58:61]
	v_mfma_f32_16x16x32_bf16 v[54:57], v[86:89], v[78:81], v[54:57]
	v_mfma_f32_16x16x32_bf16 v[50:53], v[208:211], v[78:81], v[50:53]
	v_mfma_f32_16x16x32_bf16 v[2:5], v[212:215], v[78:81], v[2:5]
	ds_read_b128 v[78:81], v119 offset:38912
	s_waitcnt lgkmcnt(3)
	v_mfma_f32_16x16x32_bf16 v[6:9], v[216:219], v[66:69], v[6:9]
	v_mfma_f32_16x16x32_bf16 v[30:33], v[220:223], v[66:69], v[30:33]
	v_mfma_f32_16x16x32_bf16 v[38:41], v[224:227], v[66:69], v[38:41]
	v_mfma_f32_16x16x32_bf16 v[42:45], v[228:231], v[66:69], v[42:45]
	s_waitcnt lgkmcnt(2)
	v_mfma_f32_16x16x32_bf16 v[46:49], v[216:219], v[70:73], v[46:49]
	v_mfma_f32_16x16x32_bf16 v[26:29], v[220:223], v[70:73], v[26:29]
	v_mfma_f32_16x16x32_bf16 v[14:17], v[224:227], v[70:73], v[14:17]
	v_mfma_f32_16x16x32_bf16 v[10:13], v[228:231], v[70:73], v[10:13]
	s_waitcnt vmcnt(6)
	s_waitcnt lgkmcnt(0)
	s_barrier
	s_add_i32 m0, s67, 0x8000
	s_nop 0
	global_load_lds_dwordx4 v188, s[80:81]
	s_add_i32 m0, s67, 0xa000
	s_nop 0
	global_load_lds_dwordx4 v189, s[80:81]
	s_add_i32 m0, s67, 0xc000
	s_nop 0
	global_load_lds_dwordx4 v190, s[80:81]
	s_add_i32 m0, s67, 0xe000
	s_nop 0
	global_load_lds_dwordx4 v191, s[80:81]
	s_add_i32 m0, s67, 0x1c000
	s_nop 0
	global_load_lds_dwordx4 v205, s[96:97]
	s_add_i32 m0, s67, 0x1e000
	s_nop 0
	global_load_lds_dwordx4 v206, s[96:97]
	s_add_u32 s80, s80, 0x80
	s_addc_u32 s81, s81, 0
	s_add_u32 s96, s96, 0x80
	s_addc_u32 s97, s97, 0
	s_movk_i32 s10, 0x800
	s_mov_b32 s11, 0
	v_lshl_add_u64 v[248:249], v[128:129], 0, s[10:11]
	global_load_dwordx2 v[232:233], v[248:249], off
	global_load_dwordx2 v[234:235], v[248:249], off offset:32
	v_lshl_add_u64 v[248:249], v[132:133], 0, s[10:11]
	global_load_dwordx2 v[236:237], v[248:249], off
	global_load_dwordx2 v[238:239], v[248:249], off offset:32
	v_lshl_add_u64 v[248:249], v[152:153], 0, s[10:11]
	global_load_dwordx2 v[240:241], v[248:249], off
	global_load_dwordx2 v[242:243], v[248:249], off offset:32
	v_lshl_add_u64 v[248:249], v[154:155], 0, s[10:11]
	global_load_dwordx2 v[244:245], v[248:249], off
	global_load_dwordx2 v[246:247], v[248:249], off offset:32
	ds_read_b128 v[82:85], v90 offset:33792
	ds_read_b128 v[86:89], v90 offset:35840
	ds_read_b128 v[208:211], v90 offset:37888
	ds_read_b128 v[212:215], v90 offset:39936
	ds_read_b128 v[66:69], v0 offset:0
	ds_read_b128 v[70:73], v0 offset:2048
	v_mfma_f32_16x16x32_bf16 v[34:37], v[216:219], v[74:77], v[34:37]
	v_mfma_f32_16x16x32_bf16 v[22:25], v[220:223], v[74:77], v[22:25]
	v_mfma_f32_16x16x32_bf16 v[18:21], v[224:227], v[74:77], v[18:21]
	v_mfma_f32_16x16x32_bf16 v[62:65], v[228:231], v[74:77], v[62:65]
	ds_read_b128 v[74:77], v0 offset:4096
	v_mfma_f32_16x16x32_bf16 v[58:61], v[216:219], v[78:81], v[58:61]
	v_mfma_f32_16x16x32_bf16 v[54:57], v[220:223], v[78:81], v[54:57]
	v_mfma_f32_16x16x32_bf16 v[50:53], v[224:227], v[78:81], v[50:53]
	v_mfma_f32_16x16x32_bf16 v[2:5], v[228:231], v[78:81], v[2:5]
	ds_read_b128 v[78:81], v0 offset:6144
	ds_read_b128 v[216:219], v91 offset:33792
	ds_read_b128 v[220:223], v91 offset:35840
	ds_read_b128 v[224:227], v91 offset:37888
	ds_read_b128 v[228:231], v91 offset:39936
	s_waitcnt lgkmcnt(7)
	v_mfma_f32_16x16x32_bf16 v[6:9], v[82:85], v[66:69], v[6:9]
	v_mfma_f32_16x16x32_bf16 v[30:33], v[86:89], v[66:69], v[30:33]
	v_mfma_f32_16x16x32_bf16 v[38:41], v[208:211], v[66:69], v[38:41]
	v_mfma_f32_16x16x32_bf16 v[42:45], v[212:215], v[66:69], v[42:45]
	ds_read_b128 v[66:69], v255 offset:0
	s_waitcnt lgkmcnt(7)
	v_mfma_f32_16x16x32_bf16 v[46:49], v[82:85], v[70:73], v[46:49]
	v_mfma_f32_16x16x32_bf16 v[26:29], v[86:89], v[70:73], v[26:29]
	v_mfma_f32_16x16x32_bf16 v[14:17], v[208:211], v[70:73], v[14:17]
	v_mfma_f32_16x16x32_bf16 v[10:13], v[212:215], v[70:73], v[10:13]
	ds_read_b128 v[70:73], v255 offset:2048
	s_waitcnt lgkmcnt(7)
	v_mfma_f32_16x16x32_bf16 v[34:37], v[82:85], v[74:77], v[34:37]
	v_mfma_f32_16x16x32_bf16 v[22:25], v[86:89], v[74:77], v[22:25]
	v_mfma_f32_16x16x32_bf16 v[18:21], v[208:211], v[74:77], v[18:21]
	v_mfma_f32_16x16x32_bf16 v[62:65], v[212:215], v[74:77], v[62:65]
	ds_read_b128 v[74:77], v255 offset:4096
	s_waitcnt lgkmcnt(7)
	v_mfma_f32_16x16x32_bf16 v[58:61], v[82:85], v[78:81], v[58:61]
	v_mfma_f32_16x16x32_bf16 v[54:57], v[86:89], v[78:81], v[54:57]
	v_mfma_f32_16x16x32_bf16 v[50:53], v[208:211], v[78:81], v[50:53]
	v_mfma_f32_16x16x32_bf16 v[2:5], v[212:215], v[78:81], v[2:5]
	ds_read_b128 v[78:81], v255 offset:6144
	s_waitcnt lgkmcnt(3)
	v_mfma_f32_16x16x32_bf16 v[6:9], v[216:219], v[66:69], v[6:9]
	v_mfma_f32_16x16x32_bf16 v[30:33], v[220:223], v[66:69], v[30:33]
	v_mfma_f32_16x16x32_bf16 v[38:41], v[224:227], v[66:69], v[38:41]
	v_mfma_f32_16x16x32_bf16 v[42:45], v[228:231], v[66:69], v[42:45]
	s_waitcnt lgkmcnt(2)
	v_mfma_f32_16x16x32_bf16 v[46:49], v[216:219], v[70:73], v[46:49]
	v_mfma_f32_16x16x32_bf16 v[26:29], v[220:223], v[70:73], v[26:29]
	v_mfma_f32_16x16x32_bf16 v[14:17], v[224:227], v[70:73], v[14:17]
	v_mfma_f32_16x16x32_bf16 v[10:13], v[228:231], v[70:73], v[10:13]
	s_waitcnt vmcnt(14)
	s_waitcnt lgkmcnt(0)
	s_barrier
	s_add_i32 m0, s67, 0x10000
	s_nop 0
	global_load_lds_dwordx4 v188, s[80:81]
	s_add_i32 m0, s67, 0x12000
	s_nop 0
	global_load_lds_dwordx4 v189, s[80:81]
	s_add_i32 m0, s67, 0x14000
	s_nop 0
	global_load_lds_dwordx4 v190, s[80:81]
	s_add_i32 m0, s67, 0x16000
	s_nop 0
	global_load_lds_dwordx4 v191, s[80:81]
	s_add_i32 m0, s67, 0x20400
	s_nop 0
	global_load_lds_dwordx4 v205, s[96:97]
	s_add_i32 m0, s67, 0x22400
	s_nop 0
	global_load_lds_dwordx4 v206, s[96:97]
	s_add_u32 s80, s80, 0x880
	s_addc_u32 s81, s81, 0
	s_add_u32 s96, s96, 0xffc80
	s_addc_u32 s97, s97, 0
	ds_read_b128 v[82:85], v90 offset:0
	ds_read_b128 v[86:89], v90 offset:2048
	ds_read_b128 v[208:211], v90 offset:4096
	ds_read_b128 v[212:215], v90 offset:6144
	ds_read_b128 v[66:69], v207 offset:0
	ds_read_b128 v[70:73], v207 offset:2048
	v_mfma_f32_16x16x32_bf16 v[34:37], v[216:219], v[74:77], v[34:37]
	v_mfma_f32_16x16x32_bf16 v[22:25], v[220:223], v[74:77], v[22:25]
	v_mfma_f32_16x16x32_bf16 v[18:21], v[224:227], v[74:77], v[18:21]
	v_mfma_f32_16x16x32_bf16 v[62:65], v[228:231], v[74:77], v[62:65]
	ds_read_b128 v[74:77], v207 offset:4096
	v_mfma_f32_16x16x32_bf16 v[58:61], v[216:219], v[78:81], v[58:61]
	v_mfma_f32_16x16x32_bf16 v[54:57], v[220:223], v[78:81], v[54:57]
	v_mfma_f32_16x16x32_bf16 v[50:53], v[224:227], v[78:81], v[50:53]
	v_mfma_f32_16x16x32_bf16 v[2:5], v[228:231], v[78:81], v[2:5]
	ds_read_b128 v[78:81], v207 offset:6144
	ds_read_b128 v[216:219], v91 offset:0
	ds_read_b128 v[220:223], v91 offset:2048
	ds_read_b128 v[224:227], v91 offset:4096
	ds_read_b128 v[228:231], v91 offset:6144
	s_waitcnt lgkmcnt(7)
	v_mfma_f32_16x16x32_bf16 v[6:9], v[82:85], v[66:69], v[6:9]
	v_mfma_f32_16x16x32_bf16 v[30:33], v[86:89], v[66:69], v[30:33]
	v_mfma_f32_16x16x32_bf16 v[38:41], v[208:211], v[66:69], v[38:41]
	v_mfma_f32_16x16x32_bf16 v[42:45], v[212:215], v[66:69], v[42:45]
	ds_read_b128 v[66:69], v119 offset:0
	s_waitcnt lgkmcnt(7)
	v_mfma_f32_16x16x32_bf16 v[46:49], v[82:85], v[70:73], v[46:49]
	v_mfma_f32_16x16x32_bf16 v[26:29], v[86:89], v[70:73], v[26:29]
	v_mfma_f32_16x16x32_bf16 v[14:17], v[208:211], v[70:73], v[14:17]
	v_mfma_f32_16x16x32_bf16 v[10:13], v[212:215], v[70:73], v[10:13]
	ds_read_b128 v[70:73], v119 offset:2048
	s_waitcnt lgkmcnt(7)
	v_mfma_f32_16x16x32_bf16 v[34:37], v[82:85], v[74:77], v[34:37]
	v_mfma_f32_16x16x32_bf16 v[22:25], v[86:89], v[74:77], v[22:25]
	v_mfma_f32_16x16x32_bf16 v[18:21], v[208:211], v[74:77], v[18:21]
	v_mfma_f32_16x16x32_bf16 v[62:65], v[212:215], v[74:77], v[62:65]
	ds_read_b128 v[74:77], v119 offset:4096
	s_waitcnt lgkmcnt(7)
	v_mfma_f32_16x16x32_bf16 v[58:61], v[82:85], v[78:81], v[58:61]
	v_mfma_f32_16x16x32_bf16 v[54:57], v[86:89], v[78:81], v[54:57]
	v_mfma_f32_16x16x32_bf16 v[50:53], v[208:211], v[78:81], v[50:53]
	v_mfma_f32_16x16x32_bf16 v[2:5], v[212:215], v[78:81], v[2:5]
	ds_read_b128 v[78:81], v119 offset:6144
	s_waitcnt lgkmcnt(3)
	v_mfma_f32_16x16x32_bf16 v[6:9], v[216:219], v[66:69], v[6:9]
	v_mfma_f32_16x16x32_bf16 v[30:33], v[220:223], v[66:69], v[30:33]
	v_mfma_f32_16x16x32_bf16 v[38:41], v[224:227], v[66:69], v[38:41]
	v_mfma_f32_16x16x32_bf16 v[42:45], v[228:231], v[66:69], v[42:45]
	s_waitcnt lgkmcnt(2)
	v_mfma_f32_16x16x32_bf16 v[46:49], v[216:219], v[70:73], v[46:49]
	v_mfma_f32_16x16x32_bf16 v[26:29], v[220:223], v[70:73], v[26:29]
	v_mfma_f32_16x16x32_bf16 v[14:17], v[224:227], v[70:73], v[14:17]
	v_mfma_f32_16x16x32_bf16 v[10:13], v[228:231], v[70:73], v[10:13]
	s_waitcnt vmcnt(14)
	s_waitcnt lgkmcnt(0)
	s_barrier
	s_add_i32 m0, s67, 0x0
	s_nop 0
	global_load_lds_dwordx4 v188, s[80:81]
	s_add_i32 m0, s67, 0x2000
	s_nop 0
	global_load_lds_dwordx4 v189, s[80:81]
	s_add_i32 m0, s67, 0x4000
	s_nop 0
	global_load_lds_dwordx4 v190, s[80:81]
	s_add_i32 m0, s67, 0x6000
	s_nop 0
	global_load_lds_dwordx4 v191, s[80:81]
	s_add_i32 m0, s67, 0x18000
	s_nop 0
	global_load_lds_dwordx4 v205, s[96:97]
	s_add_i32 m0, s67, 0x1a000
	s_nop 0
	global_load_lds_dwordx4 v206, s[96:97]
	s_add_u32 s80, s80, 0x80
	s_addc_u32 s81, s81, 0
	s_add_u32 s96, s96, 0x80
	s_addc_u32 s97, s97, 0
	ds_read_b128 v[82:85], v90 offset:16384
	ds_read_b128 v[86:89], v90 offset:18432
	ds_read_b128 v[208:211], v90 offset:20480
	ds_read_b128 v[212:215], v90 offset:22528
	ds_read_b128 v[66:69], v207 offset:32768
	ds_read_b128 v[70:73], v207 offset:34816
	v_mfma_f32_16x16x32_bf16 v[34:37], v[216:219], v[74:77], v[34:37]
	v_mfma_f32_16x16x32_bf16 v[22:25], v[220:223], v[74:77], v[22:25]
	v_mfma_f32_16x16x32_bf16 v[18:21], v[224:227], v[74:77], v[18:21]
	v_mfma_f32_16x16x32_bf16 v[62:65], v[228:231], v[74:77], v[62:65]
	ds_read_b128 v[74:77], v207 offset:36864
	v_mfma_f32_16x16x32_bf16 v[58:61], v[216:219], v[78:81], v[58:61]
	v_mfma_f32_16x16x32_bf16 v[54:57], v[220:223], v[78:81], v[54:57]
	v_mfma_f32_16x16x32_bf16 v[50:53], v[224:227], v[78:81], v[50:53]
	v_mfma_f32_16x16x32_bf16 v[2:5], v[228:231], v[78:81], v[2:5]
	ds_read_b128 v[78:81], v207 offset:38912
	ds_read_b128 v[216:219], v91 offset:16384
	ds_read_b128 v[220:223], v91 offset:18432
	ds_read_b128 v[224:227], v91 offset:20480
	ds_read_b128 v[228:231], v91 offset:22528
	s_waitcnt lgkmcnt(7)
	v_mfma_f32_16x16x32_bf16 v[6:9], v[82:85], v[66:69], v[6:9]
	v_mfma_f32_16x16x32_bf16 v[30:33], v[86:89], v[66:69], v[30:33]
	v_mfma_f32_16x16x32_bf16 v[38:41], v[208:211], v[66:69], v[38:41]
	v_mfma_f32_16x16x32_bf16 v[42:45], v[212:215], v[66:69], v[42:45]
	ds_read_b128 v[66:69], v119 offset:32768
	s_waitcnt lgkmcnt(7)
	v_mfma_f32_16x16x32_bf16 v[46:49], v[82:85], v[70:73], v[46:49]
	v_mfma_f32_16x16x32_bf16 v[26:29], v[86:89], v[70:73], v[26:29]
	v_mfma_f32_16x16x32_bf16 v[14:17], v[208:211], v[70:73], v[14:17]
	v_mfma_f32_16x16x32_bf16 v[10:13], v[212:215], v[70:73], v[10:13]
	ds_read_b128 v[70:73], v119 offset:34816
	s_waitcnt lgkmcnt(7)
	v_mfma_f32_16x16x32_bf16 v[34:37], v[82:85], v[74:77], v[34:37]
	v_mfma_f32_16x16x32_bf16 v[22:25], v[86:89], v[74:77], v[22:25]
	v_mfma_f32_16x16x32_bf16 v[18:21], v[208:211], v[74:77], v[18:21]
	v_mfma_f32_16x16x32_bf16 v[62:65], v[212:215], v[74:77], v[62:65]
	ds_read_b128 v[74:77], v119 offset:36864
	s_waitcnt lgkmcnt(7)
	v_mfma_f32_16x16x32_bf16 v[58:61], v[82:85], v[78:81], v[58:61]
	v_mfma_f32_16x16x32_bf16 v[54:57], v[86:89], v[78:81], v[54:57]
	v_mfma_f32_16x16x32_bf16 v[50:53], v[208:211], v[78:81], v[50:53]
	v_mfma_f32_16x16x32_bf16 v[2:5], v[212:215], v[78:81], v[2:5]
	ds_read_b128 v[78:81], v119 offset:38912
	s_waitcnt lgkmcnt(3)
	v_mfma_f32_16x16x32_bf16 v[6:9], v[216:219], v[66:69], v[6:9]
	v_mfma_f32_16x16x32_bf16 v[30:33], v[220:223], v[66:69], v[30:33]
	v_mfma_f32_16x16x32_bf16 v[38:41], v[224:227], v[66:69], v[38:41]
	v_mfma_f32_16x16x32_bf16 v[42:45], v[228:231], v[66:69], v[42:45]
	s_waitcnt lgkmcnt(2)
	v_mfma_f32_16x16x32_bf16 v[46:49], v[216:219], v[70:73], v[46:49]
	v_mfma_f32_16x16x32_bf16 v[26:29], v[220:223], v[70:73], v[26:29]
	v_mfma_f32_16x16x32_bf16 v[14:17], v[224:227], v[70:73], v[14:17]
	v_mfma_f32_16x16x32_bf16 v[10:13], v[228:231], v[70:73], v[10:13]
	s_waitcnt vmcnt(6)
	s_waitcnt lgkmcnt(0)
	s_barrier
	s_add_i32 m0, s67, 0x8000
	s_nop 0
	global_load_lds_dwordx4 v188, s[80:81]
	s_add_i32 m0, s67, 0xa000
	s_nop 0
	global_load_lds_dwordx4 v189, s[80:81]
	s_add_i32 m0, s67, 0xc000
	s_nop 0
	global_load_lds_dwordx4 v190, s[80:81]
	s_add_i32 m0, s67, 0xe000
	s_nop 0
	global_load_lds_dwordx4 v191, s[80:81]
	s_add_i32 m0, s67, 0x1c000
	s_nop 0
	global_load_lds_dwordx4 v205, s[96:97]
	s_add_i32 m0, s67, 0x1e000
	s_nop 0
	global_load_lds_dwordx4 v206, s[96:97]
	s_add_u32 s80, s80, 0x80
	s_addc_u32 s81, s81, 0
	s_add_u32 s96, s96, 0x80
	s_addc_u32 s97, s97, 0
	ds_read_b128 v[82:85], v90 offset:33792
	ds_read_b128 v[86:89], v90 offset:35840
	ds_read_b128 v[208:211], v90 offset:37888
	ds_read_b128 v[212:215], v90 offset:39936
	ds_read_b128 v[66:69], v0 offset:0
	ds_read_b128 v[70:73], v0 offset:2048
	v_mfma_f32_16x16x32_bf16 v[34:37], v[216:219], v[74:77], v[34:37]
	v_mfma_f32_16x16x32_bf16 v[22:25], v[220:223], v[74:77], v[22:25]
	v_mfma_f32_16x16x32_bf16 v[18:21], v[224:227], v[74:77], v[18:21]
	v_mfma_f32_16x16x32_bf16 v[62:65], v[228:231], v[74:77], v[62:65]
	ds_read_b128 v[74:77], v0 offset:4096
	v_mfma_f32_16x16x32_bf16 v[58:61], v[216:219], v[78:81], v[58:61]
	v_mfma_f32_16x16x32_bf16 v[54:57], v[220:223], v[78:81], v[54:57]
	v_mfma_f32_16x16x32_bf16 v[50:53], v[224:227], v[78:81], v[50:53]
	v_mfma_f32_16x16x32_bf16 v[2:5], v[228:231], v[78:81], v[2:5]
	ds_read_b128 v[78:81], v0 offset:6144
	ds_read_b128 v[216:219], v91 offset:33792
	ds_read_b128 v[220:223], v91 offset:35840
	ds_read_b128 v[224:227], v91 offset:37888
	ds_read_b128 v[228:231], v91 offset:39936
	s_waitcnt lgkmcnt(7)
	v_mfma_f32_16x16x32_bf16 v[6:9], v[82:85], v[66:69], v[6:9]
	v_mfma_f32_16x16x32_bf16 v[30:33], v[86:89], v[66:69], v[30:33]
	v_mfma_f32_16x16x32_bf16 v[38:41], v[208:211], v[66:69], v[38:41]
	v_mfma_f32_16x16x32_bf16 v[42:45], v[212:215], v[66:69], v[42:45]
	ds_read_b128 v[66:69], v255 offset:0
	s_waitcnt lgkmcnt(7)
	v_mfma_f32_16x16x32_bf16 v[46:49], v[82:85], v[70:73], v[46:49]
	v_mfma_f32_16x16x32_bf16 v[26:29], v[86:89], v[70:73], v[26:29]
	v_mfma_f32_16x16x32_bf16 v[14:17], v[208:211], v[70:73], v[14:17]
	v_mfma_f32_16x16x32_bf16 v[10:13], v[212:215], v[70:73], v[10:13]
	ds_read_b128 v[70:73], v255 offset:2048
	s_waitcnt lgkmcnt(7)
	v_mfma_f32_16x16x32_bf16 v[34:37], v[82:85], v[74:77], v[34:37]
	v_mfma_f32_16x16x32_bf16 v[22:25], v[86:89], v[74:77], v[22:25]
	v_mfma_f32_16x16x32_bf16 v[18:21], v[208:211], v[74:77], v[18:21]
	v_mfma_f32_16x16x32_bf16 v[62:65], v[212:215], v[74:77], v[62:65]
	ds_read_b128 v[74:77], v255 offset:4096
	s_waitcnt lgkmcnt(7)
	v_mfma_f32_16x16x32_bf16 v[58:61], v[82:85], v[78:81], v[58:61]
	v_mfma_f32_16x16x32_bf16 v[54:57], v[86:89], v[78:81], v[54:57]
	v_mfma_f32_16x16x32_bf16 v[50:53], v[208:211], v[78:81], v[50:53]
	v_mfma_f32_16x16x32_bf16 v[2:5], v[212:215], v[78:81], v[2:5]
	ds_read_b128 v[78:81], v255 offset:6144
	s_waitcnt lgkmcnt(3)
	v_mfma_f32_16x16x32_bf16 v[6:9], v[216:219], v[66:69], v[6:9]
	s_waitcnt vmcnt(18)
	v_mfma_f32_16x16x32_bf16 v[30:33], v[220:223], v[66:69], v[30:33]
	v_mfma_f32_16x16x32_bf16 v[38:41], v[224:227], v[66:69], v[38:41]
	v_mfma_f32_16x16x32_bf16 v[42:45], v[228:231], v[66:69], v[42:45]
	v_cvt_f32_ubyte0_e32 v248, v232
	v_cvt_f32_ubyte1_e32 v249, v232
	v_cvt_f32_ubyte2_e32 v250, v232
	v_cvt_f32_ubyte3_e32 v251, v232
	v_mul_f32_e32 v248, s34, v248
	v_mul_f32_e32 v249, s34, v249
	v_mul_f32_e32 v250, s34, v250
	v_mul_f32_e32 v251, s34, v251
	v_fma_f32 v184, v6, v248, v184
	v_fma_f32 v185, v7, v249, v185
	v_fma_f32 v186, v8, v250, v186
	v_fma_f32 v187, v9, v251, v187
	s_waitcnt lgkmcnt(2)
	v_mfma_f32_16x16x32_bf16 v[46:49], v[216:219], v[70:73], v[46:49]
	v_cvt_f32_ubyte0_e32 v248, v233
	v_cvt_f32_ubyte1_e32 v249, v233
	v_cvt_f32_ubyte2_e32 v250, v233
	v_cvt_f32_ubyte3_e32 v251, v233
	v_mul_f32_e32 v248, s34, v248
	v_mul_f32_e32 v249, s34, v249
	v_mul_f32_e32 v250, s34, v250
	v_mul_f32_e32 v251, s34, v251
	v_fma_f32 v180, v30, v248, v180
	v_fma_f32 v181, v31, v249, v181
	v_fma_f32 v182, v32, v250, v182
	v_fma_f32 v183, v33, v251, v183
	v_mfma_f32_16x16x32_bf16 v[26:29], v[220:223], v[70:73], v[26:29]
	v_cvt_f32_ubyte0_e32 v248, v234
	v_cvt_f32_ubyte1_e32 v249, v234
	v_cvt_f32_ubyte2_e32 v250, v234
	v_cvt_f32_ubyte3_e32 v251, v234
	v_mul_f32_e32 v248, s34, v248
	v_mul_f32_e32 v249, s34, v249
	v_mul_f32_e32 v250, s34, v250
	v_mul_f32_e32 v251, s34, v251
	v_fma_f32 v176, v38, v248, v176
	v_fma_f32 v177, v39, v249, v177
	v_fma_f32 v178, v40, v250, v178
	v_fma_f32 v179, v41, v251, v179
	v_mfma_f32_16x16x32_bf16 v[14:17], v[224:227], v[70:73], v[14:17]
	v_cvt_f32_ubyte0_e32 v248, v235
	v_cvt_f32_ubyte1_e32 v249, v235
	v_cvt_f32_ubyte2_e32 v250, v235
	v_cvt_f32_ubyte3_e32 v251, v235
	v_mul_f32_e32 v248, s34, v248
	v_mul_f32_e32 v249, s34, v249
	v_mul_f32_e32 v250, s34, v250
	v_mul_f32_e32 v251, s34, v251
	v_fma_f32 v172, v42, v248, v172
	v_fma_f32 v173, v43, v249, v173
	v_fma_f32 v174, v44, v250, v174
	v_fma_f32 v175, v45, v251, v175
	v_mfma_f32_16x16x32_bf16 v[10:13], v[228:231], v[70:73], v[10:13]
	v_cvt_f32_ubyte0_e32 v248, v236
	v_cvt_f32_ubyte1_e32 v249, v236
	v_cvt_f32_ubyte2_e32 v250, v236
	v_cvt_f32_ubyte3_e32 v251, v236
	v_mul_f32_e32 v248, s34, v248
	v_mul_f32_e32 v249, s34, v249
	v_mul_f32_e32 v250, s34, v250
	v_mul_f32_e32 v251, s34, v251
	v_fma_f32 v168, v46, v248, v168
	v_fma_f32 v169, v47, v249, v169
	v_fma_f32 v170, v48, v250, v170
	v_fma_f32 v171, v49, v251, v171
	s_waitcnt vmcnt(6)
	s_waitcnt lgkmcnt(0)
	s_barrier
	s_add_i32 m0, s67, 0x10000
	s_nop 0
	global_load_lds_dwordx4 v188, s[80:81]
	s_add_i32 m0, s67, 0x12000
	s_nop 0
	global_load_lds_dwordx4 v189, s[80:81]
	s_add_i32 m0, s67, 0x14000
	s_nop 0
	global_load_lds_dwordx4 v190, s[80:81]
	s_add_i32 m0, s67, 0x16000
	s_nop 0
	global_load_lds_dwordx4 v191, s[80:81]
	s_add_i32 m0, s67, 0x20400
	s_nop 0
	global_load_lds_dwordx4 v205, s[96:97]
	s_add_i32 m0, s67, 0x22400
	s_nop 0
	global_load_lds_dwordx4 v206, s[96:97]
	s_add_u32 s80, s80, 0x80
	s_addc_u32 s81, s81, 0
	s_add_u32 s96, s96, 0x80
	s_addc_u32 s97, s97, 0
	ds_read_b128 v[82:85], v90 offset:0
	ds_read_b128 v[86:89], v90 offset:2048
	ds_read_b128 v[208:211], v90 offset:4096
	ds_read_b128 v[212:215], v90 offset:6144
	ds_read_b128 v[66:69], v207 offset:0
	ds_read_b128 v[70:73], v207 offset:2048
	v_mfma_f32_16x16x32_bf16 v[34:37], v[216:219], v[74:77], v[34:37]
	v_cvt_f32_ubyte0_e32 v248, v237
	v_cvt_f32_ubyte1_e32 v249, v237
	v_cvt_f32_ubyte2_e32 v250, v237
	v_cvt_f32_ubyte3_e32 v251, v237
	v_mul_f32_e32 v248, s34, v248
	v_mul_f32_e32 v249, s34, v249
	v_mul_f32_e32 v250, s34, v250
	v_mul_f32_e32 v251, s34, v251
	v_fma_f32 v164, v26, v248, v164
	v_fma_f32 v165, v27, v249, v165
	v_fma_f32 v166, v28, v250, v166
	v_fma_f32 v167, v29, v251, v167
	v_mfma_f32_16x16x32_bf16 v[22:25], v[220:223], v[74:77], v[22:25]
	v_cvt_f32_ubyte0_e32 v248, v238
	v_cvt_f32_ubyte1_e32 v249, v238
	v_cvt_f32_ubyte2_e32 v250, v238
	v_cvt_f32_ubyte3_e32 v251, v238
	v_mul_f32_e32 v248, s34, v248
	v_mul_f32_e32 v249, s34, v249
	v_mul_f32_e32 v250, s34, v250
	v_mul_f32_e32 v251, s34, v251
	v_fma_f32 v160, v14, v248, v160
	v_fma_f32 v161, v15, v249, v161
	v_fma_f32 v162, v16, v250, v162
	v_fma_f32 v163, v17, v251, v163
	v_mfma_f32_16x16x32_bf16 v[18:21], v[224:227], v[74:77], v[18:21]
	v_cvt_f32_ubyte0_e32 v248, v239
	v_cvt_f32_ubyte1_e32 v249, v239
	v_cvt_f32_ubyte2_e32 v250, v239
	v_cvt_f32_ubyte3_e32 v251, v239
	v_mul_f32_e32 v248, s34, v248
	v_mul_f32_e32 v249, s34, v249
	v_mul_f32_e32 v250, s34, v250
	v_mul_f32_e32 v251, s34, v251
	v_fma_f32 v156, v10, v248, v156
	v_fma_f32 v157, v11, v249, v157
	v_fma_f32 v158, v12, v250, v158
	v_fma_f32 v159, v13, v251, v159
	v_mfma_f32_16x16x32_bf16 v[62:65], v[228:231], v[74:77], v[62:65]
	v_cvt_f32_ubyte0_e32 v248, v240
	v_cvt_f32_ubyte1_e32 v249, v240
	v_cvt_f32_ubyte2_e32 v250, v240
	v_cvt_f32_ubyte3_e32 v251, v240
	v_mul_f32_e32 v248, s34, v248
	v_mul_f32_e32 v249, s34, v249
	v_mul_f32_e32 v250, s34, v250
	v_mul_f32_e32 v251, s34, v251
	v_fma_f32 v136, v34, v248, v136
	v_fma_f32 v137, v35, v249, v137
	v_fma_f32 v150, v36, v250, v150
	v_fma_f32 v151, v37, v251, v151
	ds_read_b128 v[74:77], v207 offset:4096
	v_mfma_f32_16x16x32_bf16 v[58:61], v[216:219], v[78:81], v[58:61]
	v_cvt_f32_ubyte0_e32 v248, v241
	v_cvt_f32_ubyte1_e32 v249, v241
	v_cvt_f32_ubyte2_e32 v250, v241
	v_cvt_f32_ubyte3_e32 v251, v241
	v_mul_f32_e32 v248, s34, v248
	v_mul_f32_e32 v249, s34, v249
	v_mul_f32_e32 v250, s34, v250
	v_mul_f32_e32 v251, s34, v251
	v_fma_f32 v130, v22, v248, v130
	v_fma_f32 v131, v23, v249, v131
	v_fma_f32 v134, v24, v250, v134
	v_fma_f32 v135, v25, v251, v135
	v_mfma_f32_16x16x32_bf16 v[54:57], v[220:223], v[78:81], v[54:57]
	v_cvt_f32_ubyte0_e32 v248, v242
	v_cvt_f32_ubyte1_e32 v249, v242
	v_cvt_f32_ubyte2_e32 v250, v242
	v_cvt_f32_ubyte3_e32 v251, v242
	v_mul_f32_e32 v248, s34, v248
	v_mul_f32_e32 v249, s34, v249
	v_mul_f32_e32 v250, s34, v250
	v_mul_f32_e32 v251, s34, v251
	v_fma_f32 v124, v18, v248, v124
	v_fma_f32 v125, v19, v249, v125
	v_fma_f32 v126, v20, v250, v126
	v_fma_f32 v127, v21, v251, v127
	v_mfma_f32_16x16x32_bf16 v[50:53], v[224:227], v[78:81], v[50:53]
	v_cvt_f32_ubyte0_e32 v248, v243
	v_cvt_f32_ubyte1_e32 v249, v243
	v_cvt_f32_ubyte2_e32 v250, v243
	v_cvt_f32_ubyte3_e32 v251, v243
	v_mul_f32_e32 v248, s34, v248
	v_mul_f32_e32 v249, s34, v249
	v_mul_f32_e32 v250, s34, v250
	v_mul_f32_e32 v251, s34, v251
	v_fma_f32 v120, v62, v248, v120
	v_fma_f32 v121, v63, v249, v121
	v_fma_f32 v122, v64, v250, v122
	v_fma_f32 v123, v65, v251, v123
	v_mfma_f32_16x16x32_bf16 v[2:5], v[228:231], v[78:81], v[2:5]
	v_cvt_f32_ubyte0_e32 v248, v244
	v_cvt_f32_ubyte1_e32 v249, v244
	v_cvt_f32_ubyte2_e32 v250, v244
	v_cvt_f32_ubyte3_e32 v251, v244
	v_mul_f32_e32 v248, s34, v248
	v_mul_f32_e32 v249, s34, v249
	v_mul_f32_e32 v250, s34, v250
	v_mul_f32_e32 v251, s34, v251
	v_fma_f32 v114, v58, v248, v114
	v_fma_f32 v115, v59, v249, v115
	v_fma_f32 v116, v60, v250, v116
	v_fma_f32 v117, v61, v251, v117
	ds_read_b128 v[78:81], v207 offset:6144
	s_nop 7
	s_nop 3
	v_cvt_f32_ubyte0_e32 v248, v245
	v_cvt_f32_ubyte1_e32 v249, v245
	v_cvt_f32_ubyte2_e32 v250, v245
	v_cvt_f32_ubyte3_e32 v251, v245
	v_mul_f32_e32 v248, s34, v248
	v_mul_f32_e32 v249, s34, v249
	v_mul_f32_e32 v250, s34, v250
	v_mul_f32_e32 v251, s34, v251
	v_fma_f32 v106, v54, v248, v106
	v_fma_f32 v107, v55, v249, v107
	v_fma_f32 v108, v56, v250, v108
	v_fma_f32 v109, v57, v251, v109
	v_cvt_f32_ubyte0_e32 v248, v246
	v_cvt_f32_ubyte1_e32 v249, v246
	v_cvt_f32_ubyte2_e32 v250, v246
	v_cvt_f32_ubyte3_e32 v251, v246
	v_mul_f32_e32 v248, s34, v248
	v_mul_f32_e32 v249, s34, v249
	v_mul_f32_e32 v250, s34, v250
	v_mul_f32_e32 v251, s34, v251
	v_fma_f32 v100, v50, v248, v100
	v_fma_f32 v101, v51, v249, v101
	v_fma_f32 v102, v52, v250, v102
	v_fma_f32 v103, v53, v251, v103
	v_cvt_f32_ubyte0_e32 v248, v247
	v_cvt_f32_ubyte1_e32 v249, v247
	v_cvt_f32_ubyte2_e32 v250, v247
	v_cvt_f32_ubyte3_e32 v251, v247
	v_mul_f32_e32 v248, s34, v248
	v_mul_f32_e32 v249, s34, v249
	v_mul_f32_e32 v250, s34, v250
	v_mul_f32_e32 v251, s34, v251
	v_fma_f32 v96, v2, v248, v96
	v_fma_f32 v97, v3, v249, v97
	v_fma_f32 v98, v4, v250, v98
	v_fma_f32 v99, v5, v251, v99
	ds_read_b128 v[216:219], v91 offset:0
	ds_read_b128 v[220:223], v91 offset:2048
	ds_read_b128 v[224:227], v91 offset:4096
	ds_read_b128 v[228:231], v91 offset:6144
	s_waitcnt lgkmcnt(7)
	v_mfma_f32_16x16x32_bf16 v[6:9], v[82:85], v[66:69], 0
	v_mfma_f32_16x16x32_bf16 v[30:33], v[86:89], v[66:69], 0
	v_mfma_f32_16x16x32_bf16 v[38:41], v[208:211], v[66:69], 0
	v_mfma_f32_16x16x32_bf16 v[42:45], v[212:215], v[66:69], 0
	ds_read_b128 v[66:69], v119 offset:0
	s_waitcnt lgkmcnt(7)
	v_mfma_f32_16x16x32_bf16 v[46:49], v[82:85], v[70:73], 0
	v_mfma_f32_16x16x32_bf16 v[26:29], v[86:89], v[70:73], 0
	v_mfma_f32_16x16x32_bf16 v[14:17], v[208:211], v[70:73], 0
	v_mfma_f32_16x16x32_bf16 v[10:13], v[212:215], v[70:73], 0
	ds_read_b128 v[70:73], v119 offset:2048
	s_waitcnt lgkmcnt(7)
	v_mfma_f32_16x16x32_bf16 v[34:37], v[82:85], v[74:77], 0
	v_mfma_f32_16x16x32_bf16 v[22:25], v[86:89], v[74:77], 0
	v_mfma_f32_16x16x32_bf16 v[18:21], v[208:211], v[74:77], 0
	v_mfma_f32_16x16x32_bf16 v[62:65], v[212:215], v[74:77], 0
	ds_read_b128 v[74:77], v119 offset:4096
	s_waitcnt lgkmcnt(7)
	v_mfma_f32_16x16x32_bf16 v[58:61], v[82:85], v[78:81], 0
	v_mfma_f32_16x16x32_bf16 v[54:57], v[86:89], v[78:81], 0
	v_mfma_f32_16x16x32_bf16 v[50:53], v[208:211], v[78:81], 0
	v_mfma_f32_16x16x32_bf16 v[2:5], v[212:215], v[78:81], 0
	ds_read_b128 v[78:81], v119 offset:6144
	s_waitcnt lgkmcnt(3)
	v_mfma_f32_16x16x32_bf16 v[6:9], v[216:219], v[66:69], v[6:9]
	v_mfma_f32_16x16x32_bf16 v[30:33], v[220:223], v[66:69], v[30:33]
	v_mfma_f32_16x16x32_bf16 v[38:41], v[224:227], v[66:69], v[38:41]
	v_mfma_f32_16x16x32_bf16 v[42:45], v[228:231], v[66:69], v[42:45]
	s_waitcnt lgkmcnt(2)
	v_mfma_f32_16x16x32_bf16 v[46:49], v[216:219], v[70:73], v[46:49]
	v_mfma_f32_16x16x32_bf16 v[26:29], v[220:223], v[70:73], v[26:29]
	v_mfma_f32_16x16x32_bf16 v[14:17], v[224:227], v[70:73], v[14:17]
	v_mfma_f32_16x16x32_bf16 v[10:13], v[228:231], v[70:73], v[10:13]
	s_waitcnt vmcnt(6)
	s_waitcnt lgkmcnt(0)
	s_barrier
	s_add_i32 m0, s67, 0x0
	s_nop 0
	global_load_lds_dwordx4 v188, s[80:81]
	s_add_i32 m0, s67, 0x2000
	s_nop 0
	global_load_lds_dwordx4 v189, s[80:81]
	s_add_i32 m0, s67, 0x4000
	s_nop 0
	global_load_lds_dwordx4 v190, s[80:81]
	s_add_i32 m0, s67, 0x6000
	s_nop 0
	global_load_lds_dwordx4 v191, s[80:81]
	s_add_i32 m0, s67, 0x18000
	s_nop 0
	global_load_lds_dwordx4 v205, s[96:97]
	s_add_i32 m0, s67, 0x1a000
	s_nop 0
	global_load_lds_dwordx4 v206, s[96:97]
	s_add_u32 s80, s80, 0x80
	s_addc_u32 s81, s81, 0
	s_add_u32 s96, s96, 0x80
	s_addc_u32 s97, s97, 0
	ds_read_b128 v[82:85], v90 offset:16384
	ds_read_b128 v[86:89], v90 offset:18432
	ds_read_b128 v[208:211], v90 offset:20480
	ds_read_b128 v[212:215], v90 offset:22528
	ds_read_b128 v[66:69], v207 offset:32768
	ds_read_b128 v[70:73], v207 offset:34816
	v_mfma_f32_16x16x32_bf16 v[34:37], v[216:219], v[74:77], v[34:37]
	v_mfma_f32_16x16x32_bf16 v[22:25], v[220:223], v[74:77], v[22:25]
	v_mfma_f32_16x16x32_bf16 v[18:21], v[224:227], v[74:77], v[18:21]
	v_mfma_f32_16x16x32_bf16 v[62:65], v[228:231], v[74:77], v[62:65]
	ds_read_b128 v[74:77], v207 offset:36864
	v_mfma_f32_16x16x32_bf16 v[58:61], v[216:219], v[78:81], v[58:61]
	v_mfma_f32_16x16x32_bf16 v[54:57], v[220:223], v[78:81], v[54:57]
	v_mfma_f32_16x16x32_bf16 v[50:53], v[224:227], v[78:81], v[50:53]
	v_mfma_f32_16x16x32_bf16 v[2:5], v[228:231], v[78:81], v[2:5]
	ds_read_b128 v[78:81], v207 offset:38912
	ds_read_b128 v[216:219], v91 offset:16384
	ds_read_b128 v[220:223], v91 offset:18432
	ds_read_b128 v[224:227], v91 offset:20480
	ds_read_b128 v[228:231], v91 offset:22528
	s_waitcnt lgkmcnt(7)
	v_mfma_f32_16x16x32_bf16 v[6:9], v[82:85], v[66:69], v[6:9]
	v_mfma_f32_16x16x32_bf16 v[30:33], v[86:89], v[66:69], v[30:33]
	v_mfma_f32_16x16x32_bf16 v[38:41], v[208:211], v[66:69], v[38:41]
	v_mfma_f32_16x16x32_bf16 v[42:45], v[212:215], v[66:69], v[42:45]
	ds_read_b128 v[66:69], v119 offset:32768
	s_waitcnt lgkmcnt(7)
	v_mfma_f32_16x16x32_bf16 v[46:49], v[82:85], v[70:73], v[46:49]
	v_mfma_f32_16x16x32_bf16 v[26:29], v[86:89], v[70:73], v[26:29]
	v_mfma_f32_16x16x32_bf16 v[14:17], v[208:211], v[70:73], v[14:17]
	v_mfma_f32_16x16x32_bf16 v[10:13], v[212:215], v[70:73], v[10:13]
	ds_read_b128 v[70:73], v119 offset:34816
	s_waitcnt lgkmcnt(7)
	v_mfma_f32_16x16x32_bf16 v[34:37], v[82:85], v[74:77], v[34:37]
	v_mfma_f32_16x16x32_bf16 v[22:25], v[86:89], v[74:77], v[22:25]
	v_mfma_f32_16x16x32_bf16 v[18:21], v[208:211], v[74:77], v[18:21]
	v_mfma_f32_16x16x32_bf16 v[62:65], v[212:215], v[74:77], v[62:65]
	ds_read_b128 v[74:77], v119 offset:36864
	s_waitcnt lgkmcnt(7)
	v_mfma_f32_16x16x32_bf16 v[58:61], v[82:85], v[78:81], v[58:61]
	v_mfma_f32_16x16x32_bf16 v[54:57], v[86:89], v[78:81], v[54:57]
	v_mfma_f32_16x16x32_bf16 v[50:53], v[208:211], v[78:81], v[50:53]
	v_mfma_f32_16x16x32_bf16 v[2:5], v[212:215], v[78:81], v[2:5]
	ds_read_b128 v[78:81], v119 offset:38912
	s_waitcnt lgkmcnt(3)
	v_mfma_f32_16x16x32_bf16 v[6:9], v[216:219], v[66:69], v[6:9]
	v_mfma_f32_16x16x32_bf16 v[30:33], v[220:223], v[66:69], v[30:33]
	v_mfma_f32_16x16x32_bf16 v[38:41], v[224:227], v[66:69], v[38:41]
	v_mfma_f32_16x16x32_bf16 v[42:45], v[228:231], v[66:69], v[42:45]
	s_waitcnt lgkmcnt(2)
	v_mfma_f32_16x16x32_bf16 v[46:49], v[216:219], v[70:73], v[46:49]
	v_mfma_f32_16x16x32_bf16 v[26:29], v[220:223], v[70:73], v[26:29]
	v_mfma_f32_16x16x32_bf16 v[14:17], v[224:227], v[70:73], v[14:17]
	v_mfma_f32_16x16x32_bf16 v[10:13], v[228:231], v[70:73], v[10:13]
	s_waitcnt vmcnt(6)
	s_waitcnt lgkmcnt(0)
	s_barrier
	s_add_i32 m0, s67, 0x8000
	s_nop 0
	global_load_lds_dwordx4 v188, s[80:81]
	s_add_i32 m0, s67, 0xa000
	s_nop 0
	global_load_lds_dwordx4 v189, s[80:81]
	s_add_i32 m0, s67, 0xc000
	s_nop 0
	global_load_lds_dwordx4 v190, s[80:81]
	s_add_i32 m0, s67, 0xe000
	s_nop 0
	global_load_lds_dwordx4 v191, s[80:81]
	s_add_i32 m0, s67, 0x1c000
	s_nop 0
	global_load_lds_dwordx4 v205, s[96:97]
	s_add_i32 m0, s67, 0x1e000
	s_nop 0
	global_load_lds_dwordx4 v206, s[96:97]
	s_add_u32 s80, s80, 0x80
	s_addc_u32 s81, s81, 0
	s_add_u32 s96, s96, 0x80
	s_addc_u32 s97, s97, 0
	ds_read_b128 v[82:85], v90 offset:33792
	ds_read_b128 v[86:89], v90 offset:35840
	ds_read_b128 v[208:211], v90 offset:37888
	ds_read_b128 v[212:215], v90 offset:39936
	ds_read_b128 v[66:69], v0 offset:0
	ds_read_b128 v[70:73], v0 offset:2048
	v_mfma_f32_16x16x32_bf16 v[34:37], v[216:219], v[74:77], v[34:37]
	v_mfma_f32_16x16x32_bf16 v[22:25], v[220:223], v[74:77], v[22:25]
	v_mfma_f32_16x16x32_bf16 v[18:21], v[224:227], v[74:77], v[18:21]
	v_mfma_f32_16x16x32_bf16 v[62:65], v[228:231], v[74:77], v[62:65]
	ds_read_b128 v[74:77], v0 offset:4096
	v_mfma_f32_16x16x32_bf16 v[58:61], v[216:219], v[78:81], v[58:61]
	v_mfma_f32_16x16x32_bf16 v[54:57], v[220:223], v[78:81], v[54:57]
	v_mfma_f32_16x16x32_bf16 v[50:53], v[224:227], v[78:81], v[50:53]
	v_mfma_f32_16x16x32_bf16 v[2:5], v[228:231], v[78:81], v[2:5]
	ds_read_b128 v[78:81], v0 offset:6144
	ds_read_b128 v[216:219], v91 offset:33792
	ds_read_b128 v[220:223], v91 offset:35840
	ds_read_b128 v[224:227], v91 offset:37888
	ds_read_b128 v[228:231], v91 offset:39936
	s_waitcnt lgkmcnt(7)
	v_mfma_f32_16x16x32_bf16 v[6:9], v[82:85], v[66:69], v[6:9]
	v_mfma_f32_16x16x32_bf16 v[30:33], v[86:89], v[66:69], v[30:33]
	v_mfma_f32_16x16x32_bf16 v[38:41], v[208:211], v[66:69], v[38:41]
	v_mfma_f32_16x16x32_bf16 v[42:45], v[212:215], v[66:69], v[42:45]
	ds_read_b128 v[66:69], v255 offset:0
	s_waitcnt lgkmcnt(7)
	v_mfma_f32_16x16x32_bf16 v[46:49], v[82:85], v[70:73], v[46:49]
	v_mfma_f32_16x16x32_bf16 v[26:29], v[86:89], v[70:73], v[26:29]
	v_mfma_f32_16x16x32_bf16 v[14:17], v[208:211], v[70:73], v[14:17]
	v_mfma_f32_16x16x32_bf16 v[10:13], v[212:215], v[70:73], v[10:13]
	ds_read_b128 v[70:73], v255 offset:2048
	s_waitcnt lgkmcnt(7)
	v_mfma_f32_16x16x32_bf16 v[34:37], v[82:85], v[74:77], v[34:37]
	v_mfma_f32_16x16x32_bf16 v[22:25], v[86:89], v[74:77], v[22:25]
	v_mfma_f32_16x16x32_bf16 v[18:21], v[208:211], v[74:77], v[18:21]
	v_mfma_f32_16x16x32_bf16 v[62:65], v[212:215], v[74:77], v[62:65]
	ds_read_b128 v[74:77], v255 offset:4096
	s_waitcnt lgkmcnt(7)
	v_mfma_f32_16x16x32_bf16 v[58:61], v[82:85], v[78:81], v[58:61]
	v_mfma_f32_16x16x32_bf16 v[54:57], v[86:89], v[78:81], v[54:57]
	v_mfma_f32_16x16x32_bf16 v[50:53], v[208:211], v[78:81], v[50:53]
	v_mfma_f32_16x16x32_bf16 v[2:5], v[212:215], v[78:81], v[2:5]
	ds_read_b128 v[78:81], v255 offset:6144
	s_waitcnt lgkmcnt(3)
	v_mfma_f32_16x16x32_bf16 v[6:9], v[216:219], v[66:69], v[6:9]
	v_mfma_f32_16x16x32_bf16 v[30:33], v[220:223], v[66:69], v[30:33]
	v_mfma_f32_16x16x32_bf16 v[38:41], v[224:227], v[66:69], v[38:41]
	v_mfma_f32_16x16x32_bf16 v[42:45], v[228:231], v[66:69], v[42:45]
	s_waitcnt lgkmcnt(2)
	v_mfma_f32_16x16x32_bf16 v[46:49], v[216:219], v[70:73], v[46:49]
	v_mfma_f32_16x16x32_bf16 v[26:29], v[220:223], v[70:73], v[26:29]
	v_mfma_f32_16x16x32_bf16 v[14:17], v[224:227], v[70:73], v[14:17]
	v_mfma_f32_16x16x32_bf16 v[10:13], v[228:231], v[70:73], v[10:13]
	s_waitcnt vmcnt(6)
	s_waitcnt lgkmcnt(0)
	s_barrier
	s_add_i32 m0, s67, 0x10000
	s_nop 0
	global_load_lds_dwordx4 v188, s[80:81]
	s_add_i32 m0, s67, 0x12000
	s_nop 0
	global_load_lds_dwordx4 v189, s[80:81]
	s_add_i32 m0, s67, 0x14000
	s_nop 0
	global_load_lds_dwordx4 v190, s[80:81]
	s_add_i32 m0, s67, 0x16000
	s_nop 0
	global_load_lds_dwordx4 v191, s[80:81]
	s_add_i32 m0, s67, 0x20400
	s_nop 0
	global_load_lds_dwordx4 v205, s[96:97]
	s_add_i32 m0, s67, 0x22400
	s_nop 0
	global_load_lds_dwordx4 v206, s[96:97]
	s_add_u32 s80, s80, 0x80
	s_addc_u32 s81, s81, 0
	s_add_u32 s96, s96, 0x80
	s_addc_u32 s97, s97, 0
	ds_read_b128 v[82:85], v90 offset:0
	ds_read_b128 v[86:89], v90 offset:2048
	ds_read_b128 v[208:211], v90 offset:4096
	ds_read_b128 v[212:215], v90 offset:6144
	ds_read_b128 v[66:69], v207 offset:0
	ds_read_b128 v[70:73], v207 offset:2048
	v_mfma_f32_16x16x32_bf16 v[34:37], v[216:219], v[74:77], v[34:37]
	v_mfma_f32_16x16x32_bf16 v[22:25], v[220:223], v[74:77], v[22:25]
	v_mfma_f32_16x16x32_bf16 v[18:21], v[224:227], v[74:77], v[18:21]
	v_mfma_f32_16x16x32_bf16 v[62:65], v[228:231], v[74:77], v[62:65]
	ds_read_b128 v[74:77], v207 offset:4096
	v_mfma_f32_16x16x32_bf16 v[58:61], v[216:219], v[78:81], v[58:61]
	v_mfma_f32_16x16x32_bf16 v[54:57], v[220:223], v[78:81], v[54:57]
	v_mfma_f32_16x16x32_bf16 v[50:53], v[224:227], v[78:81], v[50:53]
	v_mfma_f32_16x16x32_bf16 v[2:5], v[228:231], v[78:81], v[2:5]
	ds_read_b128 v[78:81], v207 offset:6144
	ds_read_b128 v[216:219], v91 offset:0
	ds_read_b128 v[220:223], v91 offset:2048
	ds_read_b128 v[224:227], v91 offset:4096
	ds_read_b128 v[228:231], v91 offset:6144
	s_waitcnt lgkmcnt(7)
	v_mfma_f32_16x16x32_bf16 v[6:9], v[82:85], v[66:69], v[6:9]
	v_mfma_f32_16x16x32_bf16 v[30:33], v[86:89], v[66:69], v[30:33]
	v_mfma_f32_16x16x32_bf16 v[38:41], v[208:211], v[66:69], v[38:41]
	v_mfma_f32_16x16x32_bf16 v[42:45], v[212:215], v[66:69], v[42:45]
	ds_read_b128 v[66:69], v119 offset:0
	s_waitcnt lgkmcnt(7)
	v_mfma_f32_16x16x32_bf16 v[46:49], v[82:85], v[70:73], v[46:49]
	v_mfma_f32_16x16x32_bf16 v[26:29], v[86:89], v[70:73], v[26:29]
	v_mfma_f32_16x16x32_bf16 v[14:17], v[208:211], v[70:73], v[14:17]
	v_mfma_f32_16x16x32_bf16 v[10:13], v[212:215], v[70:73], v[10:13]
	ds_read_b128 v[70:73], v119 offset:2048
	s_waitcnt lgkmcnt(7)
	v_mfma_f32_16x16x32_bf16 v[34:37], v[82:85], v[74:77], v[34:37]
	v_mfma_f32_16x16x32_bf16 v[22:25], v[86:89], v[74:77], v[22:25]
	v_mfma_f32_16x16x32_bf16 v[18:21], v[208:211], v[74:77], v[18:21]
	v_mfma_f32_16x16x32_bf16 v[62:65], v[212:215], v[74:77], v[62:65]
	ds_read_b128 v[74:77], v119 offset:4096
	s_waitcnt lgkmcnt(7)
	v_mfma_f32_16x16x32_bf16 v[58:61], v[82:85], v[78:81], v[58:61]
	v_mfma_f32_16x16x32_bf16 v[54:57], v[86:89], v[78:81], v[54:57]
	v_mfma_f32_16x16x32_bf16 v[50:53], v[208:211], v[78:81], v[50:53]
	v_mfma_f32_16x16x32_bf16 v[2:5], v[212:215], v[78:81], v[2:5]
	ds_read_b128 v[78:81], v119 offset:6144
	s_waitcnt lgkmcnt(3)
	v_mfma_f32_16x16x32_bf16 v[6:9], v[216:219], v[66:69], v[6:9]
	v_mfma_f32_16x16x32_bf16 v[30:33], v[220:223], v[66:69], v[30:33]
	v_mfma_f32_16x16x32_bf16 v[38:41], v[224:227], v[66:69], v[38:41]
	v_mfma_f32_16x16x32_bf16 v[42:45], v[228:231], v[66:69], v[42:45]
	s_waitcnt lgkmcnt(2)
	v_mfma_f32_16x16x32_bf16 v[46:49], v[216:219], v[70:73], v[46:49]
	v_mfma_f32_16x16x32_bf16 v[26:29], v[220:223], v[70:73], v[26:29]
	v_mfma_f32_16x16x32_bf16 v[14:17], v[224:227], v[70:73], v[14:17]
	v_mfma_f32_16x16x32_bf16 v[10:13], v[228:231], v[70:73], v[10:13]
	s_waitcnt vmcnt(6)
	s_waitcnt lgkmcnt(0)
	s_barrier
	s_add_i32 m0, s67, 0x0
	s_nop 0
	global_load_lds_dwordx4 v188, s[80:81]
	s_add_i32 m0, s67, 0x2000
	s_nop 0
	global_load_lds_dwordx4 v189, s[80:81]
	s_add_i32 m0, s67, 0x4000
	s_nop 0
	global_load_lds_dwordx4 v190, s[80:81]
	s_add_i32 m0, s67, 0x6000
	s_nop 0
	global_load_lds_dwordx4 v191, s[80:81]
	s_add_i32 m0, s67, 0x18000
	s_nop 0
	global_load_lds_dwordx4 v205, s[96:97]
	s_add_i32 m0, s67, 0x1a000
	s_nop 0
	global_load_lds_dwordx4 v206, s[96:97]
	s_add_u32 s80, s80, 0x80
	s_addc_u32 s81, s81, 0
	s_add_u32 s96, s96, 0x80
	s_addc_u32 s97, s97, 0
	s_movk_i32 s10, 0xc00
	s_mov_b32 s11, 0
	v_lshl_add_u64 v[248:249], v[128:129], 0, s[10:11]
	global_load_dwordx2 v[232:233], v[248:249], off
	global_load_dwordx2 v[234:235], v[248:249], off offset:32
	v_lshl_add_u64 v[248:249], v[132:133], 0, s[10:11]
	global_load_dwordx2 v[236:237], v[248:249], off
	global_load_dwordx2 v[238:239], v[248:249], off offset:32
	v_lshl_add_u64 v[248:249], v[152:153], 0, s[10:11]
	global_load_dwordx2 v[240:241], v[248:249], off
	global_load_dwordx2 v[242:243], v[248:249], off offset:32
	v_lshl_add_u64 v[248:249], v[154:155], 0, s[10:11]
	global_load_dwordx2 v[244:245], v[248:249], off
	global_load_dwordx2 v[246:247], v[248:249], off offset:32
	ds_read_b128 v[82:85], v90 offset:16384
	ds_read_b128 v[86:89], v90 offset:18432
	ds_read_b128 v[208:211], v90 offset:20480
	ds_read_b128 v[212:215], v90 offset:22528
	ds_read_b128 v[66:69], v207 offset:32768
	ds_read_b128 v[70:73], v207 offset:34816
	v_mfma_f32_16x16x32_bf16 v[34:37], v[216:219], v[74:77], v[34:37]
	v_mfma_f32_16x16x32_bf16 v[22:25], v[220:223], v[74:77], v[22:25]
	v_mfma_f32_16x16x32_bf16 v[18:21], v[224:227], v[74:77], v[18:21]
	v_mfma_f32_16x16x32_bf16 v[62:65], v[228:231], v[74:77], v[62:65]
	ds_read_b128 v[74:77], v207 offset:36864
	v_mfma_f32_16x16x32_bf16 v[58:61], v[216:219], v[78:81], v[58:61]
	v_mfma_f32_16x16x32_bf16 v[54:57], v[220:223], v[78:81], v[54:57]
	v_mfma_f32_16x16x32_bf16 v[50:53], v[224:227], v[78:81], v[50:53]
	v_mfma_f32_16x16x32_bf16 v[2:5], v[228:231], v[78:81], v[2:5]
	ds_read_b128 v[78:81], v207 offset:38912
	ds_read_b128 v[216:219], v91 offset:16384
	ds_read_b128 v[220:223], v91 offset:18432
	ds_read_b128 v[224:227], v91 offset:20480
	ds_read_b128 v[228:231], v91 offset:22528
	s_waitcnt lgkmcnt(7)
	v_mfma_f32_16x16x32_bf16 v[6:9], v[82:85], v[66:69], v[6:9]
	v_mfma_f32_16x16x32_bf16 v[30:33], v[86:89], v[66:69], v[30:33]
	v_mfma_f32_16x16x32_bf16 v[38:41], v[208:211], v[66:69], v[38:41]
	v_mfma_f32_16x16x32_bf16 v[42:45], v[212:215], v[66:69], v[42:45]
	ds_read_b128 v[66:69], v119 offset:32768
	s_waitcnt lgkmcnt(7)
	v_mfma_f32_16x16x32_bf16 v[46:49], v[82:85], v[70:73], v[46:49]
	v_mfma_f32_16x16x32_bf16 v[26:29], v[86:89], v[70:73], v[26:29]
	v_mfma_f32_16x16x32_bf16 v[14:17], v[208:211], v[70:73], v[14:17]
	v_mfma_f32_16x16x32_bf16 v[10:13], v[212:215], v[70:73], v[10:13]
	ds_read_b128 v[70:73], v119 offset:34816
	s_waitcnt lgkmcnt(7)
	v_mfma_f32_16x16x32_bf16 v[34:37], v[82:85], v[74:77], v[34:37]
	v_mfma_f32_16x16x32_bf16 v[22:25], v[86:89], v[74:77], v[22:25]
	v_mfma_f32_16x16x32_bf16 v[18:21], v[208:211], v[74:77], v[18:21]
	v_mfma_f32_16x16x32_bf16 v[62:65], v[212:215], v[74:77], v[62:65]
	ds_read_b128 v[74:77], v119 offset:36864
	s_waitcnt lgkmcnt(7)
	v_mfma_f32_16x16x32_bf16 v[58:61], v[82:85], v[78:81], v[58:61]
	v_mfma_f32_16x16x32_bf16 v[54:57], v[86:89], v[78:81], v[54:57]
	v_mfma_f32_16x16x32_bf16 v[50:53], v[208:211], v[78:81], v[50:53]
	v_mfma_f32_16x16x32_bf16 v[2:5], v[212:215], v[78:81], v[2:5]
	ds_read_b128 v[78:81], v119 offset:38912
	s_waitcnt lgkmcnt(3)
	v_mfma_f32_16x16x32_bf16 v[6:9], v[216:219], v[66:69], v[6:9]
	v_mfma_f32_16x16x32_bf16 v[30:33], v[220:223], v[66:69], v[30:33]
	v_mfma_f32_16x16x32_bf16 v[38:41], v[224:227], v[66:69], v[38:41]
	v_mfma_f32_16x16x32_bf16 v[42:45], v[228:231], v[66:69], v[42:45]
	s_waitcnt lgkmcnt(2)
	v_mfma_f32_16x16x32_bf16 v[46:49], v[216:219], v[70:73], v[46:49]
	v_mfma_f32_16x16x32_bf16 v[26:29], v[220:223], v[70:73], v[26:29]
	v_mfma_f32_16x16x32_bf16 v[14:17], v[224:227], v[70:73], v[14:17]
	v_mfma_f32_16x16x32_bf16 v[10:13], v[228:231], v[70:73], v[10:13]
	s_waitcnt vmcnt(14)
	s_waitcnt lgkmcnt(0)
	s_barrier
	s_add_i32 m0, s67, 0x8000
	s_nop 0
	global_load_lds_dwordx4 v188, s[80:81]
	s_add_i32 m0, s67, 0xa000
	s_nop 0
	global_load_lds_dwordx4 v189, s[80:81]
	s_add_i32 m0, s67, 0xc000
	s_nop 0
	global_load_lds_dwordx4 v190, s[80:81]
	s_add_i32 m0, s67, 0xe000
	s_nop 0
	global_load_lds_dwordx4 v191, s[80:81]
	s_add_i32 m0, s67, 0x1c000
	s_nop 0
	global_load_lds_dwordx4 v205, s[96:97]
	s_add_i32 m0, s67, 0x1e000
	s_nop 0
	global_load_lds_dwordx4 v206, s[96:97]
	ds_read_b128 v[82:85], v90 offset:33792
	ds_read_b128 v[86:89], v90 offset:35840
	ds_read_b128 v[208:211], v90 offset:37888
	ds_read_b128 v[212:215], v90 offset:39936
	ds_read_b128 v[66:69], v0 offset:0
	ds_read_b128 v[70:73], v0 offset:2048
	v_mfma_f32_16x16x32_bf16 v[34:37], v[216:219], v[74:77], v[34:37]
	v_mfma_f32_16x16x32_bf16 v[22:25], v[220:223], v[74:77], v[22:25]
	v_mfma_f32_16x16x32_bf16 v[18:21], v[224:227], v[74:77], v[18:21]
	v_mfma_f32_16x16x32_bf16 v[62:65], v[228:231], v[74:77], v[62:65]
	ds_read_b128 v[74:77], v0 offset:4096
	v_mfma_f32_16x16x32_bf16 v[58:61], v[216:219], v[78:81], v[58:61]
	v_mfma_f32_16x16x32_bf16 v[54:57], v[220:223], v[78:81], v[54:57]
	v_mfma_f32_16x16x32_bf16 v[50:53], v[224:227], v[78:81], v[50:53]
	v_mfma_f32_16x16x32_bf16 v[2:5], v[228:231], v[78:81], v[2:5]
	ds_read_b128 v[78:81], v0 offset:6144
	ds_read_b128 v[216:219], v91 offset:33792
	ds_read_b128 v[220:223], v91 offset:35840
	ds_read_b128 v[224:227], v91 offset:37888
	ds_read_b128 v[228:231], v91 offset:39936
	s_waitcnt lgkmcnt(7)
	v_mfma_f32_16x16x32_bf16 v[6:9], v[82:85], v[66:69], v[6:9]
	v_mfma_f32_16x16x32_bf16 v[30:33], v[86:89], v[66:69], v[30:33]
	v_mfma_f32_16x16x32_bf16 v[38:41], v[208:211], v[66:69], v[38:41]
	v_mfma_f32_16x16x32_bf16 v[42:45], v[212:215], v[66:69], v[42:45]
	ds_read_b128 v[66:69], v255 offset:0
	s_waitcnt lgkmcnt(7)
	v_mfma_f32_16x16x32_bf16 v[46:49], v[82:85], v[70:73], v[46:49]
	v_mfma_f32_16x16x32_bf16 v[26:29], v[86:89], v[70:73], v[26:29]
	v_mfma_f32_16x16x32_bf16 v[14:17], v[208:211], v[70:73], v[14:17]
	v_mfma_f32_16x16x32_bf16 v[10:13], v[212:215], v[70:73], v[10:13]
	ds_read_b128 v[70:73], v255 offset:2048
	s_waitcnt lgkmcnt(7)
	v_mfma_f32_16x16x32_bf16 v[34:37], v[82:85], v[74:77], v[34:37]
	v_mfma_f32_16x16x32_bf16 v[22:25], v[86:89], v[74:77], v[22:25]
	v_mfma_f32_16x16x32_bf16 v[18:21], v[208:211], v[74:77], v[18:21]
	v_mfma_f32_16x16x32_bf16 v[62:65], v[212:215], v[74:77], v[62:65]
	ds_read_b128 v[74:77], v255 offset:4096
	s_waitcnt lgkmcnt(7)
	v_mfma_f32_16x16x32_bf16 v[58:61], v[82:85], v[78:81], v[58:61]
	v_mfma_f32_16x16x32_bf16 v[54:57], v[86:89], v[78:81], v[54:57]
	v_mfma_f32_16x16x32_bf16 v[50:53], v[208:211], v[78:81], v[50:53]
	v_mfma_f32_16x16x32_bf16 v[2:5], v[212:215], v[78:81], v[2:5]
	ds_read_b128 v[78:81], v255 offset:6144
	s_waitcnt lgkmcnt(3)
	v_mfma_f32_16x16x32_bf16 v[6:9], v[216:219], v[66:69], v[6:9]
	v_mfma_f32_16x16x32_bf16 v[30:33], v[220:223], v[66:69], v[30:33]
	v_mfma_f32_16x16x32_bf16 v[38:41], v[224:227], v[66:69], v[38:41]
	v_mfma_f32_16x16x32_bf16 v[42:45], v[228:231], v[66:69], v[42:45]
	s_waitcnt lgkmcnt(2)
	v_mfma_f32_16x16x32_bf16 v[46:49], v[216:219], v[70:73], v[46:49]
	v_mfma_f32_16x16x32_bf16 v[26:29], v[220:223], v[70:73], v[26:29]
	v_mfma_f32_16x16x32_bf16 v[14:17], v[224:227], v[70:73], v[14:17]
	v_mfma_f32_16x16x32_bf16 v[10:13], v[228:231], v[70:73], v[10:13]
	s_waitcnt vmcnt(14)
	s_waitcnt lgkmcnt(0)
	s_barrier
	ds_read_b128 v[82:85], v90 offset:0
	ds_read_b128 v[86:89], v90 offset:2048
	ds_read_b128 v[208:211], v90 offset:4096
	ds_read_b128 v[212:215], v90 offset:6144
	ds_read_b128 v[66:69], v207 offset:0
	ds_read_b128 v[70:73], v207 offset:2048
	v_mfma_f32_16x16x32_bf16 v[34:37], v[216:219], v[74:77], v[34:37]
	v_mfma_f32_16x16x32_bf16 v[22:25], v[220:223], v[74:77], v[22:25]
	v_mfma_f32_16x16x32_bf16 v[18:21], v[224:227], v[74:77], v[18:21]
	v_mfma_f32_16x16x32_bf16 v[62:65], v[228:231], v[74:77], v[62:65]
	ds_read_b128 v[74:77], v207 offset:4096
	v_mfma_f32_16x16x32_bf16 v[58:61], v[216:219], v[78:81], v[58:61]
	v_mfma_f32_16x16x32_bf16 v[54:57], v[220:223], v[78:81], v[54:57]
	v_mfma_f32_16x16x32_bf16 v[50:53], v[224:227], v[78:81], v[50:53]
	v_mfma_f32_16x16x32_bf16 v[2:5], v[228:231], v[78:81], v[2:5]
	ds_read_b128 v[78:81], v207 offset:6144
	ds_read_b128 v[216:219], v91 offset:0
	ds_read_b128 v[220:223], v91 offset:2048
	ds_read_b128 v[224:227], v91 offset:4096
	ds_read_b128 v[228:231], v91 offset:6144
	s_waitcnt lgkmcnt(7)
	v_mfma_f32_16x16x32_bf16 v[6:9], v[82:85], v[66:69], v[6:9]
	v_mfma_f32_16x16x32_bf16 v[30:33], v[86:89], v[66:69], v[30:33]
	v_mfma_f32_16x16x32_bf16 v[38:41], v[208:211], v[66:69], v[38:41]
	v_mfma_f32_16x16x32_bf16 v[42:45], v[212:215], v[66:69], v[42:45]
	ds_read_b128 v[66:69], v119 offset:0
	s_waitcnt lgkmcnt(7)
	v_mfma_f32_16x16x32_bf16 v[46:49], v[82:85], v[70:73], v[46:49]
	v_mfma_f32_16x16x32_bf16 v[26:29], v[86:89], v[70:73], v[26:29]
	v_mfma_f32_16x16x32_bf16 v[14:17], v[208:211], v[70:73], v[14:17]
	v_mfma_f32_16x16x32_bf16 v[10:13], v[212:215], v[70:73], v[10:13]
	ds_read_b128 v[70:73], v119 offset:2048
	s_waitcnt lgkmcnt(7)
	v_mfma_f32_16x16x32_bf16 v[34:37], v[82:85], v[74:77], v[34:37]
	v_mfma_f32_16x16x32_bf16 v[22:25], v[86:89], v[74:77], v[22:25]
	v_mfma_f32_16x16x32_bf16 v[18:21], v[208:211], v[74:77], v[18:21]
	v_mfma_f32_16x16x32_bf16 v[62:65], v[212:215], v[74:77], v[62:65]
	ds_read_b128 v[74:77], v119 offset:4096
	s_waitcnt lgkmcnt(7)
	v_mfma_f32_16x16x32_bf16 v[58:61], v[82:85], v[78:81], v[58:61]
	v_mfma_f32_16x16x32_bf16 v[54:57], v[86:89], v[78:81], v[54:57]
	v_mfma_f32_16x16x32_bf16 v[50:53], v[208:211], v[78:81], v[50:53]
	v_mfma_f32_16x16x32_bf16 v[2:5], v[212:215], v[78:81], v[2:5]
	ds_read_b128 v[78:81], v119 offset:6144
	s_waitcnt lgkmcnt(3)
	v_mfma_f32_16x16x32_bf16 v[6:9], v[216:219], v[66:69], v[6:9]
	v_mfma_f32_16x16x32_bf16 v[30:33], v[220:223], v[66:69], v[30:33]
	v_mfma_f32_16x16x32_bf16 v[38:41], v[224:227], v[66:69], v[38:41]
	v_mfma_f32_16x16x32_bf16 v[42:45], v[228:231], v[66:69], v[42:45]
	s_waitcnt lgkmcnt(2)
	v_mfma_f32_16x16x32_bf16 v[46:49], v[216:219], v[70:73], v[46:49]
	v_mfma_f32_16x16x32_bf16 v[26:29], v[220:223], v[70:73], v[26:29]
	v_mfma_f32_16x16x32_bf16 v[14:17], v[224:227], v[70:73], v[14:17]
	v_mfma_f32_16x16x32_bf16 v[10:13], v[228:231], v[70:73], v[10:13]
	s_waitcnt vmcnt(0)
	s_waitcnt lgkmcnt(0)
	s_barrier
	ds_read_b128 v[82:85], v90 offset:16384
	ds_read_b128 v[86:89], v90 offset:18432
	ds_read_b128 v[208:211], v90 offset:20480
	ds_read_b128 v[212:215], v90 offset:22528
	ds_read_b128 v[66:69], v207 offset:32768
	ds_read_b128 v[70:73], v207 offset:34816
	v_mfma_f32_16x16x32_bf16 v[34:37], v[216:219], v[74:77], v[34:37]
	v_mfma_f32_16x16x32_bf16 v[22:25], v[220:223], v[74:77], v[22:25]
	v_mfma_f32_16x16x32_bf16 v[18:21], v[224:227], v[74:77], v[18:21]
	v_mfma_f32_16x16x32_bf16 v[62:65], v[228:231], v[74:77], v[62:65]
	ds_read_b128 v[74:77], v207 offset:36864
	v_mfma_f32_16x16x32_bf16 v[58:61], v[216:219], v[78:81], v[58:61]
	v_mfma_f32_16x16x32_bf16 v[54:57], v[220:223], v[78:81], v[54:57]
	v_mfma_f32_16x16x32_bf16 v[50:53], v[224:227], v[78:81], v[50:53]
	v_mfma_f32_16x16x32_bf16 v[2:5], v[228:231], v[78:81], v[2:5]
	ds_read_b128 v[78:81], v207 offset:38912
	ds_read_b128 v[216:219], v91 offset:16384
	ds_read_b128 v[220:223], v91 offset:18432
	ds_read_b128 v[224:227], v91 offset:20480
	ds_read_b128 v[228:231], v91 offset:22528
	s_waitcnt lgkmcnt(7)
	v_mfma_f32_16x16x32_bf16 v[6:9], v[82:85], v[66:69], v[6:9]
	v_mfma_f32_16x16x32_bf16 v[30:33], v[86:89], v[66:69], v[30:33]
	v_mfma_f32_16x16x32_bf16 v[38:41], v[208:211], v[66:69], v[38:41]
	v_mfma_f32_16x16x32_bf16 v[42:45], v[212:215], v[66:69], v[42:45]
	ds_read_b128 v[66:69], v119 offset:32768
	s_waitcnt lgkmcnt(7)
	v_mfma_f32_16x16x32_bf16 v[46:49], v[82:85], v[70:73], v[46:49]
	v_mfma_f32_16x16x32_bf16 v[26:29], v[86:89], v[70:73], v[26:29]
	v_mfma_f32_16x16x32_bf16 v[14:17], v[208:211], v[70:73], v[14:17]
	v_mfma_f32_16x16x32_bf16 v[10:13], v[212:215], v[70:73], v[10:13]
	ds_read_b128 v[70:73], v119 offset:34816
	s_waitcnt lgkmcnt(7)
	v_mfma_f32_16x16x32_bf16 v[34:37], v[82:85], v[74:77], v[34:37]
	v_mfma_f32_16x16x32_bf16 v[22:25], v[86:89], v[74:77], v[22:25]
	v_mfma_f32_16x16x32_bf16 v[18:21], v[208:211], v[74:77], v[18:21]
	v_mfma_f32_16x16x32_bf16 v[62:65], v[212:215], v[74:77], v[62:65]
	ds_read_b128 v[74:77], v119 offset:36864
	s_waitcnt lgkmcnt(7)
	v_mfma_f32_16x16x32_bf16 v[58:61], v[82:85], v[78:81], v[58:61]
	v_mfma_f32_16x16x32_bf16 v[54:57], v[86:89], v[78:81], v[54:57]
	v_mfma_f32_16x16x32_bf16 v[50:53], v[208:211], v[78:81], v[50:53]
	v_mfma_f32_16x16x32_bf16 v[2:5], v[212:215], v[78:81], v[2:5]
	ds_read_b128 v[78:81], v119 offset:38912
	s_waitcnt lgkmcnt(3)
	v_mfma_f32_16x16x32_bf16 v[6:9], v[216:219], v[66:69], v[6:9]
	s_waitcnt vmcnt(6)
	v_mfma_f32_16x16x32_bf16 v[30:33], v[220:223], v[66:69], v[30:33]
	v_mfma_f32_16x16x32_bf16 v[38:41], v[224:227], v[66:69], v[38:41]
	v_mfma_f32_16x16x32_bf16 v[42:45], v[228:231], v[66:69], v[42:45]
	v_cvt_f32_ubyte0_e32 v248, v232
	v_cvt_f32_ubyte1_e32 v249, v232
	v_cvt_f32_ubyte2_e32 v250, v232
	v_cvt_f32_ubyte3_e32 v251, v232
	v_mul_f32_e32 v248, s34, v248
	v_mul_f32_e32 v249, s34, v249
	v_mul_f32_e32 v250, s34, v250
	v_mul_f32_e32 v251, s34, v251
	v_fma_f32 v184, v6, v248, v184
	v_fma_f32 v185, v7, v249, v185
	v_fma_f32 v186, v8, v250, v186
	v_fma_f32 v187, v9, v251, v187
	s_waitcnt lgkmcnt(2)
	v_mfma_f32_16x16x32_bf16 v[46:49], v[216:219], v[70:73], v[46:49]
	v_cvt_f32_ubyte0_e32 v248, v233
	v_cvt_f32_ubyte1_e32 v249, v233
	v_cvt_f32_ubyte2_e32 v250, v233
	v_cvt_f32_ubyte3_e32 v251, v233
	v_mul_f32_e32 v248, s34, v248
	v_mul_f32_e32 v249, s34, v249
	v_mul_f32_e32 v250, s34, v250
	v_mul_f32_e32 v251, s34, v251
	v_fma_f32 v180, v30, v248, v180
	v_fma_f32 v181, v31, v249, v181
	v_fma_f32 v182, v32, v250, v182
	v_fma_f32 v183, v33, v251, v183
	v_mfma_f32_16x16x32_bf16 v[26:29], v[220:223], v[70:73], v[26:29]
	v_cvt_f32_ubyte0_e32 v248, v234
	v_cvt_f32_ubyte1_e32 v249, v234
	v_cvt_f32_ubyte2_e32 v250, v234
	v_cvt_f32_ubyte3_e32 v251, v234
	v_mul_f32_e32 v248, s34, v248
	v_mul_f32_e32 v249, s34, v249
	v_mul_f32_e32 v250, s34, v250
	v_mul_f32_e32 v251, s34, v251
	v_fma_f32 v176, v38, v248, v176
	v_fma_f32 v177, v39, v249, v177
	v_fma_f32 v178, v40, v250, v178
	v_fma_f32 v179, v41, v251, v179
	v_mfma_f32_16x16x32_bf16 v[14:17], v[224:227], v[70:73], v[14:17]
	v_cvt_f32_ubyte0_e32 v248, v235
	v_cvt_f32_ubyte1_e32 v249, v235
	v_cvt_f32_ubyte2_e32 v250, v235
	v_cvt_f32_ubyte3_e32 v251, v235
	v_mul_f32_e32 v248, s34, v248
	v_mul_f32_e32 v249, s34, v249
	v_mul_f32_e32 v250, s34, v250
	v_mul_f32_e32 v251, s34, v251
	v_fma_f32 v172, v42, v248, v172
	v_fma_f32 v173, v43, v249, v173
	v_fma_f32 v174, v44, v250, v174
	v_fma_f32 v175, v45, v251, v175
	v_mfma_f32_16x16x32_bf16 v[10:13], v[228:231], v[70:73], v[10:13]
	v_cvt_f32_ubyte0_e32 v248, v236
	v_cvt_f32_ubyte1_e32 v249, v236
	v_cvt_f32_ubyte2_e32 v250, v236
	v_cvt_f32_ubyte3_e32 v251, v236
	v_mul_f32_e32 v248, s34, v248
	v_mul_f32_e32 v249, s34, v249
	v_mul_f32_e32 v250, s34, v250
	v_mul_f32_e32 v251, s34, v251
	v_fma_f32 v168, v46, v248, v168
	v_fma_f32 v169, v47, v249, v169
	v_fma_f32 v170, v48, v250, v170
	v_fma_f32 v171, v49, v251, v171
	s_waitcnt lgkmcnt(0)
	s_barrier
	v_mfma_f32_16x16x32_bf16 v[34:37], v[216:219], v[74:77], v[34:37]
	v_cvt_f32_ubyte0_e32 v248, v237
	v_cvt_f32_ubyte1_e32 v249, v237
	v_cvt_f32_ubyte2_e32 v250, v237
	v_cvt_f32_ubyte3_e32 v251, v237
	v_mul_f32_e32 v248, s34, v248
	v_mul_f32_e32 v249, s34, v249
	v_mul_f32_e32 v250, s34, v250
	v_mul_f32_e32 v251, s34, v251
	v_fma_f32 v164, v26, v248, v164
	v_fma_f32 v165, v27, v249, v165
	v_fma_f32 v166, v28, v250, v166
	v_fma_f32 v167, v29, v251, v167
	v_mfma_f32_16x16x32_bf16 v[22:25], v[220:223], v[74:77], v[22:25]
	v_cvt_f32_ubyte0_e32 v248, v238
	v_cvt_f32_ubyte1_e32 v249, v238
	v_cvt_f32_ubyte2_e32 v250, v238
	v_cvt_f32_ubyte3_e32 v251, v238
	v_mul_f32_e32 v248, s34, v248
	v_mul_f32_e32 v249, s34, v249
	v_mul_f32_e32 v250, s34, v250
	v_mul_f32_e32 v251, s34, v251
	v_fma_f32 v160, v14, v248, v160
	v_fma_f32 v161, v15, v249, v161
	v_fma_f32 v162, v16, v250, v162
	v_fma_f32 v163, v17, v251, v163
	v_mfma_f32_16x16x32_bf16 v[18:21], v[224:227], v[74:77], v[18:21]
	v_cvt_f32_ubyte0_e32 v248, v239
	v_cvt_f32_ubyte1_e32 v249, v239
	v_cvt_f32_ubyte2_e32 v250, v239
	v_cvt_f32_ubyte3_e32 v251, v239
	v_mul_f32_e32 v248, s34, v248
	v_mul_f32_e32 v249, s34, v249
	v_mul_f32_e32 v250, s34, v250
	v_mul_f32_e32 v251, s34, v251
	v_fma_f32 v156, v10, v248, v156
	v_fma_f32 v157, v11, v249, v157
	v_fma_f32 v158, v12, v250, v158
	v_fma_f32 v159, v13, v251, v159
	v_mfma_f32_16x16x32_bf16 v[62:65], v[228:231], v[74:77], v[62:65]
	v_cvt_f32_ubyte0_e32 v248, v240
	v_cvt_f32_ubyte1_e32 v249, v240
	v_cvt_f32_ubyte2_e32 v250, v240
	v_cvt_f32_ubyte3_e32 v251, v240
	v_mul_f32_e32 v248, s34, v248
	v_mul_f32_e32 v249, s34, v249
	v_mul_f32_e32 v250, s34, v250
	v_mul_f32_e32 v251, s34, v251
	v_fma_f32 v136, v34, v248, v136
	v_fma_f32 v137, v35, v249, v137
	v_fma_f32 v150, v36, v250, v150
	v_fma_f32 v151, v37, v251, v151
	v_mfma_f32_16x16x32_bf16 v[58:61], v[216:219], v[78:81], v[58:61]
	v_cvt_f32_ubyte0_e32 v248, v241
	v_cvt_f32_ubyte1_e32 v249, v241
	v_cvt_f32_ubyte2_e32 v250, v241
	v_cvt_f32_ubyte3_e32 v251, v241
	v_mul_f32_e32 v248, s34, v248
	v_mul_f32_e32 v249, s34, v249
	v_mul_f32_e32 v250, s34, v250
	v_mul_f32_e32 v251, s34, v251
	v_fma_f32 v130, v22, v248, v130
	v_fma_f32 v131, v23, v249, v131
	v_fma_f32 v134, v24, v250, v134
	v_fma_f32 v135, v25, v251, v135
	v_mfma_f32_16x16x32_bf16 v[54:57], v[220:223], v[78:81], v[54:57]
	v_cvt_f32_ubyte0_e32 v248, v242
	v_cvt_f32_ubyte1_e32 v249, v242
	v_cvt_f32_ubyte2_e32 v250, v242
	v_cvt_f32_ubyte3_e32 v251, v242
	v_mul_f32_e32 v248, s34, v248
	v_mul_f32_e32 v249, s34, v249
	v_mul_f32_e32 v250, s34, v250
	v_mul_f32_e32 v251, s34, v251
	v_fma_f32 v124, v18, v248, v124
	v_fma_f32 v125, v19, v249, v125
	v_fma_f32 v126, v20, v250, v126
	v_fma_f32 v127, v21, v251, v127
	v_mfma_f32_16x16x32_bf16 v[50:53], v[224:227], v[78:81], v[50:53]
	v_cvt_f32_ubyte0_e32 v248, v243
	v_cvt_f32_ubyte1_e32 v249, v243
	v_cvt_f32_ubyte2_e32 v250, v243
	v_cvt_f32_ubyte3_e32 v251, v243
	v_mul_f32_e32 v248, s34, v248
	v_mul_f32_e32 v249, s34, v249
	v_mul_f32_e32 v250, s34, v250
	v_mul_f32_e32 v251, s34, v251
	v_fma_f32 v120, v62, v248, v120
	v_fma_f32 v121, v63, v249, v121
	v_fma_f32 v122, v64, v250, v122
	v_fma_f32 v123, v65, v251, v123
	v_mfma_f32_16x16x32_bf16 v[2:5], v[228:231], v[78:81], v[2:5]
	v_cvt_f32_ubyte0_e32 v248, v244
	v_cvt_f32_ubyte1_e32 v249, v244
	v_cvt_f32_ubyte2_e32 v250, v244
	v_cvt_f32_ubyte3_e32 v251, v244
	v_mul_f32_e32 v248, s34, v248
	v_mul_f32_e32 v249, s34, v249
	v_mul_f32_e32 v250, s34, v250
	v_mul_f32_e32 v251, s34, v251
	v_fma_f32 v114, v58, v248, v114
	v_fma_f32 v115, v59, v249, v115
	v_fma_f32 v116, v60, v250, v116
	v_fma_f32 v117, v61, v251, v117
	s_nop 7
	s_nop 3
	v_cvt_f32_ubyte0_e32 v248, v245
	v_cvt_f32_ubyte1_e32 v249, v245
	v_cvt_f32_ubyte2_e32 v250, v245
	v_cvt_f32_ubyte3_e32 v251, v245
	v_mul_f32_e32 v248, s34, v248
	v_mul_f32_e32 v249, s34, v249
	v_mul_f32_e32 v250, s34, v250
	v_mul_f32_e32 v251, s34, v251
	v_fma_f32 v106, v54, v248, v106
	v_fma_f32 v107, v55, v249, v107
	v_fma_f32 v108, v56, v250, v108
	v_fma_f32 v109, v57, v251, v109
	v_cvt_f32_ubyte0_e32 v248, v246
	v_cvt_f32_ubyte1_e32 v249, v246
	v_cvt_f32_ubyte2_e32 v250, v246
	v_cvt_f32_ubyte3_e32 v251, v246
	v_mul_f32_e32 v248, s34, v248
	v_mul_f32_e32 v249, s34, v249
	v_mul_f32_e32 v250, s34, v250
	v_mul_f32_e32 v251, s34, v251
	v_fma_f32 v100, v50, v248, v100
	v_fma_f32 v101, v51, v249, v101
	v_fma_f32 v102, v52, v250, v102
	v_fma_f32 v103, v53, v251, v103
	v_cvt_f32_ubyte0_e32 v248, v247
	v_cvt_f32_ubyte1_e32 v249, v247
	v_cvt_f32_ubyte2_e32 v250, v247
	v_cvt_f32_ubyte3_e32 v251, v247
	v_mul_f32_e32 v248, s34, v248
	v_mul_f32_e32 v249, s34, v249
	v_mul_f32_e32 v250, s34, v250
	v_mul_f32_e32 v251, s34, v251
	v_fma_f32 v96, v2, v248, v96
	v_fma_f32 v97, v3, v249, v97
	v_fma_f32 v98, v4, v250, v98
	v_fma_f32 v99, v5, v251, v99
	s_cmp_eq_u32 0, 0
	s_cbranch_scc0 .LBB0_1004
	v_lshlrev_b32_e32 v0, 1, v118
	v_lshl_add_u64 v[6:7], s[4:5], 0, v[0:1]
	v_lshlrev_b64 v[2:3], 11, v[112:113]
	v_lshl_add_u64 v[8:9], v[6:7], 0, v[2:3]
	v_cvt_pk_bf16_f32 v2, v184, v185
	v_cvt_pk_bf16_f32 v3, v186, v187
	v_cvt_pk_bf16_f32 v4, v180, v181
	v_cvt_pk_bf16_f32 v5, v182, v183
	global_store_dwordx4 v[8:9], v[2:5], off
	v_readlane_b32 s46, v254, 29
	s_mov_b32 s38, 0
	v_cvt_pk_bf16_f32 v2, v176, v177
	v_cvt_pk_bf16_f32 v3, v178, v179
	v_cvt_pk_bf16_f32 v4, v172, v173
	v_cvt_pk_bf16_f32 v5, v174, v175
	global_store_dwordx4 v[8:9], v[2:5], off offset:64
	v_readlane_b32 s47, v254, 30
	s_nop 0
	v_lshlrev_b64 v[2:3], 11, v[110:111]
	v_lshl_add_u64 v[8:9], v[6:7], 0, v[2:3]
	v_cvt_pk_bf16_f32 v2, v168, v169
	v_cvt_pk_bf16_f32 v3, v170, v171
	v_cvt_pk_bf16_f32 v4, v164, v165
	v_cvt_pk_bf16_f32 v5, v166, v167
	global_store_dwordx4 v[8:9], v[2:5], off
	s_nop 1
	v_cvt_pk_bf16_f32 v2, v160, v161
	v_cvt_pk_bf16_f32 v3, v162, v163
	v_cvt_pk_bf16_f32 v4, v156, v157
	v_cvt_pk_bf16_f32 v5, v158, v159
	global_store_dwordx4 v[8:9], v[2:5], off offset:64
	s_nop 1
	v_lshlrev_b64 v[2:3], 11, v[104:105]
	v_lshl_add_u64 v[8:9], v[6:7], 0, v[2:3]
	v_cvt_pk_bf16_f32 v2, v136, v137
	v_cvt_pk_bf16_f32 v3, v150, v151
	v_cvt_pk_bf16_f32 v4, v130, v131
	v_cvt_pk_bf16_f32 v5, v134, v135
	global_store_dwordx4 v[8:9], v[2:5], off
	s_nop 1
	v_cvt_pk_bf16_f32 v2, v124, v125
	v_cvt_pk_bf16_f32 v3, v126, v127
	v_cvt_pk_bf16_f32 v4, v120, v121
	v_cvt_pk_bf16_f32 v5, v122, v123
	global_store_dwordx4 v[8:9], v[2:5], off offset:64
	s_nop 1
	v_lshlrev_b64 v[2:3], 11, v[94:95]
	v_lshl_add_u64 v[6:7], v[6:7], 0, v[2:3]
	v_cvt_pk_bf16_f32 v2, v114, v115
	v_cvt_pk_bf16_f32 v3, v116, v117
	v_cvt_pk_bf16_f32 v4, v106, v107
	v_cvt_pk_bf16_f32 v5, v108, v109
	global_store_dwordx4 v[6:7], v[2:5], off
	s_nop 1
	v_cvt_pk_bf16_f32 v2, v100, v101
	v_cvt_pk_bf16_f32 v3, v102, v103
	v_cvt_pk_bf16_f32 v4, v96, v97
	v_cvt_pk_bf16_f32 v5, v98, v99
	global_store_dwordx4 v[6:7], v[2:5], off offset:64
